# reverse loop-edge rotation: K-loop tail counter/pointer updates moved from the compute-segment tail to the loop head (exit test on the pre-increment counter), on top of saddr+lbase+nopfill
# speedup vs baseline: 1.0065x; 1.0036x over previous
; #define PG8_STAGE(bufoff, gbase, voff) do { _Pragma("unroll") for (int _i = 0; _i < 2; ++_i) \
;         __builtin_amdgcn_global_load_lds((const unsigned*)((const char*)(gbase) + (voff)[_i]), (LAS unsigned*)(lds + (bufoff) + ldsw + _i * 8192), 16, 0, 0); } while (0)
; #define PG8_LDA(dst, b, h) do { _Pragma("unroll") for (int m = 0; m < 4; ++m) _Pragma("unroll") for (int k = 0; k < 2; ++k) dst[m][k] = *(const LAS bf16x8*)(lds + PG8_SA(b, h) + aoff + m * 2048 + k * 1024); } while (0)
; #define PG8_LDB(dst, b, h) do { _Pragma("unroll") for (int n = 0; n < 2; ++n) _Pragma("unroll") for (int k = 0; k < 2; ++k) dst[n][k] = *(const LAS bf16x8*)(lds + PG8_SB(b, h) + boff + n * 2048 + k * 1024); } while (0)
; #define PG8_SCHED __builtin_amdgcn_sched_barrier(0)
; template <class Epi, class Sched>
; __device__ __forceinline__ void gemm_phase(LAS unsigned char* lds, const Gemm g, const Sched& S, const Epi& E) {
;     ...
;         const bool has_next = S.next(ui + 1, nxt);
;         const char* nA = has_next ? (const char*)g.A + (size_t)nxt.pm * tstep + (size_t)nxt.ks * sstep : cA; const char* nB = has_next ? (const char*)g.Bt + (size_t)nxt.pn * tstep + (size_t)nxt.ks * sstep : cB;
;         for (int t = 0; t < nt; t += 2) {
;             const bool last = (t == nt - 2);
;             const char* a1 = cA + (size_t)(t + 1) * kstep;
;             const char* a2 = last ? nA : cA + (size_t)(t + 2) * kstep; const char* b2 = last ? nB : cB + (size_t)(t + 2) * kstep;
;             const char* a3 = a2 + kstep; const char* b3 = b2 + kstep;
;             PG8_LDB(B0, 0, 0); PG8_SCHED; PG8_LDA(At, 0, 0); PG8_STAGE(PG8_SA(1, 1), a1 + hstep, voffA);
;     ...
; #pragma unroll
;         for (int a = 0; a < 2; ++a)
; #pragma unroll
;             for (int b = 0; b < 2; ++b)
; #pragma unroll
;                 for (int m = 0; m < 4; ++m)
; #pragma unroll
;                     for (int n = 0; n < 2; ++n) acc[a][b][m][n] = (f32x4){0.f, 0.f, 0.f, 0.f};
;         cur = nxt; cA = nA; cB = nB; ++ui;
.LBB0_43:
	s_ashr_i32 s27, s26, 31
	s_lshl_b64 s[38:39], s[26:27], 22
	v_cmp_lt_i64_e32 vcc, s[42:43], v[158:159]
	s_add_u32 s42, s10, s38
	s_addc_u32 s43, s11, s39
	s_and_b64 s[38:39], vcc, exec
	s_cselect_b32 s27, s43, s29
	s_cselect_b32 s71, s42, s28
	s_ashr_i32 s25, s24, 31
	s_lshl_b64 s[38:39], s[24:25], 22
	s_add_u32 s48, s13, s38
	s_addc_u32 s49, s30, s39
	s_and_b64 s[38:39], vcc, exec
	s_cselect_b32 s25, s49, s51
	s_cselect_b32 s72, s48, s50
	s_add_u32 s73, s50, 0x100
	v_mov_b32_e32 v2, 0
	s_addc_u32 s74, s51, 0
	s_mov_b32 s75, -2
	v_mov_b32_e32 v3, v2
	v_mov_b32_e32 v4, v2
	v_mov_b32_e32 v5, v2
	v_mov_b32_e32 v6, v2
	v_mov_b32_e32 v7, v2
	v_mov_b32_e32 v8, v2
	v_mov_b32_e32 v9, v2
	v_mov_b32_e32 v10, v2
	v_mov_b32_e32 v11, v2
	v_mov_b32_e32 v12, v2
	v_mov_b32_e32 v13, v2
	v_mov_b32_e32 v18, v2
	v_mov_b32_e32 v19, v2
	v_mov_b32_e32 v20, v2
	v_mov_b32_e32 v21, v2
	v_mov_b32_e32 v34, v2
	v_mov_b32_e32 v35, v2
	v_mov_b32_e32 v36, v2
	v_mov_b32_e32 v37, v2
	v_mov_b32_e32 v38, v2
	v_mov_b32_e32 v39, v2
	v_mov_b32_e32 v40, v2
	v_mov_b32_e32 v41, v2
	v_mov_b32_e32 v50, v2
	v_mov_b32_e32 v51, v2
	v_mov_b32_e32 v52, v2
	v_mov_b32_e32 v53, v2
	v_mov_b32_e32 v54, v2
	v_mov_b32_e32 v55, v2
	v_mov_b32_e32 v56, v2
	v_mov_b32_e32 v57, v2
	v_mov_b32_e32 v14, v2
	v_mov_b32_e32 v15, v2
	v_mov_b32_e32 v16, v2
	v_mov_b32_e32 v17, v2
	s_waitcnt vmcnt(0)
	v_mov_b32_e32 v22, v2
	v_mov_b32_e32 v23, v2
	v_mov_b32_e32 v24, v2
	v_mov_b32_e32 v25, v2
	v_mov_b32_e32 v26, v2
	v_mov_b32_e32 v27, v2
	v_mov_b32_e32 v28, v2
	v_mov_b32_e32 v29, v2
	v_mov_b32_e32 v30, v2
	v_mov_b32_e32 v31, v2
	v_mov_b32_e32 v32, v2
	v_mov_b32_e32 v33, v2
	v_mov_b32_e32 v42, v2
	v_mov_b32_e32 v43, v2
	v_mov_b32_e32 v44, v2
	v_mov_b32_e32 v45, v2
	v_mov_b32_e32 v46, v2
	v_mov_b32_e32 v47, v2
	v_mov_b32_e32 v48, v2
	v_mov_b32_e32 v49, v2
	v_mov_b32_e32 v58, v2
	v_mov_b32_e32 v59, v2
	v_mov_b32_e32 v60, v2
	v_mov_b32_e32 v61, v2
	v_mov_b32_e32 v62, v2
	v_mov_b32_e32 v63, v2
	v_mov_b32_e32 v64, v2
	v_mov_b32_e32 v65, v2
	v_mov_b32_e32 v82, v2
	v_mov_b32_e32 v83, v2
	v_mov_b32_e32 v84, v2
	v_mov_b32_e32 v85, v2
	v_mov_b32_e32 v86, v2
	v_mov_b32_e32 v87, v2
	v_mov_b32_e32 v88, v2
	v_mov_b32_e32 v89, v2
	v_mov_b32_e32 v90, v2
	v_mov_b32_e32 v91, v2
	v_mov_b32_e32 v92, v2
	v_mov_b32_e32 v93, v2
	v_mov_b32_e32 v94, v2
	v_mov_b32_e32 v95, v2
	v_mov_b32_e32 v96, v2
	v_mov_b32_e32 v97, v2
	v_mov_b32_e32 v114, v2
	v_mov_b32_e32 v115, v2
	v_mov_b32_e32 v116, v2
	v_mov_b32_e32 v117, v2
	v_mov_b32_e32 v118, v2
	v_mov_b32_e32 v119, v2
	v_mov_b32_e32 v120, v2
	v_mov_b32_e32 v121, v2
	v_mov_b32_e32 v130, v2
	v_mov_b32_e32 v131, v2
	v_mov_b32_e32 v132, v2
	v_mov_b32_e32 v133, v2
	v_mov_b32_e32 v134, v2
	v_mov_b32_e32 v135, v2
	v_mov_b32_e32 v136, v2
	v_mov_b32_e32 v137, v2
	v_mov_b32_e32 v98, v2
	v_mov_b32_e32 v99, v2
	v_mov_b32_e32 v100, v2
	v_mov_b32_e32 v101, v2
	v_mov_b32_e32 v102, v2
	v_mov_b32_e32 v103, v2
	v_mov_b32_e32 v104, v2
	v_mov_b32_e32 v105, v2
	v_mov_b32_e32 v106, v2
	v_mov_b32_e32 v107, v2
	v_mov_b32_e32 v108, v2
	v_mov_b32_e32 v109, v2
	v_mov_b32_e32 v110, v2
	v_mov_b32_e32 v111, v2
	v_mov_b32_e32 v112, v2
	v_mov_b32_e32 v113, v2
	v_mov_b32_e32 v122, v2
	v_mov_b32_e32 v123, v2
	v_mov_b32_e32 v124, v2
	v_mov_b32_e32 v125, v2
	v_mov_b32_e32 v126, v2
	v_mov_b32_e32 v127, v2
	v_mov_b32_e32 v128, v2
	v_mov_b32_e32 v129, v2
	v_mov_b32_e32 v138, v2
	v_mov_b32_e32 v139, v2
	v_mov_b32_e32 v140, v2
	v_mov_b32_e32 v141, v2
	v_mov_b32_e32 v142, v2
	v_mov_b32_e32 v143, v2
	v_mov_b32_e32 v144, v2
	v_mov_b32_e32 v145, v2
	s_branch .Lent_44
.LBB0_44:
	s_add_i32 s75, s75, 2
	s_add_u32 s73, s73, 0x100
	s_addc_u32 s74, s74, 0
	s_mov_b64 s[28:29], s[50:51]
.Lent_44:
	s_add_u32 s50, s28, 0x100
	s_addc_u32 s51, s29, 0
	s_cmpk_eq_i32 s75, 0x7c
	s_cselect_b32 s55, s27, s51
	s_cselect_b32 s54, s71, s50
	s_cselect_b32 s53, s25, s74
	s_cselect_b32 s52, s72, s73
	s_add_i32 m0, s9, 0xc000
	ds_read_b128 v[66:69], v226
	global_load_lds_dwordx4 v150, s[28:29]
	s_add_i32 m0, s9, 0xe000
	ds_read_b128 v[70:73], v226 offset:1024
	global_load_lds_dwordx4 v148, s[28:29]
	s_add_i32 s38, 0, 0x10000
	ds_read_b128 v[74:77], v226 offset:2048
	ds_read_b128 v[78:81], v226 offset:3072
	ds_read_b128 v[152:155], v165
	ds_read_b128 v[166:169], v165 offset:1024
	ds_read_b128 v[170:173], v165 offset:2048
	ds_read_b128 v[174:177], v165 offset:3072
	ds_read_b128 v[178:181], v165 offset:4096
	ds_read_b128 v[182:185], v165 offset:5120
	ds_read_b128 v[186:189], v165 offset:6144
	ds_read_b128 v[190:193], v165 offset:7168
	s_add_i32 s39, 0, 0x14000
	ds_read_b128 v[194:197], v226 offset:16384
	ds_read_b128 v[198:201], v226 offset:17408
	ds_read_b128 v[202:205], v226 offset:18432
	ds_read_b128 v[210:213], v226 offset:19456
	s_waitcnt lgkmcnt(4)
	s_barrier
; #define PG8_STAGE(bufoff, gbase, voff) do { _Pragma("unroll") for (int _i = 0; _i < 2; ++_i) \
;         __builtin_amdgcn_global_load_lds((const unsigned*)((const char*)(gbase) + (voff)[_i]), (LAS unsigned*)(lds + (bufoff) + ldsw + _i * 8192), 16, 0, 0); } while (0)
; #define PG8_LDA(dst, b, h) do { _Pragma("unroll") for (int m = 0; m < 4; ++m) _Pragma("unroll") for (int k = 0; k < 2; ++k) dst[m][k] = *(const LAS bf16x8*)(lds + PG8_SA(b, h) + aoff + m * 2048 + k * 1024); } while (0)
; #define PG8_LDB(dst, b, h) do { _Pragma("unroll") for (int n = 0; n < 2; ++n) _Pragma("unroll") for (int k = 0; k < 2; ++k) dst[n][k] = *(const LAS bf16x8*)(lds + PG8_SB(b, h) + boff + n * 2048 + k * 1024); } while (0)
; #define PG8_MMA(ai, bj, At, Bt) do { __builtin_amdgcn_s_setprio(1); _Pragma("unroll") for (int m = 0; m < 4; ++m) _Pragma("unroll") for (int n = 0; n < 2; ++n) _Pragma("unroll") for (int k = 0; k < 2; ++k) \
;         acc[ai][bj][m][n] = __builtin_amdgcn_mfma_f32_16x16x32_bf16(Bt[n][k], At[m][k], acc[ai][bj][m][n], 0, 0, 0); __builtin_amdgcn_s_setprio(0); } while (0)
; #define PG8_WAIT_V(n) asm volatile("s_waitcnt vmcnt(" #n ")" ::: "memory")
; #define PG8_WAIT_L(n) asm volatile("s_waitcnt lgkmcnt(" #n ")" ::: "memory")
; #define PG8_BAR __builtin_amdgcn_s_barrier()
; #define PG8_SCHED __builtin_amdgcn_sched_barrier(0)
; template <class Epi, class Sched>
; __device__ __forceinline__ void gemm_phase(LAS unsigned char* lds, const Gemm g, const Sched& S, const Epi& E) {
;     ...
;             PG8_LDB(B0, 0, 0); PG8_SCHED; PG8_LDA(At, 0, 0); PG8_STAGE(PG8_SA(1, 1), a1 + hstep, voffA);
;             PG8_WAIT_L(8); PG8_BAR; PG8_WAIT_L(0); PG8_MMA(0, 0, At, B0); PG8_BAR; PG8_SCHED;
;             PG8_LDB(B1, 0, 1); PG8_STAGE(PG8_SB(0, 0), b2, voffB);
;             PG8_BAR; PG8_WAIT_L(0); PG8_MMA(0, 1, At, B1); PG8_BAR;
;             PG8_LDA(At, 0, 1); PG8_STAGE(PG8_SA(0, 0), a2, voffA);
;             PG8_BAR; PG8_WAIT_L(0); PG8_MMA(1, 0, At, B0); PG8_BAR; PG8_SCHED;
;             PG8_STAGE(PG8_SB(0, 1), b2 + hstep, voffB);
;             PG8_WAIT_V(6); PG8_BAR; PG8_MMA(1, 1, At, B1); PG8_BAR;
	s_waitcnt lgkmcnt(0)
	v_mfma_f32_16x16x32_bf16 v[142:145], v[66:69], v[152:155], v[142:145]
	v_mfma_f32_16x16x32_bf16 v[138:141], v[74:77], v[152:155], v[138:141]
	v_mfma_f32_16x16x32_bf16 v[126:129], v[66:69], v[170:173], v[126:129]
	v_mfma_f32_16x16x32_bf16 v[122:125], v[74:77], v[170:173], v[122:125]
	v_mfma_f32_16x16x32_bf16 v[110:113], v[66:69], v[178:181], v[110:113]
	v_mfma_f32_16x16x32_bf16 v[106:109], v[74:77], v[178:181], v[106:109]
	v_mfma_f32_16x16x32_bf16 v[102:105], v[66:69], v[186:189], v[102:105]
	v_mfma_f32_16x16x32_bf16 v[98:101], v[74:77], v[186:189], v[98:101]
	v_mfma_f32_16x16x32_bf16 v[142:145], v[70:73], v[166:169], v[142:145]
	v_mfma_f32_16x16x32_bf16 v[138:141], v[78:81], v[166:169], v[138:141]
	v_mfma_f32_16x16x32_bf16 v[126:129], v[70:73], v[174:177], v[126:129]
	v_mfma_f32_16x16x32_bf16 v[122:125], v[78:81], v[174:177], v[122:125]
	v_mfma_f32_16x16x32_bf16 v[110:113], v[70:73], v[182:185], v[110:113]
	v_mfma_f32_16x16x32_bf16 v[106:109], v[78:81], v[182:185], v[106:109]
	v_mfma_f32_16x16x32_bf16 v[102:105], v[70:73], v[190:193], v[102:105]
	v_mfma_f32_16x16x32_bf16 v[98:101], v[78:81], v[190:193], v[98:101]
	v_mfma_f32_16x16x32_bf16 v[134:137], v[194:197], v[152:155], v[134:137]
	v_mfma_f32_16x16x32_bf16 v[130:133], v[202:205], v[152:155], v[130:133]
	v_mfma_f32_16x16x32_bf16 v[118:121], v[194:197], v[170:173], v[118:121]
	v_mfma_f32_16x16x32_bf16 v[114:117], v[202:205], v[170:173], v[114:117]
	v_mfma_f32_16x16x32_bf16 v[94:97], v[194:197], v[178:181], v[94:97]
	v_mfma_f32_16x16x32_bf16 v[90:93], v[202:205], v[178:181], v[90:93]
	v_mfma_f32_16x16x32_bf16 v[86:89], v[194:197], v[186:189], v[86:89]
	v_mfma_f32_16x16x32_bf16 v[82:85], v[202:205], v[186:189], v[82:85]
	v_mfma_f32_16x16x32_bf16 v[134:137], v[198:201], v[166:169], v[134:137]
	v_mfma_f32_16x16x32_bf16 v[130:133], v[210:213], v[166:169], v[130:133]
	v_mfma_f32_16x16x32_bf16 v[118:121], v[198:201], v[174:177], v[118:121]
	v_mfma_f32_16x16x32_bf16 v[114:117], v[210:213], v[174:177], v[114:117]
	v_mfma_f32_16x16x32_bf16 v[94:97], v[198:201], v[182:185], v[94:97]
	v_mfma_f32_16x16x32_bf16 v[90:93], v[210:213], v[182:185], v[90:93]
	v_mfma_f32_16x16x32_bf16 v[86:89], v[198:201], v[190:193], v[86:89]
	v_mfma_f32_16x16x32_bf16 v[82:85], v[210:213], v[190:193], v[82:85]
	s_barrier
	s_add_i32 s28, s38, s60
	s_mov_b32 m0, s28
	ds_read_b128 v[152:155], v165 offset:16384
	global_load_lds_dwordx4 v0, s[52:53]
	s_add_i32 m0, s28, 0x2000
	ds_read_b128 v[166:169], v165 offset:17408
	global_load_lds_dwordx4 v146, s[52:53]
	s_mov_b32 m0, s9
	ds_read_b128 v[170:173], v165 offset:18432
	global_load_lds_dwordx4 v0, s[54:55]
	s_mov_b32 m0, s61
	ds_read_b128 v[174:177], v165 offset:19456
	global_load_lds_dwordx4 v146, s[54:55]
	ds_read_b128 v[178:181], v165 offset:20480
	ds_read_b128 v[182:185], v165 offset:21504
	ds_read_b128 v[186:189], v165 offset:22528
	ds_read_b128 v[190:193], v165 offset:23552
	s_waitcnt vmcnt(4)
	s_waitcnt lgkmcnt(0)
	s_barrier
	v_mfma_f32_16x16x32_bf16 v[62:65], v[66:69], v[152:155], v[62:65]
	v_mfma_f32_16x16x32_bf16 v[58:61], v[74:77], v[152:155], v[58:61]
	v_mfma_f32_16x16x32_bf16 v[46:49], v[66:69], v[170:173], v[46:49]
	v_mfma_f32_16x16x32_bf16 v[42:45], v[74:77], v[170:173], v[42:45]
	v_mfma_f32_16x16x32_bf16 v[30:33], v[66:69], v[178:181], v[30:33]
	v_mfma_f32_16x16x32_bf16 v[26:29], v[74:77], v[178:181], v[26:29]
	v_mfma_f32_16x16x32_bf16 v[22:25], v[66:69], v[186:189], v[22:25]
	v_mfma_f32_16x16x32_bf16 v[14:17], v[74:77], v[186:189], v[14:17]
	v_mfma_f32_16x16x32_bf16 v[62:65], v[70:73], v[166:169], v[62:65]
	v_mfma_f32_16x16x32_bf16 v[58:61], v[78:81], v[166:169], v[58:61]
	v_mfma_f32_16x16x32_bf16 v[46:49], v[70:73], v[174:177], v[46:49]
	v_mfma_f32_16x16x32_bf16 v[42:45], v[78:81], v[174:177], v[42:45]
	v_mfma_f32_16x16x32_bf16 v[30:33], v[70:73], v[182:185], v[30:33]
	v_mfma_f32_16x16x32_bf16 v[26:29], v[78:81], v[182:185], v[26:29]
	v_mfma_f32_16x16x32_bf16 v[22:25], v[70:73], v[190:193], v[22:25]
	v_mfma_f32_16x16x32_bf16 v[14:17], v[78:81], v[190:193], v[14:17]
	v_mfma_f32_16x16x32_bf16 v[54:57], v[194:197], v[152:155], v[54:57]
	v_mfma_f32_16x16x32_bf16 v[50:53], v[202:205], v[152:155], v[50:53]
	v_mfma_f32_16x16x32_bf16 v[38:41], v[194:197], v[170:173], v[38:41]
	v_mfma_f32_16x16x32_bf16 v[34:37], v[202:205], v[170:173], v[34:37]
	v_mfma_f32_16x16x32_bf16 v[18:21], v[194:197], v[178:181], v[18:21]
	v_mfma_f32_16x16x32_bf16 v[10:13], v[202:205], v[178:181], v[10:13]
	v_mfma_f32_16x16x32_bf16 v[6:9], v[194:197], v[186:189], v[6:9]
	v_mfma_f32_16x16x32_bf16 v[2:5], v[202:205], v[186:189], v[2:5]
	v_mfma_f32_16x16x32_bf16 v[54:57], v[198:201], v[166:169], v[54:57]
	v_mfma_f32_16x16x32_bf16 v[50:53], v[210:213], v[166:169], v[50:53]
	v_mfma_f32_16x16x32_bf16 v[38:41], v[198:201], v[174:177], v[38:41]
	v_mfma_f32_16x16x32_bf16 v[34:37], v[210:213], v[174:177], v[34:37]
	v_mfma_f32_16x16x32_bf16 v[18:21], v[198:201], v[182:185], v[18:21]
	v_mfma_f32_16x16x32_bf16 v[10:13], v[210:213], v[182:185], v[10:13]
	v_mfma_f32_16x16x32_bf16 v[6:9], v[198:201], v[190:193], v[6:9]
	v_mfma_f32_16x16x32_bf16 v[2:5], v[210:213], v[190:193], v[2:5]
	s_barrier
; #define PG8_STAGE(bufoff, gbase, voff) do { _Pragma("unroll") for (int _i = 0; _i < 2; ++_i) \
;         __builtin_amdgcn_global_load_lds((const unsigned*)((const char*)(gbase) + (voff)[_i]), (LAS unsigned*)(lds + (bufoff) + ldsw + _i * 8192), 16, 0, 0); } while (0)
; #define PG8_LDA(dst, b, h) do { _Pragma("unroll") for (int m = 0; m < 4; ++m) _Pragma("unroll") for (int k = 0; k < 2; ++k) dst[m][k] = *(const LAS bf16x8*)(lds + PG8_SA(b, h) + aoff + m * 2048 + k * 1024); } while (0)
; #define PG8_LDB(dst, b, h) do { _Pragma("unroll") for (int n = 0; n < 2; ++n) _Pragma("unroll") for (int k = 0; k < 2; ++k) dst[n][k] = *(const LAS bf16x8*)(lds + PG8_SB(b, h) + boff + n * 2048 + k * 1024); } while (0)
; #define PG8_MMA(ai, bj, At, Bt) do { __builtin_amdgcn_s_setprio(1); _Pragma("unroll") for (int m = 0; m < 4; ++m) _Pragma("unroll") for (int n = 0; n < 2; ++n) _Pragma("unroll") for (int k = 0; k < 2; ++k) \
;         acc[ai][bj][m][n] = __builtin_amdgcn_mfma_f32_16x16x32_bf16(Bt[n][k], At[m][k], acc[ai][bj][m][n], 0, 0, 0); __builtin_amdgcn_s_setprio(0); } while (0)
; #define PG8_BAR __builtin_amdgcn_s_barrier()
;     __device__ __forceinline__ void operator()(const f32x4 (&acc)[2][2][4][2], const Unit& u, int wr, int wc, int fr, int fq) const {
;         const bool lat = u.pm < 64; const int r = lat ? (u.pm >> 3) : 8;
;         const float* s = lat ? src_lat : src_ctx; float* d = lat ? dst_lat : dst_ctx;
;         const int row0 = (lat ? u.pm : u.pm - 64) * BM + wr * 64 + fr, col0 = u.pn * BM + wc * 32 + 4 * fq;
; template <class Epi, class Sched>
; __device__ __forceinline__ void gemm_phase(LAS unsigned char* lds, const Gemm g, const Sched& S, const Epi& E) {
;     ...
;             PG8_WAIT_V(6); PG8_BAR; PG8_MMA(1, 1, At, B1); PG8_BAR;
;             PG8_LDB(B0, 1, 0); PG8_SCHED; PG8_LDA(At, 1, 0); PG8_STAGE(PG8_SA(0, 1), a2 + hstep, voffA);
;             PG8_WAIT_L(8); PG8_BAR; PG8_WAIT_L(0); PG8_MMA(0, 0, At, B0); PG8_BAR; PG8_SCHED;
;             PG8_LDB(B1, 1, 1); PG8_STAGE(PG8_SB(1, 0), b3, voffB);
;             PG8_BAR; PG8_WAIT_L(0); PG8_MMA(0, 1, At, B1); PG8_BAR;
;             PG8_LDA(At, 1, 1); PG8_STAGE(PG8_SA(1, 0), a3, voffA);
;             PG8_BAR; PG8_WAIT_L(0); PG8_MMA(1, 0, At, B0); PG8_BAR; PG8_SCHED;
;             PG8_STAGE(PG8_SB(1, 1), b3 + hstep, voffB);
;             PG8_WAIT_V(6); PG8_BAR; PG8_MMA(1, 1, At, B1); PG8_BAR;
	s_add_u32 s28, s52, 0x200000
	s_addc_u32 s29, s53, 0
	s_add_i32 s38, s39, s60
	s_mov_b32 m0, s38
	ds_read_b128 v[66:69], v226 offset:32768
	global_load_lds_dwordx4 v0, s[28:29]
	s_add_i32 m0, s38, 0x2000
	ds_read_b128 v[70:73], v226 offset:33792
	global_load_lds_dwordx4 v146, s[28:29]
	s_add_u32 s28, s54, 0x200000
	s_addc_u32 s29, s55, 0
	s_mov_b32 m0, s62
	ds_read_b128 v[74:77], v226 offset:34816
	global_load_lds_dwordx4 v0, s[28:29]
	s_mov_b32 m0, s63
	ds_read_b128 v[78:81], v226 offset:35840
	global_load_lds_dwordx4 v146, s[28:29]
	s_add_i32 s38, 0, 0x18000
	ds_read_b128 v[152:155], v165 offset:32768
	ds_read_b128 v[166:169], v165 offset:33792
	ds_read_b128 v[170:173], v165 offset:34816
	ds_read_b128 v[174:177], v165 offset:35840
	ds_read_b128 v[178:181], v165 offset:36864
	ds_read_b128 v[182:185], v165 offset:37888
	ds_read_b128 v[186:189], v165 offset:38912
	ds_read_b128 v[190:193], v165 offset:39936
	s_add_i32 s39, 0, 0x1c000
	ds_read_b128 v[194:197], v226 offset:49152
	ds_read_b128 v[198:201], v226 offset:50176
	ds_read_b128 v[202:205], v226 offset:51200
	ds_read_b128 v[210:213], v226 offset:52224
	s_waitcnt lgkmcnt(4)
	s_barrier
	s_waitcnt lgkmcnt(0)
	v_mfma_f32_16x16x32_bf16 v[142:145], v[66:69], v[152:155], v[142:145]
	v_mfma_f32_16x16x32_bf16 v[138:141], v[74:77], v[152:155], v[138:141]
	v_mfma_f32_16x16x32_bf16 v[126:129], v[66:69], v[170:173], v[126:129]
	v_mfma_f32_16x16x32_bf16 v[122:125], v[74:77], v[170:173], v[122:125]
	v_mfma_f32_16x16x32_bf16 v[110:113], v[66:69], v[178:181], v[110:113]
	v_mfma_f32_16x16x32_bf16 v[106:109], v[74:77], v[178:181], v[106:109]
	v_mfma_f32_16x16x32_bf16 v[102:105], v[66:69], v[186:189], v[102:105]
	v_mfma_f32_16x16x32_bf16 v[98:101], v[74:77], v[186:189], v[98:101]
	v_mfma_f32_16x16x32_bf16 v[142:145], v[70:73], v[166:169], v[142:145]
	v_mfma_f32_16x16x32_bf16 v[138:141], v[78:81], v[166:169], v[138:141]
	v_mfma_f32_16x16x32_bf16 v[126:129], v[70:73], v[174:177], v[126:129]
	v_mfma_f32_16x16x32_bf16 v[122:125], v[78:81], v[174:177], v[122:125]
	v_mfma_f32_16x16x32_bf16 v[110:113], v[70:73], v[182:185], v[110:113]
	v_mfma_f32_16x16x32_bf16 v[106:109], v[78:81], v[182:185], v[106:109]
	v_mfma_f32_16x16x32_bf16 v[102:105], v[70:73], v[190:193], v[102:105]
	v_mfma_f32_16x16x32_bf16 v[98:101], v[78:81], v[190:193], v[98:101]
	v_mfma_f32_16x16x32_bf16 v[134:137], v[194:197], v[152:155], v[134:137]
	v_mfma_f32_16x16x32_bf16 v[130:133], v[202:205], v[152:155], v[130:133]
	v_mfma_f32_16x16x32_bf16 v[118:121], v[194:197], v[170:173], v[118:121]
	v_mfma_f32_16x16x32_bf16 v[114:117], v[202:205], v[170:173], v[114:117]
	v_mfma_f32_16x16x32_bf16 v[94:97], v[194:197], v[178:181], v[94:97]
	v_mfma_f32_16x16x32_bf16 v[90:93], v[202:205], v[178:181], v[90:93]
	v_mfma_f32_16x16x32_bf16 v[86:89], v[194:197], v[186:189], v[86:89]
	v_mfma_f32_16x16x32_bf16 v[82:85], v[202:205], v[186:189], v[82:85]
	v_mfma_f32_16x16x32_bf16 v[134:137], v[198:201], v[166:169], v[134:137]
	v_mfma_f32_16x16x32_bf16 v[130:133], v[210:213], v[166:169], v[130:133]
	v_mfma_f32_16x16x32_bf16 v[118:121], v[198:201], v[174:177], v[118:121]
	v_mfma_f32_16x16x32_bf16 v[114:117], v[210:213], v[174:177], v[114:117]
	v_mfma_f32_16x16x32_bf16 v[94:97], v[198:201], v[182:185], v[94:97]
	v_mfma_f32_16x16x32_bf16 v[90:93], v[210:213], v[182:185], v[90:93]
	v_mfma_f32_16x16x32_bf16 v[86:89], v[198:201], v[190:193], v[86:89]
	v_mfma_f32_16x16x32_bf16 v[82:85], v[210:213], v[190:193], v[82:85]
	s_barrier
	s_add_i32 s28, s38, s60
	s_add_u32 s100, s52, s36
	s_addc_u32 s101, s53, s37
	s_mov_b32 m0, s28
	ds_read_b128 v[152:155], v165 offset:49152
	global_load_lds_dwordx4 v0, s[100:101]
	s_add_i32 m0, s28, 0x2000
	ds_read_b128 v[166:169], v165 offset:50176
	global_load_lds_dwordx4 v146, s[100:101]
	s_mov_b32 m0, s66
	s_add_u32 s100, s54, s36
	s_addc_u32 s101, s55, s37
	global_load_lds_dwordx4 v0, s[100:101]
	s_mov_b32 m0, s67
	ds_read_b128 v[170:173], v165 offset:51200
	global_load_lds_dwordx4 v146, s[100:101]
	ds_read_b128 v[174:177], v165 offset:52224
	ds_read_b128 v[178:181], v165 offset:53248
	ds_read_b128 v[182:185], v165 offset:54272
	ds_read_b128 v[186:189], v165 offset:55296
	ds_read_b128 v[190:193], v165 offset:56320
	s_waitcnt vmcnt(4)
	s_waitcnt lgkmcnt(0)
	s_barrier
	v_mfma_f32_16x16x32_bf16 v[62:65], v[66:69], v[152:155], v[62:65]
	v_mfma_f32_16x16x32_bf16 v[58:61], v[74:77], v[152:155], v[58:61]
	v_mfma_f32_16x16x32_bf16 v[46:49], v[66:69], v[170:173], v[46:49]
	v_mfma_f32_16x16x32_bf16 v[42:45], v[74:77], v[170:173], v[42:45]
	v_mfma_f32_16x16x32_bf16 v[30:33], v[66:69], v[178:181], v[30:33]
	v_mfma_f32_16x16x32_bf16 v[26:29], v[74:77], v[178:181], v[26:29]
	v_mfma_f32_16x16x32_bf16 v[22:25], v[66:69], v[186:189], v[22:25]
	v_mfma_f32_16x16x32_bf16 v[14:17], v[74:77], v[186:189], v[14:17]
	v_mfma_f32_16x16x32_bf16 v[62:65], v[70:73], v[166:169], v[62:65]
	v_mfma_f32_16x16x32_bf16 v[58:61], v[78:81], v[166:169], v[58:61]
	v_mfma_f32_16x16x32_bf16 v[46:49], v[70:73], v[174:177], v[46:49]
	v_mfma_f32_16x16x32_bf16 v[42:45], v[78:81], v[174:177], v[42:45]
	v_mfma_f32_16x16x32_bf16 v[30:33], v[70:73], v[182:185], v[30:33]
	v_mfma_f32_16x16x32_bf16 v[26:29], v[78:81], v[182:185], v[26:29]
	v_mfma_f32_16x16x32_bf16 v[22:25], v[70:73], v[190:193], v[22:25]
	v_mfma_f32_16x16x32_bf16 v[14:17], v[78:81], v[190:193], v[14:17]
	s_add_u32 s28, s52, 0x200080
	s_addc_u32 s29, s53, 0
	s_add_i32 s38, s39, s60
	s_mov_b32 m0, s38
	s_nop 0
	global_load_lds_dwordx4 v0, s[28:29]
	s_add_i32 m0, s38, 0x2000
	s_nop 0
	global_load_lds_dwordx4 v146, s[28:29]
	v_mfma_f32_16x16x32_bf16 v[54:57], v[194:197], v[152:155], v[54:57]
	v_mfma_f32_16x16x32_bf16 v[50:53], v[202:205], v[152:155], v[50:53]
	v_mfma_f32_16x16x32_bf16 v[38:41], v[194:197], v[170:173], v[38:41]
	v_mfma_f32_16x16x32_bf16 v[34:37], v[202:205], v[170:173], v[34:37]
	v_mfma_f32_16x16x32_bf16 v[18:21], v[194:197], v[178:181], v[18:21]
	v_mfma_f32_16x16x32_bf16 v[10:13], v[202:205], v[178:181], v[10:13]
	v_mfma_f32_16x16x32_bf16 v[6:9], v[194:197], v[186:189], v[6:9]
	v_mfma_f32_16x16x32_bf16 v[2:5], v[202:205], v[186:189], v[2:5]
	v_mfma_f32_16x16x32_bf16 v[54:57], v[198:201], v[166:169], v[54:57]
	v_mfma_f32_16x16x32_bf16 v[50:53], v[210:213], v[166:169], v[50:53]
	v_mfma_f32_16x16x32_bf16 v[38:41], v[198:201], v[174:177], v[38:41]
	v_mfma_f32_16x16x32_bf16 v[34:37], v[210:213], v[174:177], v[34:37]
	v_mfma_f32_16x16x32_bf16 v[18:21], v[198:201], v[182:185], v[18:21]
	v_mfma_f32_16x16x32_bf16 v[10:13], v[210:213], v[182:185], v[10:13]
	v_mfma_f32_16x16x32_bf16 v[6:9], v[198:201], v[190:193], v[6:9]
	v_mfma_f32_16x16x32_bf16 v[2:5], v[210:213], v[190:193], v[2:5]
	s_cmp_gt_i32 s75, 123
	s_barrier
	s_cbranch_scc0 .LBB0_44
	s_cmp_lt_i32 s8, 64
	s_cselect_b64 s[50:51], -1, 0
	s_cmp_gt_i32 s8, 63
	s_cbranch_scc0 .LBB0_35
	s_mov_b64 s[52:53], 0x18000
	s_mov_b64 s[28:29], s[46:47]
	s_branch .LBB0_36

; #define PG8_STAGE(bufoff, gbase, voff) do { _Pragma("unroll") for (int _i = 0; _i < 2; ++_i) \
;         __builtin_amdgcn_global_load_lds((const unsigned*)((const char*)(gbase) + (voff)[_i]), (LAS unsigned*)(lds + (bufoff) + ldsw + _i * 8192), 16, 0, 0); } while (0)
; #define PG8_LDA(dst, b, h) do { _Pragma("unroll") for (int m = 0; m < 4; ++m) _Pragma("unroll") for (int k = 0; k < 2; ++k) dst[m][k] = *(const LAS bf16x8*)(lds + PG8_SA(b, h) + aoff + m * 2048 + k * 1024); } while (0)
; #define PG8_LDB(dst, b, h) do { _Pragma("unroll") for (int n = 0; n < 2; ++n) _Pragma("unroll") for (int k = 0; k < 2; ++k) dst[n][k] = *(const LAS bf16x8*)(lds + PG8_SB(b, h) + boff + n * 2048 + k * 1024); } while (0)
; #define PG8_SCHED __builtin_amdgcn_sched_barrier(0)
; template <class Epi, class Sched>
; __device__ __forceinline__ void gemm_phase(LAS unsigned char* lds, const Gemm g, const Sched& S, const Epi& E) {
;     ...
;         const bool has_next = S.next(ui + 1, nxt);
;         const char* nA = has_next ? (const char*)g.A + (size_t)nxt.pm * tstep + (size_t)nxt.ks * sstep : cA; const char* nB = has_next ? (const char*)g.Bt + (size_t)nxt.pn * tstep + (size_t)nxt.ks * sstep : cB;
;         for (int t = 0; t < nt; t += 2) {
;             const bool last = (t == nt - 2);
;             const char* a1 = cA + (size_t)(t + 1) * kstep;
;             const char* a2 = last ? nA : cA + (size_t)(t + 2) * kstep; const char* b2 = last ? nB : cB + (size_t)(t + 2) * kstep;
;             const char* a3 = a2 + kstep; const char* b3 = b2 + kstep;
;             PG8_LDB(B0, 0, 0); PG8_SCHED; PG8_LDA(At, 0, 0); PG8_STAGE(PG8_SA(1, 1), a1 + hstep, voffA);
;     ...
; #pragma unroll
;         for (int a = 0; a < 2; ++a)
; #pragma unroll
;             for (int b = 0; b < 2; ++b)
; #pragma unroll
;                 for (int m = 0; m < 4; ++m)
; #pragma unroll
;                     for (int n = 0; n < 2; ++n) acc[a][b][m][n] = (f32x4){0.f, 0.f, 0.f, 0.f};
;         cur = nxt; cA = nA; cB = nB; ++ui;
.LBB0_57:
	s_ashr_i32 s43, s42, 31
	s_lshl_b64 s[38:39], s[42:43], 22
	s_add_u32 s11, s61, s38
	s_addc_u32 s41, s62, s39
	s_ashr_i32 s29, s28, 31
	s_lshl_b64 s[38:39], s[28:29], 12
	s_add_u32 s46, s11, s38
	s_addc_u32 s47, s41, s39
	s_and_b64 s[48:49], s[54:55], exec
	s_cselect_b32 s11, s47, s51
	s_cselect_b32 s29, s46, s50
	s_ashr_i32 s41, s40, 31
	s_lshl_b64 s[48:49], s[40:41], 22
	s_add_u32 s41, s13, s48
	s_addc_u32 s43, s30, s49
	s_add_u32 s48, s41, s38
	s_addc_u32 s49, s43, s39
	s_and_b64 s[38:39], s[54:55], exec
	s_cselect_b32 s41, s49, s53
	s_cselect_b32 s43, s48, s52
	s_add_u32 s69, s52, 0x100
	v_mov_b32_e32 v2, 0
	s_addc_u32 s70, s53, 0
	s_mov_b32 s71, -2
	v_mov_b32_e32 v3, v2
	v_mov_b32_e32 v4, v2
	v_mov_b32_e32 v5, v2
	v_mov_b32_e32 v6, v2
	v_mov_b32_e32 v7, v2
	v_mov_b32_e32 v8, v2
	v_mov_b32_e32 v9, v2
	v_mov_b32_e32 v10, v2
	v_mov_b32_e32 v11, v2
	v_mov_b32_e32 v12, v2
	v_mov_b32_e32 v13, v2
	v_mov_b32_e32 v14, v2
	v_mov_b32_e32 v15, v2
	v_mov_b32_e32 v16, v2
	v_mov_b32_e32 v17, v2
	s_waitcnt vmcnt(0)
	v_mov_b32_e32 v26, v2
	v_mov_b32_e32 v27, v2
	v_mov_b32_e32 v28, v2
	v_mov_b32_e32 v29, v2
	v_mov_b32_e32 v30, v2
	v_mov_b32_e32 v31, v2
	v_mov_b32_e32 v32, v2
	v_mov_b32_e32 v33, v2
	v_mov_b32_e32 v42, v2
	v_mov_b32_e32 v43, v2
	v_mov_b32_e32 v44, v2
	v_mov_b32_e32 v45, v2
	v_mov_b32_e32 v46, v2
	v_mov_b32_e32 v47, v2
	v_mov_b32_e32 v48, v2
	v_mov_b32_e32 v49, v2
	v_mov_b32_e32 v18, v2
	v_mov_b32_e32 v19, v2
	v_mov_b32_e32 v20, v2
	v_mov_b32_e32 v21, v2
	v_mov_b32_e32 v22, v2
	v_mov_b32_e32 v23, v2
	v_mov_b32_e32 v24, v2
	v_mov_b32_e32 v25, v2
	v_mov_b32_e32 v34, v2
	v_mov_b32_e32 v35, v2
	v_mov_b32_e32 v36, v2
	v_mov_b32_e32 v37, v2
	v_mov_b32_e32 v38, v2
	v_mov_b32_e32 v39, v2
	v_mov_b32_e32 v40, v2
	v_mov_b32_e32 v41, v2
	v_mov_b32_e32 v50, v2
	v_mov_b32_e32 v51, v2
	v_mov_b32_e32 v52, v2
	v_mov_b32_e32 v53, v2
	v_mov_b32_e32 v54, v2
	v_mov_b32_e32 v55, v2
	v_mov_b32_e32 v56, v2
	v_mov_b32_e32 v57, v2
	v_mov_b32_e32 v58, v2
	v_mov_b32_e32 v59, v2
	v_mov_b32_e32 v60, v2
	v_mov_b32_e32 v61, v2
	v_mov_b32_e32 v62, v2
	v_mov_b32_e32 v63, v2
	v_mov_b32_e32 v64, v2
	v_mov_b32_e32 v65, v2
	v_mov_b32_e32 v66, v2
	v_mov_b32_e32 v67, v2
	v_mov_b32_e32 v68, v2
	v_mov_b32_e32 v69, v2
	v_mov_b32_e32 v70, v2
	v_mov_b32_e32 v71, v2
	v_mov_b32_e32 v72, v2
	v_mov_b32_e32 v73, v2
	v_mov_b32_e32 v74, v2
	v_mov_b32_e32 v75, v2
	v_mov_b32_e32 v76, v2
	v_mov_b32_e32 v77, v2
	v_mov_b32_e32 v78, v2
	v_mov_b32_e32 v79, v2
	v_mov_b32_e32 v80, v2
	v_mov_b32_e32 v81, v2
	v_mov_b32_e32 v86, v2
	v_mov_b32_e32 v87, v2
	v_mov_b32_e32 v88, v2
	v_mov_b32_e32 v89, v2
	v_mov_b32_e32 v94, v2
	v_mov_b32_e32 v95, v2
	v_mov_b32_e32 v96, v2
	v_mov_b32_e32 v97, v2
	v_mov_b32_e32 v102, v2
	v_mov_b32_e32 v103, v2
	v_mov_b32_e32 v104, v2
	v_mov_b32_e32 v105, v2
	v_mov_b32_e32 v110, v2
	v_mov_b32_e32 v111, v2
	v_mov_b32_e32 v112, v2
	v_mov_b32_e32 v113, v2
	v_mov_b32_e32 v82, v2
	v_mov_b32_e32 v83, v2
	v_mov_b32_e32 v84, v2
	v_mov_b32_e32 v85, v2
	v_mov_b32_e32 v90, v2
	v_mov_b32_e32 v91, v2
	v_mov_b32_e32 v92, v2
	v_mov_b32_e32 v93, v2
	v_mov_b32_e32 v98, v2
	v_mov_b32_e32 v99, v2
	v_mov_b32_e32 v100, v2
	v_mov_b32_e32 v101, v2
	v_mov_b32_e32 v106, v2
	v_mov_b32_e32 v107, v2
	v_mov_b32_e32 v108, v2
	v_mov_b32_e32 v109, v2
	v_mov_b32_e32 v114, v2
	v_mov_b32_e32 v115, v2
	v_mov_b32_e32 v116, v2
	v_mov_b32_e32 v117, v2
	v_mov_b32_e32 v118, v2
	v_mov_b32_e32 v119, v2
	v_mov_b32_e32 v120, v2
	v_mov_b32_e32 v121, v2
	v_mov_b32_e32 v122, v2
	v_mov_b32_e32 v123, v2
	v_mov_b32_e32 v124, v2
	v_mov_b32_e32 v125, v2
	v_mov_b32_e32 v126, v2
	v_mov_b32_e32 v127, v2
	v_mov_b32_e32 v128, v2
	v_mov_b32_e32 v129, v2
	s_branch .Lent_58
.LBB0_58:
	s_add_i32 s71, s71, 2
	s_add_u32 s69, s69, 0x100
	s_addc_u32 s70, s70, 0
	s_mov_b64 s[50:51], s[52:53]
.Lent_58:
	s_add_u32 s52, s50, 0x100
	s_addc_u32 s53, s51, 0
	s_cmp_eq_u32 s71, 28
	s_cselect_b32 s57, s11, s53
	s_cselect_b32 s56, s29, s52
	s_cselect_b32 s55, s41, s70
	s_cselect_b32 s54, s43, s69
	s_add_i32 m0, s25, 0xc000
	ds_read_b128 v[140:143], v226
	global_load_lds_dwordx4 v134, s[50:51]
	s_add_i32 m0, s25, 0xe000
	ds_read_b128 v[144:147], v226 offset:1024
	global_load_lds_dwordx4 v132, s[50:51]
	s_add_i32 s38, 0, 0x10000
	ds_read_b128 v[148:151], v226 offset:2048
	ds_read_b128 v[152:155], v226 offset:3072
	ds_read_b128 v[160:163], v139
	ds_read_b128 v[164:167], v139 offset:1024
	ds_read_b128 v[168:171], v139 offset:2048
	ds_read_b128 v[172:175], v139 offset:3072
	ds_read_b128 v[176:179], v139 offset:4096
	ds_read_b128 v[180:183], v139 offset:5120
	ds_read_b128 v[184:187], v139 offset:6144
	ds_read_b128 v[188:191], v139 offset:7168
	s_add_i32 s50, 0, 0x14000
	ds_read_b128 v[192:195], v226 offset:16384
	ds_read_b128 v[196:199], v226 offset:17408
	ds_read_b128 v[200:203], v226 offset:18432
	ds_read_b128 v[204:207], v226 offset:19456
	s_waitcnt lgkmcnt(4)
	s_barrier
; #define PG8_STAGE(bufoff, gbase, voff) do { _Pragma("unroll") for (int _i = 0; _i < 2; ++_i) \
;         __builtin_amdgcn_global_load_lds((const unsigned*)((const char*)(gbase) + (voff)[_i]), (LAS unsigned*)(lds + (bufoff) + ldsw + _i * 8192), 16, 0, 0); } while (0)
; #define PG8_LDA(dst, b, h) do { _Pragma("unroll") for (int m = 0; m < 4; ++m) _Pragma("unroll") for (int k = 0; k < 2; ++k) dst[m][k] = *(const LAS bf16x8*)(lds + PG8_SA(b, h) + aoff + m * 2048 + k * 1024); } while (0)
; #define PG8_LDB(dst, b, h) do { _Pragma("unroll") for (int n = 0; n < 2; ++n) _Pragma("unroll") for (int k = 0; k < 2; ++k) dst[n][k] = *(const LAS bf16x8*)(lds + PG8_SB(b, h) + boff + n * 2048 + k * 1024); } while (0)
; #define PG8_MMA(ai, bj, At, Bt) do { __builtin_amdgcn_s_setprio(1); _Pragma("unroll") for (int m = 0; m < 4; ++m) _Pragma("unroll") for (int n = 0; n < 2; ++n) _Pragma("unroll") for (int k = 0; k < 2; ++k) \
;         acc[ai][bj][m][n] = __builtin_amdgcn_mfma_f32_16x16x32_bf16(Bt[n][k], At[m][k], acc[ai][bj][m][n], 0, 0, 0); __builtin_amdgcn_s_setprio(0); } while (0)
; #define PG8_WAIT_V(n) asm volatile("s_waitcnt vmcnt(" #n ")" ::: "memory")
; #define PG8_WAIT_L(n) asm volatile("s_waitcnt lgkmcnt(" #n ")" ::: "memory")
; #define PG8_BAR __builtin_amdgcn_s_barrier()
; #define PG8_SCHED __builtin_amdgcn_sched_barrier(0)
; template <class Epi, class Sched>
; __device__ __forceinline__ void gemm_phase(LAS unsigned char* lds, const Gemm g, const Sched& S, const Epi& E) {
;     ...
;             PG8_LDB(B0, 0, 0); PG8_SCHED; PG8_LDA(At, 0, 0); PG8_STAGE(PG8_SA(1, 1), a1 + hstep, voffA);
;             PG8_WAIT_L(8); PG8_BAR; PG8_WAIT_L(0); PG8_MMA(0, 0, At, B0); PG8_BAR; PG8_SCHED;
;             PG8_LDB(B1, 0, 1); PG8_STAGE(PG8_SB(0, 0), b2, voffB);
;             PG8_BAR; PG8_WAIT_L(0); PG8_MMA(0, 1, At, B1); PG8_BAR;
;             PG8_LDA(At, 0, 1); PG8_STAGE(PG8_SA(0, 0), a2, voffA);
;             PG8_BAR; PG8_WAIT_L(0); PG8_MMA(1, 0, At, B0); PG8_BAR; PG8_SCHED;
;             PG8_STAGE(PG8_SB(0, 1), b2 + hstep, voffB);
;             PG8_WAIT_V(6); PG8_BAR; PG8_MMA(1, 1, At, B1); PG8_BAR;
	s_waitcnt lgkmcnt(0)
	v_mfma_f32_16x16x32_bf16 v[126:129], v[140:143], v[160:163], v[126:129]
	v_mfma_f32_16x16x32_bf16 v[122:125], v[148:151], v[160:163], v[122:125]
	v_mfma_f32_16x16x32_bf16 v[118:121], v[140:143], v[168:171], v[118:121]
	v_mfma_f32_16x16x32_bf16 v[114:117], v[148:151], v[168:171], v[114:117]
	v_mfma_f32_16x16x32_bf16 v[106:109], v[140:143], v[176:179], v[106:109]
	v_mfma_f32_16x16x32_bf16 v[98:101], v[148:151], v[176:179], v[98:101]
	v_mfma_f32_16x16x32_bf16 v[90:93], v[140:143], v[184:187], v[90:93]
	v_mfma_f32_16x16x32_bf16 v[82:85], v[148:151], v[184:187], v[82:85]
	v_mfma_f32_16x16x32_bf16 v[126:129], v[144:147], v[164:167], v[126:129]
	v_mfma_f32_16x16x32_bf16 v[122:125], v[152:155], v[164:167], v[122:125]
	v_mfma_f32_16x16x32_bf16 v[118:121], v[144:147], v[172:175], v[118:121]
	v_mfma_f32_16x16x32_bf16 v[114:117], v[152:155], v[172:175], v[114:117]
	v_mfma_f32_16x16x32_bf16 v[106:109], v[144:147], v[180:183], v[106:109]
	v_mfma_f32_16x16x32_bf16 v[98:101], v[152:155], v[180:183], v[98:101]
	v_mfma_f32_16x16x32_bf16 v[90:93], v[144:147], v[188:191], v[90:93]
	v_mfma_f32_16x16x32_bf16 v[82:85], v[152:155], v[188:191], v[82:85]
	v_mfma_f32_16x16x32_bf16 v[110:113], v[192:195], v[160:163], v[110:113]
	v_mfma_f32_16x16x32_bf16 v[102:105], v[200:203], v[160:163], v[102:105]
	v_mfma_f32_16x16x32_bf16 v[94:97], v[192:195], v[168:171], v[94:97]
	v_mfma_f32_16x16x32_bf16 v[86:89], v[200:203], v[168:171], v[86:89]
	v_mfma_f32_16x16x32_bf16 v[78:81], v[192:195], v[176:179], v[78:81]
	v_mfma_f32_16x16x32_bf16 v[74:77], v[200:203], v[176:179], v[74:77]
	v_mfma_f32_16x16x32_bf16 v[70:73], v[192:195], v[184:187], v[70:73]
	v_mfma_f32_16x16x32_bf16 v[66:69], v[200:203], v[184:187], v[66:69]
	v_mfma_f32_16x16x32_bf16 v[110:113], v[196:199], v[164:167], v[110:113]
	v_mfma_f32_16x16x32_bf16 v[102:105], v[204:207], v[164:167], v[102:105]
	v_mfma_f32_16x16x32_bf16 v[94:97], v[196:199], v[172:175], v[94:97]
	v_mfma_f32_16x16x32_bf16 v[86:89], v[204:207], v[172:175], v[86:89]
	v_mfma_f32_16x16x32_bf16 v[78:81], v[196:199], v[180:183], v[78:81]
	v_mfma_f32_16x16x32_bf16 v[74:77], v[204:207], v[180:183], v[74:77]
	v_mfma_f32_16x16x32_bf16 v[70:73], v[196:199], v[188:191], v[70:73]
	v_mfma_f32_16x16x32_bf16 v[66:69], v[204:207], v[188:191], v[66:69]
	s_barrier
	s_add_i32 s38, s38, s63
	s_mov_b32 m0, s38
	ds_read_b128 v[160:163], v139 offset:16384
	global_load_lds_dwordx4 v0, s[54:55]
	s_add_i32 m0, s38, 0x2000
	ds_read_b128 v[164:167], v139 offset:17408
	global_load_lds_dwordx4 v130, s[54:55]
	s_mov_b32 m0, s25
	ds_read_b128 v[168:171], v139 offset:18432
	global_load_lds_dwordx4 v0, s[56:57]
	s_mov_b32 m0, s27
	ds_read_b128 v[172:175], v139 offset:19456
	global_load_lds_dwordx4 v130, s[56:57]
	ds_read_b128 v[176:179], v139 offset:20480
	ds_read_b128 v[180:183], v139 offset:21504
	ds_read_b128 v[184:187], v139 offset:22528
	ds_read_b128 v[188:191], v139 offset:23552
	s_waitcnt vmcnt(4)
	s_waitcnt lgkmcnt(0)
	s_barrier
	v_mfma_f32_16x16x32_bf16 v[62:65], v[140:143], v[160:163], v[62:65]
	v_mfma_f32_16x16x32_bf16 v[58:61], v[148:151], v[160:163], v[58:61]
	v_mfma_f32_16x16x32_bf16 v[54:57], v[140:143], v[168:171], v[54:57]
	v_mfma_f32_16x16x32_bf16 v[50:53], v[148:151], v[168:171], v[50:53]
	v_mfma_f32_16x16x32_bf16 v[38:41], v[140:143], v[176:179], v[38:41]
	v_mfma_f32_16x16x32_bf16 v[34:37], v[148:151], v[176:179], v[34:37]
	v_mfma_f32_16x16x32_bf16 v[22:25], v[140:143], v[184:187], v[22:25]
	v_mfma_f32_16x16x32_bf16 v[18:21], v[148:151], v[184:187], v[18:21]
	v_mfma_f32_16x16x32_bf16 v[62:65], v[144:147], v[164:167], v[62:65]
	v_mfma_f32_16x16x32_bf16 v[58:61], v[152:155], v[164:167], v[58:61]
	v_mfma_f32_16x16x32_bf16 v[54:57], v[144:147], v[172:175], v[54:57]
	v_mfma_f32_16x16x32_bf16 v[50:53], v[152:155], v[172:175], v[50:53]
	v_mfma_f32_16x16x32_bf16 v[38:41], v[144:147], v[180:183], v[38:41]
	v_mfma_f32_16x16x32_bf16 v[34:37], v[152:155], v[180:183], v[34:37]
	v_mfma_f32_16x16x32_bf16 v[22:25], v[144:147], v[188:191], v[22:25]
	v_mfma_f32_16x16x32_bf16 v[18:21], v[152:155], v[188:191], v[18:21]
	v_mfma_f32_16x16x32_bf16 v[46:49], v[192:195], v[160:163], v[46:49]
	v_mfma_f32_16x16x32_bf16 v[42:45], v[200:203], v[160:163], v[42:45]
	v_mfma_f32_16x16x32_bf16 v[30:33], v[192:195], v[168:171], v[30:33]
	v_mfma_f32_16x16x32_bf16 v[26:29], v[200:203], v[168:171], v[26:29]
	v_mfma_f32_16x16x32_bf16 v[14:17], v[192:195], v[176:179], v[14:17]
	v_mfma_f32_16x16x32_bf16 v[10:13], v[200:203], v[176:179], v[10:13]
	v_mfma_f32_16x16x32_bf16 v[6:9], v[192:195], v[184:187], v[6:9]
	v_mfma_f32_16x16x32_bf16 v[2:5], v[200:203], v[184:187], v[2:5]
	v_mfma_f32_16x16x32_bf16 v[46:49], v[196:199], v[164:167], v[46:49]
	v_mfma_f32_16x16x32_bf16 v[42:45], v[204:207], v[164:167], v[42:45]
	v_mfma_f32_16x16x32_bf16 v[30:33], v[196:199], v[172:175], v[30:33]
	v_mfma_f32_16x16x32_bf16 v[26:29], v[204:207], v[172:175], v[26:29]
	v_mfma_f32_16x16x32_bf16 v[14:17], v[196:199], v[180:183], v[14:17]
	v_mfma_f32_16x16x32_bf16 v[10:13], v[204:207], v[180:183], v[10:13]
	v_mfma_f32_16x16x32_bf16 v[6:9], v[196:199], v[188:191], v[6:9]
	v_mfma_f32_16x16x32_bf16 v[2:5], v[204:207], v[188:191], v[2:5]
	s_barrier
; #define PG8_STAGE(bufoff, gbase, voff) do { _Pragma("unroll") for (int _i = 0; _i < 2; ++_i) \
;         __builtin_amdgcn_global_load_lds((const unsigned*)((const char*)(gbase) + (voff)[_i]), (LAS unsigned*)(lds + (bufoff) + ldsw + _i * 8192), 16, 0, 0); } while (0)
; #define PG8_LDA(dst, b, h) do { _Pragma("unroll") for (int m = 0; m < 4; ++m) _Pragma("unroll") for (int k = 0; k < 2; ++k) dst[m][k] = *(const LAS bf16x8*)(lds + PG8_SA(b, h) + aoff + m * 2048 + k * 1024); } while (0)
; #define PG8_LDB(dst, b, h) do { _Pragma("unroll") for (int n = 0; n < 2; ++n) _Pragma("unroll") for (int k = 0; k < 2; ++k) dst[n][k] = *(const LAS bf16x8*)(lds + PG8_SB(b, h) + boff + n * 2048 + k * 1024); } while (0)
; #define PG8_MMA(ai, bj, At, Bt) do { __builtin_amdgcn_s_setprio(1); _Pragma("unroll") for (int m = 0; m < 4; ++m) _Pragma("unroll") for (int n = 0; n < 2; ++n) _Pragma("unroll") for (int k = 0; k < 2; ++k) \
;         acc[ai][bj][m][n] = __builtin_amdgcn_mfma_f32_16x16x32_bf16(Bt[n][k], At[m][k], acc[ai][bj][m][n], 0, 0, 0); __builtin_amdgcn_s_setprio(0); } while (0)
; #define PG8_WAIT_L(n) asm volatile("s_waitcnt lgkmcnt(" #n ")" ::: "memory")
; #define PG8_BAR __builtin_amdgcn_s_barrier()
; #define PG8_SCHED __builtin_amdgcn_sched_barrier(0)
; template <class Epi, class Sched>
; __device__ __forceinline__ void gemm_phase(LAS unsigned char* lds, const Gemm g, const Sched& S, const Epi& E) {
;     ...
;             PG8_LDB(B0, 1, 0); PG8_SCHED; PG8_LDA(At, 1, 0); PG8_STAGE(PG8_SA(0, 1), a2 + hstep, voffA);
;             PG8_WAIT_L(8); PG8_BAR; PG8_WAIT_L(0); PG8_MMA(0, 0, At, B0); PG8_BAR; PG8_SCHED;
;             PG8_LDB(B1, 1, 1); PG8_STAGE(PG8_SB(1, 0), b3, voffB);
;             PG8_BAR; PG8_WAIT_L(0); PG8_MMA(0, 1, At, B1); PG8_BAR;
;             PG8_LDA(At, 1, 1); PG8_STAGE(PG8_SA(1, 0), a3, voffA);
;             PG8_BAR; PG8_WAIT_L(0); PG8_MMA(1, 0, At, B0); PG8_BAR; PG8_SCHED;
	s_add_u32 s38, s54, 0x200000
	s_addc_u32 s39, s55, 0
	s_add_i32 s50, s50, s63
	s_mov_b32 m0, s50
	ds_read_b128 v[140:143], v226 offset:32768
	global_load_lds_dwordx4 v0, s[38:39]
	s_add_i32 m0, s50, 0x2000
	ds_read_b128 v[144:147], v226 offset:33792
	global_load_lds_dwordx4 v130, s[38:39]
	s_add_u32 s38, s56, 0x200000
	s_addc_u32 s39, s57, 0
	s_mov_b32 m0, s64
	ds_read_b128 v[148:151], v226 offset:34816
	global_load_lds_dwordx4 v0, s[38:39]
	s_mov_b32 m0, s65
	ds_read_b128 v[152:155], v226 offset:35840
	global_load_lds_dwordx4 v130, s[38:39]
	s_add_i32 s50, 0, 0x18000
	ds_read_b128 v[160:163], v139 offset:32768
	ds_read_b128 v[164:167], v139 offset:33792
	ds_read_b128 v[168:171], v139 offset:34816
	ds_read_b128 v[172:175], v139 offset:35840
	ds_read_b128 v[176:179], v139 offset:36864
	ds_read_b128 v[180:183], v139 offset:37888
	ds_read_b128 v[184:187], v139 offset:38912
	ds_read_b128 v[188:191], v139 offset:39936
	s_add_i32 s51, 0, 0x1c000
	ds_read_b128 v[192:195], v226 offset:49152
	ds_read_b128 v[196:199], v226 offset:50176
	ds_read_b128 v[200:203], v226 offset:51200
	ds_read_b128 v[204:207], v226 offset:52224
	s_waitcnt lgkmcnt(4)
	s_barrier
	s_waitcnt lgkmcnt(0)
	v_mfma_f32_16x16x32_bf16 v[126:129], v[140:143], v[160:163], v[126:129]
	v_mfma_f32_16x16x32_bf16 v[122:125], v[148:151], v[160:163], v[122:125]
	v_mfma_f32_16x16x32_bf16 v[118:121], v[140:143], v[168:171], v[118:121]
	v_mfma_f32_16x16x32_bf16 v[114:117], v[148:151], v[168:171], v[114:117]
	v_mfma_f32_16x16x32_bf16 v[106:109], v[140:143], v[176:179], v[106:109]
	v_mfma_f32_16x16x32_bf16 v[98:101], v[148:151], v[176:179], v[98:101]
	v_mfma_f32_16x16x32_bf16 v[90:93], v[140:143], v[184:187], v[90:93]
	v_mfma_f32_16x16x32_bf16 v[82:85], v[148:151], v[184:187], v[82:85]
	v_mfma_f32_16x16x32_bf16 v[126:129], v[144:147], v[164:167], v[126:129]
	v_mfma_f32_16x16x32_bf16 v[122:125], v[152:155], v[164:167], v[122:125]
	v_mfma_f32_16x16x32_bf16 v[118:121], v[144:147], v[172:175], v[118:121]
	v_mfma_f32_16x16x32_bf16 v[114:117], v[152:155], v[172:175], v[114:117]
	v_mfma_f32_16x16x32_bf16 v[106:109], v[144:147], v[180:183], v[106:109]
	v_mfma_f32_16x16x32_bf16 v[98:101], v[152:155], v[180:183], v[98:101]
	v_mfma_f32_16x16x32_bf16 v[90:93], v[144:147], v[188:191], v[90:93]
	v_mfma_f32_16x16x32_bf16 v[82:85], v[152:155], v[188:191], v[82:85]
	v_mfma_f32_16x16x32_bf16 v[110:113], v[192:195], v[160:163], v[110:113]
	v_mfma_f32_16x16x32_bf16 v[102:105], v[200:203], v[160:163], v[102:105]
	v_mfma_f32_16x16x32_bf16 v[94:97], v[192:195], v[168:171], v[94:97]
	v_mfma_f32_16x16x32_bf16 v[86:89], v[200:203], v[168:171], v[86:89]
	v_mfma_f32_16x16x32_bf16 v[78:81], v[192:195], v[176:179], v[78:81]
	v_mfma_f32_16x16x32_bf16 v[74:77], v[200:203], v[176:179], v[74:77]
	v_mfma_f32_16x16x32_bf16 v[70:73], v[192:195], v[184:187], v[70:73]
	v_mfma_f32_16x16x32_bf16 v[66:69], v[200:203], v[184:187], v[66:69]
	v_mfma_f32_16x16x32_bf16 v[110:113], v[196:199], v[164:167], v[110:113]
	v_mfma_f32_16x16x32_bf16 v[102:105], v[204:207], v[164:167], v[102:105]
	v_mfma_f32_16x16x32_bf16 v[94:97], v[196:199], v[172:175], v[94:97]
	v_mfma_f32_16x16x32_bf16 v[86:89], v[204:207], v[172:175], v[86:89]
	v_mfma_f32_16x16x32_bf16 v[78:81], v[196:199], v[180:183], v[78:81]
	v_mfma_f32_16x16x32_bf16 v[74:77], v[204:207], v[180:183], v[74:77]
	v_mfma_f32_16x16x32_bf16 v[70:73], v[196:199], v[188:191], v[70:73]
	v_mfma_f32_16x16x32_bf16 v[66:69], v[204:207], v[188:191], v[66:69]
	s_barrier
	s_add_i32 s38, s50, s63
	s_add_u32 s100, s54, s36
	s_addc_u32 s101, s55, s37
	s_mov_b32 m0, s38
	ds_read_b128 v[160:163], v139 offset:49152
	global_load_lds_dwordx4 v0, s[100:101]
	s_add_i32 m0, s38, 0x2000
	ds_read_b128 v[164:167], v139 offset:50176
	global_load_lds_dwordx4 v130, s[100:101]
	s_mov_b32 m0, s66
	s_add_u32 s100, s56, s36
	s_addc_u32 s101, s57, s37
	global_load_lds_dwordx4 v0, s[100:101]
	s_mov_b32 m0, s67
	ds_read_b128 v[168:171], v139 offset:51200
	global_load_lds_dwordx4 v130, s[100:101]
	ds_read_b128 v[172:175], v139 offset:52224
	ds_read_b128 v[176:179], v139 offset:53248
	ds_read_b128 v[180:183], v139 offset:54272
	ds_read_b128 v[184:187], v139 offset:55296
	ds_read_b128 v[188:191], v139 offset:56320
	s_waitcnt vmcnt(4)
	s_waitcnt lgkmcnt(0)
	s_barrier
; #define PG8_STAGE(bufoff, gbase, voff) do { _Pragma("unroll") for (int _i = 0; _i < 2; ++_i) \
;         __builtin_amdgcn_global_load_lds((const unsigned*)((const char*)(gbase) + (voff)[_i]), (LAS unsigned*)(lds + (bufoff) + ldsw + _i * 8192), 16, 0, 0); } while (0)
; #define PG8_LDA(dst, b, h) do { _Pragma("unroll") for (int m = 0; m < 4; ++m) _Pragma("unroll") for (int k = 0; k < 2; ++k) dst[m][k] = *(const LAS bf16x8*)(lds + PG8_SA(b, h) + aoff + m * 2048 + k * 1024); } while (0)
; #define PG8_LDB(dst, b, h) do { _Pragma("unroll") for (int n = 0; n < 2; ++n) _Pragma("unroll") for (int k = 0; k < 2; ++k) dst[n][k] = *(const LAS bf16x8*)(lds + PG8_SB(b, h) + boff + n * 2048 + k * 1024); } while (0)
; #define PG8_MMA(ai, bj, At, Bt) do { __builtin_amdgcn_s_setprio(1); _Pragma("unroll") for (int m = 0; m < 4; ++m) _Pragma("unroll") for (int n = 0; n < 2; ++n) _Pragma("unroll") for (int k = 0; k < 2; ++k) \
;         acc[ai][bj][m][n] = __builtin_amdgcn_mfma_f32_16x16x32_bf16(Bt[n][k], At[m][k], acc[ai][bj][m][n], 0, 0, 0); __builtin_amdgcn_s_setprio(0); } while (0)
;     __device__ __forceinline__ void operator()(const f32x4 (&acc)[2][2][4][2], const Unit& u, int wr, int wc, int fr, int fq) const {
;         const int row0 = u.pm * BM + wr * 64 + fr, col0 = u.pn * BM + wc * 32 + 4 * fq;
;         float* base = part + (size_t)u.ks * Mp * ldc;
; #pragma unroll
;         for (int ai = 0; ai < 2; ++ai)
; #pragma unroll
;             for (int m = 0; m < 4; ++m) { float* rowp = base + (size_t)(row0 + ai * HALF + m * 16) * ldc + col0;
; #pragma unroll
;                 for (int bj = 0; bj < 2; ++bj)
; #pragma unroll
;                     for (int n = 0; n < 2; ++n) *(f32x4*)(rowp + bj * HALF + n * 16) = acc[ai][bj][m][n]; }
;     }
; template <class Epi, class Sched>
; __device__ __forceinline__ void gemm_phase(LAS unsigned char* lds, const Gemm g, const Sched& S, const Epi& E) {
;     ...
;             PG8_LDB(B1, 1, 1); PG8_STAGE(PG8_SB(1, 0), b3, voffB);
;             PG8_BAR; PG8_WAIT_L(0); PG8_MMA(0, 1, At, B1); PG8_BAR;
;             PG8_LDA(At, 1, 1); PG8_STAGE(PG8_SA(1, 0), a3, voffA);
;             PG8_BAR; PG8_WAIT_L(0); PG8_MMA(1, 0, At, B0); PG8_BAR; PG8_SCHED;
;             PG8_STAGE(PG8_SB(1, 1), b3 + hstep, voffB);
;             PG8_WAIT_V(6); PG8_BAR; PG8_MMA(1, 1, At, B1); PG8_BAR;
;     ...
;     PG8_WAIT_V(0);
;     if (wr == 0) PG8_BAR;
	v_mfma_f32_16x16x32_bf16 v[62:65], v[140:143], v[160:163], v[62:65]
	v_mfma_f32_16x16x32_bf16 v[58:61], v[148:151], v[160:163], v[58:61]
	v_mfma_f32_16x16x32_bf16 v[54:57], v[140:143], v[168:171], v[54:57]
	v_mfma_f32_16x16x32_bf16 v[50:53], v[148:151], v[168:171], v[50:53]
	v_mfma_f32_16x16x32_bf16 v[38:41], v[140:143], v[176:179], v[38:41]
	v_mfma_f32_16x16x32_bf16 v[34:37], v[148:151], v[176:179], v[34:37]
	v_mfma_f32_16x16x32_bf16 v[22:25], v[140:143], v[184:187], v[22:25]
	v_mfma_f32_16x16x32_bf16 v[18:21], v[148:151], v[184:187], v[18:21]
	v_mfma_f32_16x16x32_bf16 v[62:65], v[144:147], v[164:167], v[62:65]
	v_mfma_f32_16x16x32_bf16 v[58:61], v[152:155], v[164:167], v[58:61]
	v_mfma_f32_16x16x32_bf16 v[54:57], v[144:147], v[172:175], v[54:57]
	v_mfma_f32_16x16x32_bf16 v[50:53], v[152:155], v[172:175], v[50:53]
	v_mfma_f32_16x16x32_bf16 v[38:41], v[144:147], v[180:183], v[38:41]
	v_mfma_f32_16x16x32_bf16 v[34:37], v[152:155], v[180:183], v[34:37]
	v_mfma_f32_16x16x32_bf16 v[22:25], v[144:147], v[188:191], v[22:25]
	v_mfma_f32_16x16x32_bf16 v[18:21], v[152:155], v[188:191], v[18:21]
	s_add_u32 s38, s54, 0x200080
	s_addc_u32 s39, s55, 0
	s_add_i32 s50, s51, s63
	s_mov_b32 m0, s50
	s_nop 0
	global_load_lds_dwordx4 v0, s[38:39]
	s_add_i32 m0, s50, 0x2000
	s_nop 0
	global_load_lds_dwordx4 v130, s[38:39]
	v_mfma_f32_16x16x32_bf16 v[46:49], v[192:195], v[160:163], v[46:49]
	v_mfma_f32_16x16x32_bf16 v[42:45], v[200:203], v[160:163], v[42:45]
	v_mfma_f32_16x16x32_bf16 v[30:33], v[192:195], v[168:171], v[30:33]
	v_mfma_f32_16x16x32_bf16 v[26:29], v[200:203], v[168:171], v[26:29]
	v_mfma_f32_16x16x32_bf16 v[14:17], v[192:195], v[176:179], v[14:17]
	v_mfma_f32_16x16x32_bf16 v[10:13], v[200:203], v[176:179], v[10:13]
	v_mfma_f32_16x16x32_bf16 v[6:9], v[192:195], v[184:187], v[6:9]
	v_mfma_f32_16x16x32_bf16 v[2:5], v[200:203], v[184:187], v[2:5]
	v_mfma_f32_16x16x32_bf16 v[46:49], v[196:199], v[164:167], v[46:49]
	v_mfma_f32_16x16x32_bf16 v[42:45], v[204:207], v[164:167], v[42:45]
	v_mfma_f32_16x16x32_bf16 v[30:33], v[196:199], v[172:175], v[30:33]
	v_mfma_f32_16x16x32_bf16 v[26:29], v[204:207], v[172:175], v[26:29]
	v_mfma_f32_16x16x32_bf16 v[14:17], v[196:199], v[180:183], v[14:17]
	v_mfma_f32_16x16x32_bf16 v[10:13], v[204:207], v[180:183], v[10:13]
	v_mfma_f32_16x16x32_bf16 v[6:9], v[196:199], v[188:191], v[6:9]
	v_mfma_f32_16x16x32_bf16 v[2:5], v[204:207], v[188:191], v[2:5]
	s_cmp_gt_i32 s71, 27
	s_barrier
	s_cbranch_scc0 .LBB0_58
	s_ashr_i32 s11, s10, 31
	s_lshl_b64 s[10:11], s[10:11], 24
	v_lshl_or_b32 v140, s26, 8, v138
	s_add_u32 s10, s8, s10
	v_lshl_add_u32 v142, s24, 8, v136
	s_addc_u32 s11, s9, s11
	v_ashrrev_i32_e32 v141, 31, v140
	v_ashrrev_i32_e32 v143, 31, v142
	v_lshl_add_u64 v[140:141], v[140:141], 2, s[10:11]
	v_lshlrev_b64 v[144:145], 13, v[142:143]
	v_lshl_add_u64 v[144:145], v[140:141], 0, v[144:145]
	global_store_dwordx4 v[144:145], v[126:129], off
	global_store_dwordx4 v[144:145], v[122:125], off offset:64
	global_store_dwordx4 v[144:145], v[110:113], off offset:512
	global_store_dwordx4 v[144:145], v[102:105], off offset:576
	s_mov_b64 s[10:11], 0x100000
	s_mov_b32 s26, s40
	v_or_b32_e32 v102, 16, v142
	v_ashrrev_i32_e32 v103, 31, v102
	v_lshlrev_b64 v[102:103], 13, v[102:103]
	v_lshl_add_u64 v[102:103], v[140:141], 0, v[102:103]
	global_store_dwordx4 v[102:103], v[118:121], off
	global_store_dwordx4 v[102:103], v[114:117], off offset:64
	global_store_dwordx4 v[102:103], v[94:97], off offset:512
	global_store_dwordx4 v[102:103], v[86:89], off offset:576
	s_mov_b32 s24, s42
	s_mov_b64 s[52:53], s[48:49]
	v_or_b32_e32 v86, 32, v142
	v_ashrrev_i32_e32 v87, 31, v86
	v_lshlrev_b64 v[86:87], 13, v[86:87]
	v_lshl_add_u64 v[86:87], v[140:141], 0, v[86:87]
	global_store_dwordx4 v[86:87], v[106:109], off
	global_store_dwordx4 v[86:87], v[98:101], off offset:64
	global_store_dwordx4 v[86:87], v[78:81], off offset:512
	global_store_dwordx4 v[86:87], v[74:77], off offset:576
	s_mov_b64 s[50:51], s[46:47]
	s_nop 0
	v_or_b32_e32 v74, 48, v142
	v_ashrrev_i32_e32 v75, 31, v74
	v_lshlrev_b64 v[74:75], 13, v[74:75]
	v_lshl_add_u64 v[74:75], v[140:141], 0, v[74:75]
	global_store_dwordx4 v[74:75], v[90:93], off
	global_store_dwordx4 v[74:75], v[82:85], off offset:64
	global_store_dwordx4 v[74:75], v[70:73], off offset:512
	global_store_dwordx4 v[74:75], v[66:69], off offset:576
	s_nop 1
	v_add_co_u32_e32 v68, vcc, s93, v144
	v_lshl_add_u64 v[66:67], v[144:145], 0, s[10:11]
	s_nop 0
	v_addc_co_u32_e32 v69, vcc, 0, v145, vcc
	s_mov_b64 s[10:11], 0x120000
	global_store_dwordx4 v[68:69], v[62:65], off
	global_store_dwordx4 v[66:67], v[58:61], off offset:64
	global_store_dwordx4 v[66:67], v[46:49], off offset:512
	global_store_dwordx4 v[66:67], v[42:45], off offset:576
	s_nop 1
	v_lshl_add_u64 v[42:43], v[144:145], 0, s[10:11]
	s_mov_b32 s10, 0x120000
	v_add_co_u32_e32 v44, vcc, s10, v144
	s_mov_b64 s[10:11], 0x140000
	s_nop 0
	v_addc_co_u32_e32 v45, vcc, 0, v145, vcc
	global_store_dwordx4 v[44:45], v[54:57], off
	global_store_dwordx4 v[42:43], v[50:53], off offset:64
	global_store_dwordx4 v[42:43], v[30:33], off offset:512
	global_store_dwordx4 v[42:43], v[26:29], off offset:576
	s_nop 1
	v_lshl_add_u64 v[26:27], v[144:145], 0, s[10:11]
	s_mov_b32 s10, 0x140000
	v_add_co_u32_e32 v28, vcc, s10, v144
	s_mov_b64 s[10:11], 0x160000
	s_nop 0
	v_addc_co_u32_e32 v29, vcc, 0, v145, vcc
	global_store_dwordx4 v[28:29], v[38:41], off
	global_store_dwordx4 v[26:27], v[34:37], off offset:64
	global_store_dwordx4 v[26:27], v[14:17], off offset:512
	global_store_dwordx4 v[26:27], v[10:13], off offset:576
	s_nop 1
	v_add_co_u32_e32 v12, vcc, 0x160000, v144
	v_lshl_add_u64 v[10:11], v[144:145], 0, s[10:11]
	s_nop 0
	v_addc_co_u32_e32 v13, vcc, 0, v145, vcc
	s_and_b64 vcc, exec, s[44:45]
	s_mov_b32 s10, s28
	global_store_dwordx4 v[12:13], v[22:25], off
	global_store_dwordx4 v[10:11], v[18:21], off offset:64
	global_store_dwordx4 v[10:11], v[6:9], off offset:512
	global_store_dwordx4 v[10:11], v[2:5], off offset:576
	s_cbranch_vccz .LBB0_55
	s_waitcnt vmcnt(0)
	s_cmpk_gt_u32 s60, 0xff
	s_cbranch_scc1 .LBB0_62
	s_barrier

; #define PG8_STAGE(bufoff, gbase, voff) do { _Pragma("unroll") for (int _i = 0; _i < 2; ++_i) \
;         __builtin_amdgcn_global_load_lds((const unsigned*)((const char*)(gbase) + (voff)[_i]), (LAS unsigned*)(lds + (bufoff) + ldsw + _i * 8192), 16, 0, 0); } while (0)
; #define PG8_LDA(dst, b, h) do { _Pragma("unroll") for (int m = 0; m < 4; ++m) _Pragma("unroll") for (int k = 0; k < 2; ++k) dst[m][k] = *(const LAS bf16x8*)(lds + PG8_SA(b, h) + aoff + m * 2048 + k * 1024); } while (0)
; #define PG8_LDB(dst, b, h) do { _Pragma("unroll") for (int n = 0; n < 2; ++n) _Pragma("unroll") for (int k = 0; k < 2; ++k) dst[n][k] = *(const LAS bf16x8*)(lds + PG8_SB(b, h) + boff + n * 2048 + k * 1024); } while (0)
; #define PG8_SCHED __builtin_amdgcn_sched_barrier(0)
; template <class Epi, class Sched>
; __device__ __forceinline__ void gemm_phase(LAS unsigned char* lds, const Gemm g, const Sched& S, const Epi& E) {
;     ...
;         const bool has_next = S.next(ui + 1, nxt);
;         const char* nA = has_next ? (const char*)g.A + (size_t)nxt.pm * tstep + (size_t)nxt.ks * sstep : cA; const char* nB = has_next ? (const char*)g.Bt + (size_t)nxt.pn * tstep + (size_t)nxt.ks * sstep : cB;
;         for (int t = 0; t < nt; t += 2) {
;             const bool last = (t == nt - 2);
;             const char* a1 = cA + (size_t)(t + 1) * kstep;
;             const char* a2 = last ? nA : cA + (size_t)(t + 2) * kstep; const char* b2 = last ? nB : cB + (size_t)(t + 2) * kstep;
;             const char* a3 = a2 + kstep; const char* b3 = b2 + kstep;
;             PG8_LDB(B0, 0, 0); PG8_SCHED; PG8_LDA(At, 0, 0); PG8_STAGE(PG8_SA(1, 1), a1 + hstep, voffA);
;     ...
; #pragma unroll
;         for (int a = 0; a < 2; ++a)
; #pragma unroll
;             for (int b = 0; b < 2; ++b)
; #pragma unroll
;                 for (int m = 0; m < 4; ++m)
; #pragma unroll
;                     for (int n = 0; n < 2; ++n) acc[a][b][m][n] = (f32x4){0.f, 0.f, 0.f, 0.f};
;         cur = nxt; cA = nA; cB = nB; ++ui;
.LBB0_72:
	s_ashr_i32 s29, s28, 31
	v_mov_b64_e32 v[2:3], s[30:31]
	s_lshl_b64 s[38:39], s[28:29], 20
	v_cmp_lt_i64_e32 vcc, s[42:43], v[2:3]
	s_add_u32 s42, s10, s38
	s_addc_u32 s43, s11, s39
	s_and_b64 s[38:39], vcc, exec
	s_cselect_b32 s29, s43, s49
	s_cselect_b32 s69, s42, s48
	s_ashr_i32 s27, s26, 31
	s_lshl_b64 s[38:39], s[26:27], 20
	s_add_u32 s44, s53, s38
	s_addc_u32 s45, s54, s39
	s_and_b64 s[38:39], vcc, exec
	s_cselect_b32 s27, s45, s47
	s_cselect_b32 s70, s44, s46
	s_add_u32 s71, s46, 0x100
	s_addc_u32 s72, s47, 0
	s_add_u32 s46, s48, 0x80080
	v_mov_b32_e32 v2, 0
	s_addc_u32 s47, s49, 0
	s_mov_b32 s73, -2
	v_mov_b32_e32 v3, v2
	v_mov_b32_e32 v4, v2
	v_mov_b32_e32 v5, v2
	v_mov_b32_e32 v6, v2
	v_mov_b32_e32 v7, v2
	v_mov_b32_e32 v8, v2
	v_mov_b32_e32 v9, v2
	v_mov_b32_e32 v18, v2
	v_mov_b32_e32 v19, v2
	v_mov_b32_e32 v20, v2
	v_mov_b32_e32 v21, v2
	v_mov_b32_e32 v22, v2
	v_mov_b32_e32 v23, v2
	v_mov_b32_e32 v24, v2
	v_mov_b32_e32 v25, v2
	v_mov_b32_e32 v34, v2
	v_mov_b32_e32 v35, v2
	v_mov_b32_e32 v36, v2
	v_mov_b32_e32 v37, v2
	v_mov_b32_e32 v38, v2
	v_mov_b32_e32 v39, v2
	v_mov_b32_e32 v40, v2
	v_mov_b32_e32 v41, v2
	v_mov_b32_e32 v50, v2
	v_mov_b32_e32 v51, v2
	v_mov_b32_e32 v52, v2
	v_mov_b32_e32 v53, v2
	v_mov_b32_e32 v54, v2
	v_mov_b32_e32 v55, v2
	v_mov_b32_e32 v56, v2
	v_mov_b32_e32 v57, v2
	v_mov_b32_e32 v10, v2
	v_mov_b32_e32 v11, v2
	v_mov_b32_e32 v12, v2
	v_mov_b32_e32 v13, v2
	v_mov_b32_e32 v14, v2
	v_mov_b32_e32 v15, v2
	v_mov_b32_e32 v16, v2
	v_mov_b32_e32 v17, v2
	v_mov_b32_e32 v26, v2
	v_mov_b32_e32 v27, v2
	v_mov_b32_e32 v28, v2
	v_mov_b32_e32 v29, v2
	v_mov_b32_e32 v30, v2
	v_mov_b32_e32 v31, v2
	v_mov_b32_e32 v32, v2
	v_mov_b32_e32 v33, v2
	v_mov_b32_e32 v42, v2
	v_mov_b32_e32 v43, v2
	v_mov_b32_e32 v44, v2
	v_mov_b32_e32 v45, v2
	v_mov_b32_e32 v46, v2
	v_mov_b32_e32 v47, v2
	v_mov_b32_e32 v48, v2
	v_mov_b32_e32 v49, v2
	v_mov_b32_e32 v58, v2
	v_mov_b32_e32 v59, v2
	v_mov_b32_e32 v60, v2
	v_mov_b32_e32 v61, v2
	v_mov_b32_e32 v62, v2
	v_mov_b32_e32 v63, v2
	v_mov_b32_e32 v64, v2
	v_mov_b32_e32 v65, v2
	v_mov_b32_e32 v66, v2
	v_mov_b32_e32 v67, v2
	v_mov_b32_e32 v68, v2
	v_mov_b32_e32 v69, v2
	v_mov_b32_e32 v70, v2
	v_mov_b32_e32 v71, v2
	v_mov_b32_e32 v72, v2
	v_mov_b32_e32 v73, v2
	v_mov_b32_e32 v82, v2
	v_mov_b32_e32 v83, v2
	v_mov_b32_e32 v84, v2
	v_mov_b32_e32 v85, v2
	v_mov_b32_e32 v86, v2
	v_mov_b32_e32 v87, v2
	v_mov_b32_e32 v88, v2
	v_mov_b32_e32 v89, v2
	v_mov_b32_e32 v98, v2
	v_mov_b32_e32 v99, v2
	v_mov_b32_e32 v100, v2
	v_mov_b32_e32 v101, v2
	v_mov_b32_e32 v102, v2
	v_mov_b32_e32 v103, v2
	v_mov_b32_e32 v104, v2
	v_mov_b32_e32 v105, v2
	v_mov_b32_e32 v114, v2
	v_mov_b32_e32 v115, v2
	v_mov_b32_e32 v116, v2
	v_mov_b32_e32 v117, v2
	v_mov_b32_e32 v118, v2
	v_mov_b32_e32 v119, v2
	v_mov_b32_e32 v120, v2
	v_mov_b32_e32 v121, v2
	v_mov_b32_e32 v74, v2
	v_mov_b32_e32 v75, v2
	v_mov_b32_e32 v76, v2
	v_mov_b32_e32 v77, v2
	v_mov_b32_e32 v78, v2
	v_mov_b32_e32 v79, v2
	v_mov_b32_e32 v80, v2
	v_mov_b32_e32 v81, v2
	v_mov_b32_e32 v90, v2
	v_mov_b32_e32 v91, v2
	v_mov_b32_e32 v92, v2
	v_mov_b32_e32 v93, v2
	v_mov_b32_e32 v94, v2
	v_mov_b32_e32 v95, v2
	v_mov_b32_e32 v96, v2
	v_mov_b32_e32 v97, v2
	v_mov_b32_e32 v106, v2
	v_mov_b32_e32 v107, v2
	v_mov_b32_e32 v108, v2
	v_mov_b32_e32 v109, v2
	v_mov_b32_e32 v110, v2
	v_mov_b32_e32 v111, v2
	v_mov_b32_e32 v112, v2
	v_mov_b32_e32 v113, v2
	v_mov_b32_e32 v122, v2
	v_mov_b32_e32 v123, v2
	v_mov_b32_e32 v124, v2
	v_mov_b32_e32 v125, v2
	v_mov_b32_e32 v126, v2
	v_mov_b32_e32 v127, v2
	v_mov_b32_e32 v128, v2
	v_mov_b32_e32 v129, v2
	s_branch .Lent_73
.LBB0_73:
	s_add_i32 s73, s73, 2
	s_add_u32 s71, s71, 0x100
	s_addc_u32 s72, s72, 0
	s_add_u32 s46, s46, 0x100
	s_addc_u32 s47, s47, 0
.Lent_73:
	s_add_u32 s38, s46, 0xfff80080
	s_addc_u32 s39, s47, -1
	s_cmp_eq_u32 s73, 28
	s_cselect_b32 s51, s29, s39
	s_cselect_b32 s50, s69, s38
	s_cselect_b32 s49, s27, s72
	s_cselect_b32 s48, s70, s71
	s_add_i32 m0, s9, 0xc000
	ds_read_b128 v[146:149], v226
	global_load_lds_dwordx4 v138, s[46:47]
	s_add_i32 m0, s9, 0xe000
	ds_read_b128 v[150:153], v226 offset:1024
	global_load_lds_dwordx4 v136, s[46:47]
	s_add_i32 s74, 0, 0x10000
	ds_read_b128 v[154:157], v226 offset:2048
	ds_read_b128 v[160:163], v226 offset:3072
	ds_read_b128 v[164:167], v145
	ds_read_b128 v[168:171], v145 offset:1024
	ds_read_b128 v[172:175], v145 offset:2048
	ds_read_b128 v[176:179], v145 offset:3072
	ds_read_b128 v[180:183], v145 offset:4096
	ds_read_b128 v[184:187], v145 offset:5120
	ds_read_b128 v[188:191], v145 offset:6144
	ds_read_b128 v[192:195], v145 offset:7168
	s_add_i32 s75, 0, 0x14000
	ds_read_b128 v[196:199], v226 offset:16384
	ds_read_b128 v[200:203], v226 offset:17408
	ds_read_b128 v[204:207], v226 offset:18432
	ds_read_b128 v[210:213], v226 offset:19456
	s_waitcnt lgkmcnt(4)
	s_barrier
; #define PG8_STAGE(bufoff, gbase, voff) do { _Pragma("unroll") for (int _i = 0; _i < 2; ++_i) \
;         __builtin_amdgcn_global_load_lds((const unsigned*)((const char*)(gbase) + (voff)[_i]), (LAS unsigned*)(lds + (bufoff) + ldsw + _i * 8192), 16, 0, 0); } while (0)
; #define PG8_LDA(dst, b, h) do { _Pragma("unroll") for (int m = 0; m < 4; ++m) _Pragma("unroll") for (int k = 0; k < 2; ++k) dst[m][k] = *(const LAS bf16x8*)(lds + PG8_SA(b, h) + aoff + m * 2048 + k * 1024); } while (0)
; #define PG8_LDB(dst, b, h) do { _Pragma("unroll") for (int n = 0; n < 2; ++n) _Pragma("unroll") for (int k = 0; k < 2; ++k) dst[n][k] = *(const LAS bf16x8*)(lds + PG8_SB(b, h) + boff + n * 2048 + k * 1024); } while (0)
; #define PG8_MMA(ai, bj, At, Bt) do { __builtin_amdgcn_s_setprio(1); _Pragma("unroll") for (int m = 0; m < 4; ++m) _Pragma("unroll") for (int n = 0; n < 2; ++n) _Pragma("unroll") for (int k = 0; k < 2; ++k) \
;         acc[ai][bj][m][n] = __builtin_amdgcn_mfma_f32_16x16x32_bf16(Bt[n][k], At[m][k], acc[ai][bj][m][n], 0, 0, 0); __builtin_amdgcn_s_setprio(0); } while (0)
; #define PG8_WAIT_V(n) asm volatile("s_waitcnt vmcnt(" #n ")" ::: "memory")
; #define PG8_WAIT_L(n) asm volatile("s_waitcnt lgkmcnt(" #n ")" ::: "memory")
; #define PG8_BAR __builtin_amdgcn_s_barrier()
; #define PG8_SCHED __builtin_amdgcn_sched_barrier(0)
; template <class Epi, class Sched>
; __device__ __forceinline__ void gemm_phase(LAS unsigned char* lds, const Gemm g, const Sched& S, const Epi& E) {
;     ...
;             PG8_LDB(B0, 0, 0); PG8_SCHED; PG8_LDA(At, 0, 0); PG8_STAGE(PG8_SA(1, 1), a1 + hstep, voffA);
;             PG8_WAIT_L(8); PG8_BAR; PG8_WAIT_L(0); PG8_MMA(0, 0, At, B0); PG8_BAR; PG8_SCHED;
;             PG8_LDB(B1, 0, 1); PG8_STAGE(PG8_SB(0, 0), b2, voffB);
;             PG8_BAR; PG8_WAIT_L(0); PG8_MMA(0, 1, At, B1); PG8_BAR;
;             PG8_LDA(At, 0, 1); PG8_STAGE(PG8_SA(0, 0), a2, voffA);
;             PG8_BAR; PG8_WAIT_L(0); PG8_MMA(1, 0, At, B0); PG8_BAR; PG8_SCHED;
;             PG8_STAGE(PG8_SB(0, 1), b2 + hstep, voffB);
;             PG8_WAIT_V(6); PG8_BAR; PG8_MMA(1, 1, At, B1); PG8_BAR;
	s_waitcnt lgkmcnt(0)
	v_mfma_f32_16x16x32_bf16 v[126:129], v[146:149], v[164:167], v[126:129]
	v_mfma_f32_16x16x32_bf16 v[122:125], v[154:157], v[164:167], v[122:125]
	v_mfma_f32_16x16x32_bf16 v[110:113], v[146:149], v[172:175], v[110:113]
	v_mfma_f32_16x16x32_bf16 v[106:109], v[154:157], v[172:175], v[106:109]
	v_mfma_f32_16x16x32_bf16 v[94:97], v[146:149], v[180:183], v[94:97]
	v_mfma_f32_16x16x32_bf16 v[90:93], v[154:157], v[180:183], v[90:93]
	v_mfma_f32_16x16x32_bf16 v[78:81], v[146:149], v[188:191], v[78:81]
	v_mfma_f32_16x16x32_bf16 v[74:77], v[154:157], v[188:191], v[74:77]
	v_mfma_f32_16x16x32_bf16 v[126:129], v[150:153], v[168:171], v[126:129]
	v_mfma_f32_16x16x32_bf16 v[122:125], v[160:163], v[168:171], v[122:125]
	v_mfma_f32_16x16x32_bf16 v[110:113], v[150:153], v[176:179], v[110:113]
	v_mfma_f32_16x16x32_bf16 v[106:109], v[160:163], v[176:179], v[106:109]
	v_mfma_f32_16x16x32_bf16 v[94:97], v[150:153], v[184:187], v[94:97]
	v_mfma_f32_16x16x32_bf16 v[90:93], v[160:163], v[184:187], v[90:93]
	v_mfma_f32_16x16x32_bf16 v[78:81], v[150:153], v[192:195], v[78:81]
	v_mfma_f32_16x16x32_bf16 v[74:77], v[160:163], v[192:195], v[74:77]
	v_mfma_f32_16x16x32_bf16 v[118:121], v[196:199], v[164:167], v[118:121]
	v_mfma_f32_16x16x32_bf16 v[114:117], v[204:207], v[164:167], v[114:117]
	v_mfma_f32_16x16x32_bf16 v[102:105], v[196:199], v[172:175], v[102:105]
	v_mfma_f32_16x16x32_bf16 v[98:101], v[204:207], v[172:175], v[98:101]
	v_mfma_f32_16x16x32_bf16 v[86:89], v[196:199], v[180:183], v[86:89]
	v_mfma_f32_16x16x32_bf16 v[82:85], v[204:207], v[180:183], v[82:85]
	v_mfma_f32_16x16x32_bf16 v[70:73], v[196:199], v[188:191], v[70:73]
	v_mfma_f32_16x16x32_bf16 v[66:69], v[204:207], v[188:191], v[66:69]
	v_mfma_f32_16x16x32_bf16 v[118:121], v[200:203], v[168:171], v[118:121]
	v_mfma_f32_16x16x32_bf16 v[114:117], v[210:213], v[168:171], v[114:117]
	v_mfma_f32_16x16x32_bf16 v[102:105], v[200:203], v[176:179], v[102:105]
	v_mfma_f32_16x16x32_bf16 v[98:101], v[210:213], v[176:179], v[98:101]
	v_mfma_f32_16x16x32_bf16 v[86:89], v[200:203], v[184:187], v[86:89]
	v_mfma_f32_16x16x32_bf16 v[82:85], v[210:213], v[184:187], v[82:85]
	v_mfma_f32_16x16x32_bf16 v[70:73], v[200:203], v[192:195], v[70:73]
	v_mfma_f32_16x16x32_bf16 v[66:69], v[210:213], v[192:195], v[66:69]
	s_barrier
	s_add_i32 s38, s74, s56
	s_mov_b32 m0, s38
	ds_read_b128 v[164:167], v145 offset:16384
	global_load_lds_dwordx4 v0, s[48:49]
	s_add_i32 m0, s38, 0x2000
	ds_read_b128 v[168:171], v145 offset:17408
	global_load_lds_dwordx4 v130, s[48:49]
	s_mov_b32 m0, s9
	ds_read_b128 v[172:175], v145 offset:18432
	global_load_lds_dwordx4 v134, s[50:51]
	s_mov_b32 m0, s60
	ds_read_b128 v[176:179], v145 offset:19456
	global_load_lds_dwordx4 v132, s[50:51]
	ds_read_b128 v[180:183], v145 offset:20480
	ds_read_b128 v[184:187], v145 offset:21504
	ds_read_b128 v[188:191], v145 offset:22528
	ds_read_b128 v[192:195], v145 offset:23552
	s_waitcnt vmcnt(4)
	s_waitcnt lgkmcnt(0)
	s_barrier
	v_mfma_f32_16x16x32_bf16 v[62:65], v[146:149], v[164:167], v[62:65]
	v_mfma_f32_16x16x32_bf16 v[58:61], v[154:157], v[164:167], v[58:61]
	v_mfma_f32_16x16x32_bf16 v[46:49], v[146:149], v[172:175], v[46:49]
	v_mfma_f32_16x16x32_bf16 v[42:45], v[154:157], v[172:175], v[42:45]
	v_mfma_f32_16x16x32_bf16 v[30:33], v[146:149], v[180:183], v[30:33]
	v_mfma_f32_16x16x32_bf16 v[26:29], v[154:157], v[180:183], v[26:29]
	v_mfma_f32_16x16x32_bf16 v[14:17], v[146:149], v[188:191], v[14:17]
	v_mfma_f32_16x16x32_bf16 v[10:13], v[154:157], v[188:191], v[10:13]
	v_mfma_f32_16x16x32_bf16 v[62:65], v[150:153], v[168:171], v[62:65]
	v_mfma_f32_16x16x32_bf16 v[58:61], v[160:163], v[168:171], v[58:61]
	v_mfma_f32_16x16x32_bf16 v[46:49], v[150:153], v[176:179], v[46:49]
	v_mfma_f32_16x16x32_bf16 v[42:45], v[160:163], v[176:179], v[42:45]
	v_mfma_f32_16x16x32_bf16 v[30:33], v[150:153], v[184:187], v[30:33]
	v_mfma_f32_16x16x32_bf16 v[26:29], v[160:163], v[184:187], v[26:29]
	v_mfma_f32_16x16x32_bf16 v[14:17], v[150:153], v[192:195], v[14:17]
	v_mfma_f32_16x16x32_bf16 v[10:13], v[160:163], v[192:195], v[10:13]
	v_mfma_f32_16x16x32_bf16 v[54:57], v[196:199], v[164:167], v[54:57]
	v_mfma_f32_16x16x32_bf16 v[50:53], v[204:207], v[164:167], v[50:53]
	v_mfma_f32_16x16x32_bf16 v[38:41], v[196:199], v[172:175], v[38:41]
	v_mfma_f32_16x16x32_bf16 v[34:37], v[204:207], v[172:175], v[34:37]
	v_mfma_f32_16x16x32_bf16 v[22:25], v[196:199], v[180:183], v[22:25]
	v_mfma_f32_16x16x32_bf16 v[18:21], v[204:207], v[180:183], v[18:21]
	v_mfma_f32_16x16x32_bf16 v[6:9], v[196:199], v[188:191], v[6:9]
	v_mfma_f32_16x16x32_bf16 v[2:5], v[204:207], v[188:191], v[2:5]
	v_mfma_f32_16x16x32_bf16 v[54:57], v[200:203], v[168:171], v[54:57]
	v_mfma_f32_16x16x32_bf16 v[50:53], v[210:213], v[168:171], v[50:53]
	v_mfma_f32_16x16x32_bf16 v[38:41], v[200:203], v[176:179], v[38:41]
	v_mfma_f32_16x16x32_bf16 v[34:37], v[210:213], v[176:179], v[34:37]
	v_mfma_f32_16x16x32_bf16 v[22:25], v[200:203], v[184:187], v[22:25]
	v_mfma_f32_16x16x32_bf16 v[18:21], v[210:213], v[184:187], v[18:21]
	v_mfma_f32_16x16x32_bf16 v[6:9], v[200:203], v[192:195], v[6:9]
	v_mfma_f32_16x16x32_bf16 v[2:5], v[210:213], v[192:195], v[2:5]
	s_barrier
; #define PG8_STAGE(bufoff, gbase, voff) do { _Pragma("unroll") for (int _i = 0; _i < 2; ++_i) \
;         __builtin_amdgcn_global_load_lds((const unsigned*)((const char*)(gbase) + (voff)[_i]), (LAS unsigned*)(lds + (bufoff) + ldsw + _i * 8192), 16, 0, 0); } while (0)
; #define PG8_LDA(dst, b, h) do { _Pragma("unroll") for (int m = 0; m < 4; ++m) _Pragma("unroll") for (int k = 0; k < 2; ++k) dst[m][k] = *(const LAS bf16x8*)(lds + PG8_SA(b, h) + aoff + m * 2048 + k * 1024); } while (0)
; #define PG8_LDB(dst, b, h) do { _Pragma("unroll") for (int n = 0; n < 2; ++n) _Pragma("unroll") for (int k = 0; k < 2; ++k) dst[n][k] = *(const LAS bf16x8*)(lds + PG8_SB(b, h) + boff + n * 2048 + k * 1024); } while (0)
; #define PG8_MMA(ai, bj, At, Bt) do { __builtin_amdgcn_s_setprio(1); _Pragma("unroll") for (int m = 0; m < 4; ++m) _Pragma("unroll") for (int n = 0; n < 2; ++n) _Pragma("unroll") for (int k = 0; k < 2; ++k) \
;         acc[ai][bj][m][n] = __builtin_amdgcn_mfma_f32_16x16x32_bf16(Bt[n][k], At[m][k], acc[ai][bj][m][n], 0, 0, 0); __builtin_amdgcn_s_setprio(0); } while (0)
; #define PG8_WAIT_V(n) asm volatile("s_waitcnt vmcnt(" #n ")" ::: "memory")
; #define PG8_WAIT_L(n) asm volatile("s_waitcnt lgkmcnt(" #n ")" ::: "memory")
; #define PG8_BAR __builtin_amdgcn_s_barrier()
; #define PG8_SCHED __builtin_amdgcn_sched_barrier(0)
; template <class Epi, class Sched>
; __device__ __forceinline__ void gemm_phase(LAS unsigned char* lds, const Gemm g, const Sched& S, const Epi& E) {
;     ...
;             PG8_LDB(B0, 1, 0); PG8_SCHED; PG8_LDA(At, 1, 0); PG8_STAGE(PG8_SA(0, 1), a2 + hstep, voffA);
;             PG8_WAIT_L(8); PG8_BAR; PG8_WAIT_L(0); PG8_MMA(0, 0, At, B0); PG8_BAR; PG8_SCHED;
;             PG8_LDB(B1, 1, 1); PG8_STAGE(PG8_SB(1, 0), b3, voffB);
;             PG8_BAR; PG8_WAIT_L(0); PG8_MMA(0, 1, At, B1); PG8_BAR;
;             PG8_LDA(At, 1, 1); PG8_STAGE(PG8_SA(1, 0), a3, voffA);
;             PG8_BAR; PG8_WAIT_L(0); PG8_MMA(1, 0, At, B0); PG8_BAR; PG8_SCHED;
;             PG8_STAGE(PG8_SB(1, 1), b3 + hstep, voffB);
;             PG8_WAIT_V(6); PG8_BAR; PG8_MMA(1, 1, At, B1); PG8_BAR;
	s_add_u32 s38, s48, 0x80000
	s_addc_u32 s39, s49, 0
	s_add_i32 s74, s75, s56
	s_mov_b32 m0, s74
	ds_read_b128 v[146:149], v226 offset:32768
	global_load_lds_dwordx4 v0, s[38:39]
	s_add_i32 m0, s74, 0x2000
	ds_read_b128 v[150:153], v226 offset:33792
	global_load_lds_dwordx4 v130, s[38:39]
	s_add_u32 s38, s50, 0x80000
	s_addc_u32 s39, s51, 0
	s_mov_b32 m0, s61
	ds_read_b128 v[154:157], v226 offset:34816
	global_load_lds_dwordx4 v134, s[38:39]
	s_mov_b32 m0, s62
	ds_read_b128 v[160:163], v226 offset:35840
	global_load_lds_dwordx4 v132, s[38:39]
	s_add_i32 s74, 0, 0x18000
	ds_read_b128 v[164:167], v145 offset:32768
	ds_read_b128 v[168:171], v145 offset:33792
	ds_read_b128 v[172:175], v145 offset:34816
	ds_read_b128 v[176:179], v145 offset:35840
	ds_read_b128 v[180:183], v145 offset:36864
	ds_read_b128 v[184:187], v145 offset:37888
	ds_read_b128 v[188:191], v145 offset:38912
	ds_read_b128 v[192:195], v145 offset:39936
	s_nop 0
	ds_read_b128 v[196:199], v226 offset:49152
	ds_read_b128 v[200:203], v226 offset:50176
	ds_read_b128 v[204:207], v226 offset:51200
	ds_read_b128 v[210:213], v226 offset:52224
	s_waitcnt lgkmcnt(4)
	s_barrier
	s_waitcnt lgkmcnt(0)
	v_mfma_f32_16x16x32_bf16 v[126:129], v[146:149], v[164:167], v[126:129]
	v_mfma_f32_16x16x32_bf16 v[122:125], v[154:157], v[164:167], v[122:125]
	v_mfma_f32_16x16x32_bf16 v[110:113], v[146:149], v[172:175], v[110:113]
	v_mfma_f32_16x16x32_bf16 v[106:109], v[154:157], v[172:175], v[106:109]
	v_mfma_f32_16x16x32_bf16 v[94:97], v[146:149], v[180:183], v[94:97]
	v_mfma_f32_16x16x32_bf16 v[90:93], v[154:157], v[180:183], v[90:93]
	v_mfma_f32_16x16x32_bf16 v[78:81], v[146:149], v[188:191], v[78:81]
	v_mfma_f32_16x16x32_bf16 v[74:77], v[154:157], v[188:191], v[74:77]
	v_mfma_f32_16x16x32_bf16 v[126:129], v[150:153], v[168:171], v[126:129]
	v_mfma_f32_16x16x32_bf16 v[122:125], v[160:163], v[168:171], v[122:125]
	v_mfma_f32_16x16x32_bf16 v[110:113], v[150:153], v[176:179], v[110:113]
	v_mfma_f32_16x16x32_bf16 v[106:109], v[160:163], v[176:179], v[106:109]
	v_mfma_f32_16x16x32_bf16 v[94:97], v[150:153], v[184:187], v[94:97]
	v_mfma_f32_16x16x32_bf16 v[90:93], v[160:163], v[184:187], v[90:93]
	v_mfma_f32_16x16x32_bf16 v[78:81], v[150:153], v[192:195], v[78:81]
	v_mfma_f32_16x16x32_bf16 v[74:77], v[160:163], v[192:195], v[74:77]
	v_mfma_f32_16x16x32_bf16 v[118:121], v[196:199], v[164:167], v[118:121]
	v_mfma_f32_16x16x32_bf16 v[114:117], v[204:207], v[164:167], v[114:117]
	v_mfma_f32_16x16x32_bf16 v[102:105], v[196:199], v[172:175], v[102:105]
	v_mfma_f32_16x16x32_bf16 v[98:101], v[204:207], v[172:175], v[98:101]
	v_mfma_f32_16x16x32_bf16 v[86:89], v[196:199], v[180:183], v[86:89]
	v_mfma_f32_16x16x32_bf16 v[82:85], v[204:207], v[180:183], v[82:85]
	v_mfma_f32_16x16x32_bf16 v[70:73], v[196:199], v[188:191], v[70:73]
	v_mfma_f32_16x16x32_bf16 v[66:69], v[204:207], v[188:191], v[66:69]
	v_mfma_f32_16x16x32_bf16 v[118:121], v[200:203], v[168:171], v[118:121]
	v_mfma_f32_16x16x32_bf16 v[114:117], v[210:213], v[168:171], v[114:117]
	v_mfma_f32_16x16x32_bf16 v[102:105], v[200:203], v[176:179], v[102:105]
	v_mfma_f32_16x16x32_bf16 v[98:101], v[210:213], v[176:179], v[98:101]
	v_mfma_f32_16x16x32_bf16 v[86:89], v[200:203], v[184:187], v[86:89]
	v_mfma_f32_16x16x32_bf16 v[82:85], v[210:213], v[184:187], v[82:85]
	v_mfma_f32_16x16x32_bf16 v[70:73], v[200:203], v[192:195], v[70:73]
	v_mfma_f32_16x16x32_bf16 v[66:69], v[210:213], v[192:195], v[66:69]
	s_barrier
	s_add_i32 s38, s74, s56
	s_add_u32 s100, s48, s36
	s_addc_u32 s101, s49, s37
	s_mov_b32 m0, s38
	ds_read_b128 v[164:167], v145 offset:49152
	global_load_lds_dwordx4 v0, s[100:101]
	s_add_i32 m0, s38, 0x2000
	ds_read_b128 v[168:171], v145 offset:50176
	global_load_lds_dwordx4 v130, s[100:101]
	s_mov_b32 m0, s64
	s_add_u32 s100, s50, s36
	s_addc_u32 s101, s51, s37
	global_load_lds_dwordx4 v134, s[100:101]
	s_mov_b32 m0, s65
	ds_read_b128 v[172:175], v145 offset:51200
	global_load_lds_dwordx4 v132, s[100:101]
	ds_read_b128 v[176:179], v145 offset:52224
	ds_read_b128 v[180:183], v145 offset:53248
	ds_read_b128 v[184:187], v145 offset:54272
	ds_read_b128 v[188:191], v145 offset:55296
	ds_read_b128 v[192:195], v145 offset:56320
	s_waitcnt vmcnt(4)
	s_waitcnt lgkmcnt(0)
	s_barrier
	v_mfma_f32_16x16x32_bf16 v[62:65], v[146:149], v[164:167], v[62:65]
	v_mfma_f32_16x16x32_bf16 v[58:61], v[154:157], v[164:167], v[58:61]
	v_mfma_f32_16x16x32_bf16 v[46:49], v[146:149], v[172:175], v[46:49]
	v_mfma_f32_16x16x32_bf16 v[42:45], v[154:157], v[172:175], v[42:45]
	v_mfma_f32_16x16x32_bf16 v[30:33], v[146:149], v[180:183], v[30:33]
	v_mfma_f32_16x16x32_bf16 v[26:29], v[154:157], v[180:183], v[26:29]
	v_mfma_f32_16x16x32_bf16 v[14:17], v[146:149], v[188:191], v[14:17]
	v_mfma_f32_16x16x32_bf16 v[10:13], v[154:157], v[188:191], v[10:13]
	v_mfma_f32_16x16x32_bf16 v[62:65], v[150:153], v[168:171], v[62:65]
	v_mfma_f32_16x16x32_bf16 v[58:61], v[160:163], v[168:171], v[58:61]
	v_mfma_f32_16x16x32_bf16 v[46:49], v[150:153], v[176:179], v[46:49]
	v_mfma_f32_16x16x32_bf16 v[42:45], v[160:163], v[176:179], v[42:45]
	v_mfma_f32_16x16x32_bf16 v[30:33], v[150:153], v[184:187], v[30:33]
	v_mfma_f32_16x16x32_bf16 v[26:29], v[160:163], v[184:187], v[26:29]
	v_mfma_f32_16x16x32_bf16 v[14:17], v[150:153], v[192:195], v[14:17]
	v_mfma_f32_16x16x32_bf16 v[10:13], v[160:163], v[192:195], v[10:13]
	s_add_u32 s38, s48, 0x80080
	s_addc_u32 s39, s49, 0
	s_add_i32 s48, s56, 0x1c000
	s_mov_b32 m0, s48
	s_nop 0
	global_load_lds_dwordx4 v0, s[38:39]
	s_add_i32 m0, s48, 0x2000
	s_nop 0
	global_load_lds_dwordx4 v130, s[38:39]
	v_mfma_f32_16x16x32_bf16 v[54:57], v[196:199], v[164:167], v[54:57]
	v_mfma_f32_16x16x32_bf16 v[50:53], v[204:207], v[164:167], v[50:53]
	v_mfma_f32_16x16x32_bf16 v[38:41], v[196:199], v[172:175], v[38:41]
	v_mfma_f32_16x16x32_bf16 v[34:37], v[204:207], v[172:175], v[34:37]
	v_mfma_f32_16x16x32_bf16 v[22:25], v[196:199], v[180:183], v[22:25]
	v_mfma_f32_16x16x32_bf16 v[18:21], v[204:207], v[180:183], v[18:21]
	v_mfma_f32_16x16x32_bf16 v[6:9], v[196:199], v[188:191], v[6:9]
	v_mfma_f32_16x16x32_bf16 v[2:5], v[204:207], v[188:191], v[2:5]
	v_mfma_f32_16x16x32_bf16 v[54:57], v[200:203], v[168:171], v[54:57]
	v_mfma_f32_16x16x32_bf16 v[50:53], v[210:213], v[168:171], v[50:53]
	v_mfma_f32_16x16x32_bf16 v[38:41], v[200:203], v[176:179], v[38:41]
	v_mfma_f32_16x16x32_bf16 v[34:37], v[210:213], v[176:179], v[34:37]
	v_mfma_f32_16x16x32_bf16 v[22:25], v[200:203], v[184:187], v[22:25]
	v_mfma_f32_16x16x32_bf16 v[18:21], v[210:213], v[184:187], v[18:21]
	v_mfma_f32_16x16x32_bf16 v[6:9], v[200:203], v[192:195], v[6:9]
	v_mfma_f32_16x16x32_bf16 v[2:5], v[210:213], v[192:195], v[2:5]
	s_cmp_gt_i32 s73, 27
	s_barrier
; __device__ __forceinline__ unsigned cvt_pk_bf16(float lo, float hi) { unsigned r; asm("v_cvt_pk_bf16_f32 %0, %1, %2" : "=v"(r) : "v"(lo), "v"(hi)); return r; }
; #define PG8_MMA(ai, bj, At, Bt) do { __builtin_amdgcn_s_setprio(1); _Pragma("unroll") for (int m = 0; m < 4; ++m) _Pragma("unroll") for (int n = 0; n < 2; ++n) _Pragma("unroll") for (int k = 0; k < 2; ++k) \
;         acc[ai][bj][m][n] = __builtin_amdgcn_mfma_f32_16x16x32_bf16(Bt[n][k], At[m][k], acc[ai][bj][m][n], 0, 0, 0); __builtin_amdgcn_s_setprio(0); } while (0)
; #define PG8_WAIT_V(n) asm volatile("s_waitcnt vmcnt(" #n ")" ::: "memory")
; #define PG8_BAR __builtin_amdgcn_s_barrier()
;     __device__ __forceinline__ void operator()(const f32x4 (&acc)[2][2][4][2], const Unit& u, int wr, int wc, int fr, int fq) const {
;         const int row0 = u.pm * BM + wr * 64 + fr, col0 = u.pn * BM + wc * 32 + 8 * fq;
; #pragma unroll
;         for (int ai = 0; ai < 2; ++ai)
; #pragma unroll
;             for (int m = 0; m < 4; ++m) { bf16_t* rowp = O + (size_t)(row0 + ai * HALF + m * 16) * ldc + col0;
; #pragma unroll
;                 for (int bj = 0; bj < 2; ++bj) { f32x4 v0 = acc[ai][bj][m][0], v1 = acc[ai][bj][m][1];
;                     if (ACT == 1) {
; #pragma unroll
;                         for (int j = 0; j < 4; ++j) { float a = fmaxf(v0[j], 0.f), b = fmaxf(v1[j], 0.f); v0[j] = a * a; v1[j] = b * b; } }
;                     u32x4 w; w.x = cvt_pk_bf16(v0[0], v0[1]); w.y = cvt_pk_bf16(v0[2], v0[3]); w.z = cvt_pk_bf16(v1[0], v1[1]); w.w = cvt_pk_bf16(v1[2], v1[3]);
;                     if (ACT == 1) __builtin_nontemporal_store(w, (u32x4*)(rowp + bj * HALF));
;                     else *(u32x4*)(rowp + bj * HALF) = w; } }
;     }
; template <class Epi, class Sched>
; __device__ __forceinline__ void gemm_phase(LAS unsigned char* lds, const Gemm g, const Sched& S, const Epi& E) {
;     ...
;             PG8_WAIT_V(6); PG8_BAR; PG8_MMA(1, 1, At, B1); PG8_BAR;
	s_cbranch_scc0 .LBB0_73
	v_lshl_add_u32 v146, s8, 8, v142
	v_max_f32_e32 v122, v122, v122
	v_ashrrev_i32_e32 v147, 31, v146
	v_max_f32_e32 v122, 0, v122
	v_max_f32_e32 v123, v123, v123
	v_max_f32_e32 v124, v124, v124
	v_lshl_or_b32 v140, s68, 8, v144
	v_lshlrev_b64 v[148:149], 14, v[146:147]
	v_mul_f32_e32 v147, v122, v122
	v_max_f32_e32 v122, v127, v127
	v_max_f32_e32 v123, 0, v123
	v_max_f32_e32 v124, 0, v124
	v_ashrrev_i32_e32 v141, 31, v140
	v_max_f32_e32 v126, v126, v126
	v_max_f32_e32 v122, 0, v122
	v_mul_f32_e32 v127, v123, v123
	v_max_f32_e32 v123, v128, v128
	v_mul_f32_e32 v128, v124, v124
	v_max_f32_e32 v124, v129, v129
	v_max_f32_e32 v125, v125, v125
	v_lshl_add_u64 v[148:149], s[24:25], 0, v[148:149]
	v_lshlrev_b64 v[150:151], 1, v[140:141]
	v_max_f32_e32 v126, 0, v126
	v_mul_f32_e32 v122, v122, v122
	v_max_f32_e32 v123, 0, v123
	v_max_f32_e32 v124, 0, v124
	v_max_f32_e32 v125, 0, v125
	v_max_f32_e32 v114, v114, v114
	v_lshl_add_u64 v[140:141], v[148:149], 0, v[150:151]
	v_mul_f32_e32 v126, v126, v126
	v_mul_f32_e32 v123, v123, v123
	v_mul_f32_e32 v124, v124, v124
	v_mul_f32_e32 v125, v125, v125
	v_cvt_pk_bf16_f32 v122, v126, v122
	v_max_f32_e32 v114, 0, v114
	v_max_f32_e32 v115, v115, v115
	v_max_f32_e32 v116, v116, v116
	v_cvt_pk_bf16_f32 v123, v123, v124
	v_cvt_pk_bf16_f32 v124, v147, v127
	v_cvt_pk_bf16_f32 v125, v128, v125
	global_store_dwordx4 v[140:141], v[122:125], off nt
	v_max_f32_e32 v115, 0, v115
	v_max_f32_e32 v116, 0, v116
	v_mul_f32_e32 v122, v114, v114
	v_max_f32_e32 v114, v119, v119
	v_max_f32_e32 v118, v118, v118
	v_max_f32_e32 v114, 0, v114
	v_mul_f32_e32 v119, v115, v115
	v_max_f32_e32 v115, v120, v120
	v_mul_f32_e32 v120, v116, v116
	v_max_f32_e32 v116, v121, v121
	v_max_f32_e32 v117, v117, v117
	v_max_f32_e32 v118, 0, v118
	v_mul_f32_e32 v114, v114, v114
	v_max_f32_e32 v115, 0, v115
	v_max_f32_e32 v116, 0, v116
	v_max_f32_e32 v117, 0, v117
	v_mul_f32_e32 v118, v118, v118
	v_mul_f32_e32 v115, v115, v115
	v_mul_f32_e32 v116, v116, v116
	v_mul_f32_e32 v117, v117, v117
	v_cvt_pk_bf16_f32 v114, v118, v114
	v_max_f32_e32 v106, v106, v106
	v_cvt_pk_bf16_f32 v115, v115, v116
	v_cvt_pk_bf16_f32 v116, v122, v119
	v_cvt_pk_bf16_f32 v117, v120, v117
	global_store_dwordx4 v[140:141], v[114:117], off offset:256 nt
	v_max_f32_e32 v106, 0, v106
	v_max_f32_e32 v107, v107, v107
	v_or_b32_e32 v114, 16, v146
	v_max_f32_e32 v108, v108, v108
	v_ashrrev_i32_e32 v115, 31, v114
	v_mul_f32_e32 v116, v106, v106
	v_max_f32_e32 v106, v111, v111
	v_max_f32_e32 v107, 0, v107
	v_max_f32_e32 v108, 0, v108
	v_lshlrev_b64 v[114:115], 14, v[114:115]
	v_max_f32_e32 v110, v110, v110
	v_max_f32_e32 v106, 0, v106
	v_mul_f32_e32 v111, v107, v107
	v_max_f32_e32 v107, v112, v112
	v_mul_f32_e32 v112, v108, v108
	v_max_f32_e32 v108, v113, v113
	v_max_f32_e32 v109, v109, v109
	v_lshl_add_u64 v[114:115], s[24:25], 0, v[114:115]
	v_max_f32_e32 v110, 0, v110
	v_mul_f32_e32 v106, v106, v106
	v_max_f32_e32 v107, 0, v107
	v_max_f32_e32 v108, 0, v108
	v_max_f32_e32 v109, 0, v109
	v_max_f32_e32 v98, v98, v98
	v_lshl_add_u64 v[114:115], v[114:115], 0, v[150:151]
	v_mul_f32_e32 v110, v110, v110
	v_mul_f32_e32 v107, v107, v107
	v_mul_f32_e32 v108, v108, v108
	v_mul_f32_e32 v109, v109, v109
	v_cvt_pk_bf16_f32 v106, v110, v106
	v_max_f32_e32 v98, 0, v98
	v_max_f32_e32 v99, v99, v99
	v_max_f32_e32 v100, v100, v100
	v_cvt_pk_bf16_f32 v107, v107, v108
	v_cvt_pk_bf16_f32 v108, v116, v111
	v_cvt_pk_bf16_f32 v109, v112, v109
	global_store_dwordx4 v[114:115], v[106:109], off nt
	v_max_f32_e32 v99, 0, v99
	v_max_f32_e32 v100, 0, v100
	v_mul_f32_e32 v106, v98, v98
	v_max_f32_e32 v98, v103, v103
	v_max_f32_e32 v102, v102, v102
	v_max_f32_e32 v98, 0, v98
	v_mul_f32_e32 v103, v99, v99
	v_max_f32_e32 v99, v104, v104
	v_mul_f32_e32 v104, v100, v100
	v_max_f32_e32 v100, v105, v105
	v_max_f32_e32 v101, v101, v101
	v_max_f32_e32 v102, 0, v102
	v_mul_f32_e32 v98, v98, v98
	v_max_f32_e32 v99, 0, v99
	v_max_f32_e32 v100, 0, v100
	v_max_f32_e32 v101, 0, v101
	v_mul_f32_e32 v102, v102, v102
	v_mul_f32_e32 v99, v99, v99
	v_mul_f32_e32 v100, v100, v100
	v_mul_f32_e32 v101, v101, v101
	v_cvt_pk_bf16_f32 v98, v102, v98
	v_max_f32_e32 v90, v90, v90
	v_cvt_pk_bf16_f32 v99, v99, v100
	v_cvt_pk_bf16_f32 v100, v106, v103
	v_cvt_pk_bf16_f32 v101, v104, v101
	global_store_dwordx4 v[114:115], v[98:101], off offset:256 nt
	v_max_f32_e32 v90, 0, v90
	v_max_f32_e32 v91, v91, v91
	v_or_b32_e32 v98, 32, v146
	v_max_f32_e32 v92, v92, v92
	v_ashrrev_i32_e32 v99, 31, v98
	v_mul_f32_e32 v100, v90, v90
	v_max_f32_e32 v90, v95, v95
	v_max_f32_e32 v91, 0, v91
	v_max_f32_e32 v92, 0, v92
	v_lshlrev_b64 v[98:99], 14, v[98:99]
	v_max_f32_e32 v94, v94, v94
	v_max_f32_e32 v90, 0, v90
	v_mul_f32_e32 v95, v91, v91
	v_max_f32_e32 v91, v96, v96
	v_mul_f32_e32 v96, v92, v92
	v_max_f32_e32 v92, v97, v97
	v_max_f32_e32 v93, v93, v93
	v_lshl_add_u64 v[98:99], s[24:25], 0, v[98:99]
	v_max_f32_e32 v94, 0, v94
	v_mul_f32_e32 v90, v90, v90
	v_max_f32_e32 v91, 0, v91
	v_max_f32_e32 v92, 0, v92
	v_max_f32_e32 v93, 0, v93
	v_max_f32_e32 v82, v82, v82
	v_lshl_add_u64 v[98:99], v[98:99], 0, v[150:151]
	v_mul_f32_e32 v94, v94, v94
	v_mul_f32_e32 v91, v91, v91
	v_mul_f32_e32 v92, v92, v92
	v_mul_f32_e32 v93, v93, v93
	v_cvt_pk_bf16_f32 v90, v94, v90
	v_max_f32_e32 v82, 0, v82
	v_max_f32_e32 v83, v83, v83
	v_max_f32_e32 v84, v84, v84
	v_cvt_pk_bf16_f32 v91, v91, v92
	v_cvt_pk_bf16_f32 v92, v100, v95
	v_cvt_pk_bf16_f32 v93, v96, v93
	global_store_dwordx4 v[98:99], v[90:93], off nt
	v_max_f32_e32 v83, 0, v83
	v_max_f32_e32 v84, 0, v84
	v_mul_f32_e32 v90, v82, v82
	v_max_f32_e32 v82, v87, v87
	v_max_f32_e32 v86, v86, v86
; __device__ __forceinline__ unsigned cvt_pk_bf16(float lo, float hi) { unsigned r; asm("v_cvt_pk_bf16_f32 %0, %1, %2" : "=v"(r) : "v"(lo), "v"(hi)); return r; }
;     __device__ __forceinline__ void operator()(const f32x4 (&acc)[2][2][4][2], const Unit& u, int wr, int wc, int fr, int fq) const {
;         const int row0 = u.pm * BM + wr * 64 + fr, col0 = u.pn * BM + wc * 32 + 8 * fq;
; #pragma unroll
;         for (int ai = 0; ai < 2; ++ai)
; #pragma unroll
;             for (int m = 0; m < 4; ++m) { bf16_t* rowp = O + (size_t)(row0 + ai * HALF + m * 16) * ldc + col0;
; #pragma unroll
;                 for (int bj = 0; bj < 2; ++bj) { f32x4 v0 = acc[ai][bj][m][0], v1 = acc[ai][bj][m][1];
;                     if (ACT == 1) {
; #pragma unroll
;                         for (int j = 0; j < 4; ++j) { float a = fmaxf(v0[j], 0.f), b = fmaxf(v1[j], 0.f); v0[j] = a * a; v1[j] = b * b; } }
;                     u32x4 w; w.x = cvt_pk_bf16(v0[0], v0[1]); w.y = cvt_pk_bf16(v0[2], v0[3]); w.z = cvt_pk_bf16(v1[0], v1[1]); w.w = cvt_pk_bf16(v1[2], v1[3]);
;                     if (ACT == 1) __builtin_nontemporal_store(w, (u32x4*)(rowp + bj * HALF));
;                     else *(u32x4*)(rowp + bj * HALF) = w; } }
;     }
	v_max_f32_e32 v82, 0, v82
	v_mul_f32_e32 v87, v83, v83
	v_max_f32_e32 v83, v88, v88
	v_mul_f32_e32 v88, v84, v84
	v_max_f32_e32 v84, v89, v89
	v_max_f32_e32 v85, v85, v85
	v_max_f32_e32 v86, 0, v86
	v_mul_f32_e32 v82, v82, v82
	v_max_f32_e32 v83, 0, v83
	v_max_f32_e32 v84, 0, v84
	v_max_f32_e32 v85, 0, v85
	v_mul_f32_e32 v86, v86, v86
	v_mul_f32_e32 v83, v83, v83
	v_mul_f32_e32 v84, v84, v84
	v_mul_f32_e32 v85, v85, v85
	v_cvt_pk_bf16_f32 v82, v86, v82
	v_max_f32_e32 v74, v74, v74
	v_cvt_pk_bf16_f32 v83, v83, v84
	v_cvt_pk_bf16_f32 v84, v90, v87
	v_cvt_pk_bf16_f32 v85, v88, v85
	global_store_dwordx4 v[98:99], v[82:85], off offset:256 nt
	v_max_f32_e32 v74, 0, v74
	v_max_f32_e32 v75, v75, v75
	v_or_b32_e32 v82, 48, v146
	v_max_f32_e32 v76, v76, v76
	v_ashrrev_i32_e32 v83, 31, v82
	v_mul_f32_e32 v84, v74, v74
	v_max_f32_e32 v74, v79, v79
	v_max_f32_e32 v75, 0, v75
	v_max_f32_e32 v76, 0, v76
	v_lshlrev_b64 v[82:83], 14, v[82:83]
	v_max_f32_e32 v78, v78, v78
	v_max_f32_e32 v74, 0, v74
	v_mul_f32_e32 v79, v75, v75
	v_max_f32_e32 v75, v80, v80
	v_mul_f32_e32 v80, v76, v76
	v_max_f32_e32 v76, v81, v81
	v_max_f32_e32 v77, v77, v77
	v_lshl_add_u64 v[82:83], s[24:25], 0, v[82:83]
	v_max_f32_e32 v78, 0, v78
	v_mul_f32_e32 v74, v74, v74
	v_max_f32_e32 v75, 0, v75
	v_max_f32_e32 v76, 0, v76
	v_max_f32_e32 v77, 0, v77
	v_max_f32_e32 v66, v66, v66
	v_max_f32_e32 v67, v67, v67
	v_max_f32_e32 v68, v68, v68
	v_lshl_add_u64 v[82:83], v[82:83], 0, v[150:151]
	v_mul_f32_e32 v78, v78, v78
	v_mul_f32_e32 v75, v75, v75
	v_mul_f32_e32 v76, v76, v76
	v_mul_f32_e32 v77, v77, v77
	v_cvt_pk_bf16_f32 v74, v78, v74
	v_max_f32_e32 v66, 0, v66
	v_max_f32_e32 v67, 0, v67
	v_max_f32_e32 v68, 0, v68
	v_cvt_pk_bf16_f32 v75, v75, v76
	v_cvt_pk_bf16_f32 v76, v84, v79
	v_cvt_pk_bf16_f32 v77, v80, v77
	global_store_dwordx4 v[82:83], v[74:77], off nt
	v_max_f32_e32 v69, v69, v69
	v_max_f32_e32 v70, v70, v70
	v_mul_f32_e32 v74, v66, v66
	v_max_f32_e32 v66, v71, v71
	v_mul_f32_e32 v71, v67, v67
	v_max_f32_e32 v67, v72, v72
	v_mul_f32_e32 v72, v68, v68
	v_max_f32_e32 v68, v73, v73
	v_max_f32_e32 v67, 0, v67
	v_max_f32_e32 v68, 0, v68
	v_max_f32_e32 v66, 0, v66
	v_mul_f32_e32 v67, v67, v67
	v_max_f32_e32 v69, 0, v69
	v_mul_f32_e32 v68, v68, v68
	v_max_f32_e32 v58, v58, v58
	v_max_f32_e32 v70, 0, v70
	v_mul_f32_e32 v66, v66, v66
	v_mul_f32_e32 v69, v69, v69
	v_cvt_pk_bf16_f32 v67, v67, v68
	v_cvt_pk_bf16_f32 v68, v74, v71
	v_max_f32_e32 v58, 0, v58
	v_max_f32_e32 v59, v59, v59
	v_max_f32_e32 v60, v60, v60
	v_mul_f32_e32 v70, v70, v70
	v_cvt_pk_bf16_f32 v66, v70, v66
	v_cvt_pk_bf16_f32 v69, v72, v69
	global_store_dwordx4 v[82:83], v[66:69], off offset:256 nt
	v_max_f32_e32 v62, v62, v62
	v_max_f32_e32 v59, 0, v59
	v_mul_f32_e32 v68, v58, v58
	v_max_f32_e32 v58, v63, v63
	v_max_f32_e32 v60, 0, v60
	v_max_f32_e32 v62, 0, v62
	v_max_f32_e32 v58, 0, v58
	v_mul_f32_e32 v63, v59, v59
	v_max_f32_e32 v59, v64, v64
	v_mul_f32_e32 v64, v60, v60
	v_max_f32_e32 v60, v65, v65
	v_mul_f32_e32 v62, v62, v62
	v_mul_f32_e32 v58, v58, v58
	v_max_f32_e32 v59, 0, v59
	v_max_f32_e32 v60, 0, v60
	v_max_f32_e32 v61, v61, v61
	s_mov_b32 s8, 0x200000
	v_mul_f32_e32 v59, v59, v59
	v_max_f32_e32 v61, 0, v61
	v_mul_f32_e32 v60, v60, v60
	v_cvt_pk_bf16_f32 v58, v62, v58
	v_add_co_u32_e32 v62, vcc, s8, v140
	v_max_f32_e32 v50, v50, v50
	v_max_f32_e32 v51, v51, v51
	v_max_f32_e32 v52, v52, v52
	v_mul_f32_e32 v61, v61, v61
	v_cvt_pk_bf16_f32 v59, v59, v60
	v_cvt_pk_bf16_f32 v60, v68, v63
	v_addc_co_u32_e32 v63, vcc, 0, v141, vcc
	v_max_f32_e32 v50, 0, v50
	v_max_f32_e32 v51, 0, v51
	v_max_f32_e32 v52, 0, v52
	v_cvt_pk_bf16_f32 v61, v64, v61
	global_store_dwordx4 v[62:63], v[58:61], off nt
	v_max_f32_e32 v53, v53, v53
	s_mov_b64 s[38:39], 0x200000
	v_mul_f32_e32 v58, v50, v50
	v_max_f32_e32 v50, v55, v55
	v_mul_f32_e32 v55, v51, v51
	v_max_f32_e32 v51, v56, v56
	v_mul_f32_e32 v56, v52, v52
	v_max_f32_e32 v52, v57, v57
	v_max_f32_e32 v51, 0, v51
	v_max_f32_e32 v52, 0, v52
	v_max_f32_e32 v54, v54, v54
	v_max_f32_e32 v50, 0, v50
	v_mul_f32_e32 v51, v51, v51
	v_max_f32_e32 v53, 0, v53
	v_mul_f32_e32 v52, v52, v52
	v_max_f32_e32 v42, v42, v42
	v_lshl_add_u64 v[66:67], v[140:141], 0, s[38:39]
	v_max_f32_e32 v54, 0, v54
	v_mul_f32_e32 v50, v50, v50
	v_mul_f32_e32 v53, v53, v53
	v_cvt_pk_bf16_f32 v51, v51, v52
	v_cvt_pk_bf16_f32 v52, v58, v55
	v_max_f32_e32 v42, 0, v42
	v_max_f32_e32 v43, v43, v43
	v_max_f32_e32 v44, v44, v44
	v_mul_f32_e32 v54, v54, v54
	v_cvt_pk_bf16_f32 v50, v54, v50
	v_cvt_pk_bf16_f32 v53, v56, v53
	global_store_dwordx4 v[66:67], v[50:53], off offset:256 nt
	v_max_f32_e32 v46, v46, v46
	v_max_f32_e32 v43, 0, v43
	v_mul_f32_e32 v52, v42, v42
	v_max_f32_e32 v42, v47, v47
	v_max_f32_e32 v44, 0, v44
	v_max_f32_e32 v46, 0, v46
	v_max_f32_e32 v42, 0, v42
	v_mul_f32_e32 v47, v43, v43
	v_max_f32_e32 v43, v48, v48
	v_mul_f32_e32 v48, v44, v44
	v_max_f32_e32 v44, v49, v49
	v_mul_f32_e32 v46, v46, v46
	v_mul_f32_e32 v42, v42, v42
	v_max_f32_e32 v43, 0, v43
	v_max_f32_e32 v44, 0, v44
	v_max_f32_e32 v45, v45, v45
	s_mov_b32 s8, 0x240000
	v_mul_f32_e32 v43, v43, v43
	v_max_f32_e32 v45, 0, v45
	v_mul_f32_e32 v44, v44, v44
	v_cvt_pk_bf16_f32 v42, v46, v42
; __device__ __forceinline__ unsigned cvt_pk_bf16(float lo, float hi) { unsigned r; asm("v_cvt_pk_bf16_f32 %0, %1, %2" : "=v"(r) : "v"(lo), "v"(hi)); return r; }
;     __device__ __forceinline__ void operator()(const f32x4 (&acc)[2][2][4][2], const Unit& u, int wr, int wc, int fr, int fq) const {
;     ...
;             for (int m = 0; m < 4; ++m) { bf16_t* rowp = O + (size_t)(row0 + ai * HALF + m * 16) * ldc + col0;
; #pragma unroll
;                 for (int bj = 0; bj < 2; ++bj) { f32x4 v0 = acc[ai][bj][m][0], v1 = acc[ai][bj][m][1];
;                     if (ACT == 1) {
; #pragma unroll
;                         for (int j = 0; j < 4; ++j) { float a = fmaxf(v0[j], 0.f), b = fmaxf(v1[j], 0.f); v0[j] = a * a; v1[j] = b * b; } }
;                     u32x4 w; w.x = cvt_pk_bf16(v0[0], v0[1]); w.y = cvt_pk_bf16(v0[2], v0[3]); w.z = cvt_pk_bf16(v1[0], v1[1]); w.w = cvt_pk_bf16(v1[2], v1[3]);
;                     if (ACT == 1) __builtin_nontemporal_store(w, (u32x4*)(rowp + bj * HALF));
;                     else *(u32x4*)(rowp + bj * HALF) = w; } }
	v_add_co_u32_e32 v46, vcc, s8, v140
	v_max_f32_e32 v34, v34, v34
	v_max_f32_e32 v35, v35, v35
	v_max_f32_e32 v36, v36, v36
	v_mul_f32_e32 v45, v45, v45
	v_cvt_pk_bf16_f32 v43, v43, v44
	v_cvt_pk_bf16_f32 v44, v52, v47
	v_addc_co_u32_e32 v47, vcc, 0, v141, vcc
	v_max_f32_e32 v34, 0, v34
	v_max_f32_e32 v35, 0, v35
	v_max_f32_e32 v36, 0, v36
	v_cvt_pk_bf16_f32 v45, v48, v45
	global_store_dwordx4 v[46:47], v[42:45], off nt
	v_max_f32_e32 v37, v37, v37
	s_mov_b64 s[38:39], 0x240000
	v_mul_f32_e32 v42, v34, v34
	v_max_f32_e32 v34, v39, v39
	v_mul_f32_e32 v39, v35, v35
	v_max_f32_e32 v35, v40, v40
	v_mul_f32_e32 v40, v36, v36
	v_max_f32_e32 v36, v41, v41
	v_max_f32_e32 v35, 0, v35
	v_max_f32_e32 v36, 0, v36
	v_max_f32_e32 v38, v38, v38
	v_max_f32_e32 v34, 0, v34
	v_mul_f32_e32 v35, v35, v35
	v_max_f32_e32 v37, 0, v37
	v_mul_f32_e32 v36, v36, v36
	v_max_f32_e32 v26, v26, v26
	v_lshl_add_u64 v[50:51], v[140:141], 0, s[38:39]
	v_max_f32_e32 v38, 0, v38
	v_mul_f32_e32 v34, v34, v34
	v_mul_f32_e32 v37, v37, v37
	v_cvt_pk_bf16_f32 v35, v35, v36
	v_cvt_pk_bf16_f32 v36, v42, v39
	v_max_f32_e32 v26, 0, v26
	v_max_f32_e32 v27, v27, v27
	v_max_f32_e32 v28, v28, v28
	v_mul_f32_e32 v38, v38, v38
	v_cvt_pk_bf16_f32 v34, v38, v34
	v_cvt_pk_bf16_f32 v37, v40, v37
	global_store_dwordx4 v[50:51], v[34:37], off offset:256 nt
	v_max_f32_e32 v30, v30, v30
	v_max_f32_e32 v27, 0, v27
	v_mul_f32_e32 v36, v26, v26
	v_max_f32_e32 v26, v31, v31
	v_max_f32_e32 v28, 0, v28
	v_max_f32_e32 v30, 0, v30
	v_max_f32_e32 v26, 0, v26
	v_mul_f32_e32 v31, v27, v27
	v_max_f32_e32 v27, v32, v32
	v_mul_f32_e32 v32, v28, v28
	v_max_f32_e32 v28, v33, v33
	v_mul_f32_e32 v30, v30, v30
	v_mul_f32_e32 v26, v26, v26
	v_max_f32_e32 v27, 0, v27
	v_max_f32_e32 v28, 0, v28
	v_max_f32_e32 v29, v29, v29
	s_mov_b32 s8, 0x280000
	v_mul_f32_e32 v27, v27, v27
	v_max_f32_e32 v29, 0, v29
	v_mul_f32_e32 v28, v28, v28
	v_cvt_pk_bf16_f32 v26, v30, v26
	v_add_co_u32_e32 v30, vcc, s8, v140
	v_max_f32_e32 v18, v18, v18
	v_max_f32_e32 v19, v19, v19
	v_max_f32_e32 v20, v20, v20
	v_mul_f32_e32 v29, v29, v29
	v_cvt_pk_bf16_f32 v27, v27, v28
	v_cvt_pk_bf16_f32 v28, v36, v31
	v_addc_co_u32_e32 v31, vcc, 0, v141, vcc
	v_max_f32_e32 v18, 0, v18
	v_max_f32_e32 v19, 0, v19
	v_max_f32_e32 v20, 0, v20
	v_cvt_pk_bf16_f32 v29, v32, v29
	global_store_dwordx4 v[30:31], v[26:29], off nt
	v_max_f32_e32 v21, v21, v21
	s_mov_b64 s[38:39], 0x280000
	v_mul_f32_e32 v26, v18, v18
	v_max_f32_e32 v18, v23, v23
	v_mul_f32_e32 v23, v19, v19
	v_max_f32_e32 v19, v24, v24
	v_mul_f32_e32 v24, v20, v20
	v_max_f32_e32 v20, v25, v25
	v_max_f32_e32 v19, 0, v19
	v_max_f32_e32 v20, 0, v20
	v_max_f32_e32 v22, v22, v22
	v_max_f32_e32 v18, 0, v18
	v_mul_f32_e32 v19, v19, v19
	v_max_f32_e32 v21, 0, v21
	v_mul_f32_e32 v20, v20, v20
	v_max_f32_e32 v10, v10, v10
	v_lshl_add_u64 v[34:35], v[140:141], 0, s[38:39]
	v_max_f32_e32 v22, 0, v22
	v_mul_f32_e32 v18, v18, v18
	v_mul_f32_e32 v21, v21, v21
	v_cvt_pk_bf16_f32 v19, v19, v20
	v_cvt_pk_bf16_f32 v20, v26, v23
	v_max_f32_e32 v10, 0, v10
	v_max_f32_e32 v11, v11, v11
	v_max_f32_e32 v12, v12, v12
	v_mul_f32_e32 v22, v22, v22
	v_cvt_pk_bf16_f32 v18, v22, v18
	v_cvt_pk_bf16_f32 v21, v24, v21
	global_store_dwordx4 v[34:35], v[18:21], off offset:256 nt
	v_max_f32_e32 v14, v14, v14
	v_max_f32_e32 v11, 0, v11
	v_mul_f32_e32 v20, v10, v10
	v_max_f32_e32 v10, v15, v15
	v_max_f32_e32 v12, 0, v12
	v_max_f32_e32 v14, 0, v14
	v_max_f32_e32 v10, 0, v10
	v_mul_f32_e32 v15, v11, v11
	v_max_f32_e32 v11, v16, v16
	v_mul_f32_e32 v16, v12, v12
	v_max_f32_e32 v12, v17, v17
	v_mul_f32_e32 v14, v14, v14
	v_mul_f32_e32 v10, v10, v10
	v_max_f32_e32 v11, 0, v11
	v_max_f32_e32 v12, 0, v12
	v_max_f32_e32 v13, v13, v13
	s_mov_b32 s8, 0x2c0000
	v_mul_f32_e32 v11, v11, v11
	v_max_f32_e32 v13, 0, v13
	v_mul_f32_e32 v12, v12, v12
	v_cvt_pk_bf16_f32 v10, v14, v10
	v_add_co_u32_e32 v14, vcc, s8, v140
	v_max_f32_e32 v2, v2, v2
	v_max_f32_e32 v3, v3, v3
	v_max_f32_e32 v4, v4, v4
	v_mul_f32_e32 v13, v13, v13
	v_cvt_pk_bf16_f32 v11, v11, v12
	v_cvt_pk_bf16_f32 v12, v20, v15
	v_addc_co_u32_e32 v15, vcc, 0, v141, vcc
	v_max_f32_e32 v2, 0, v2
	v_max_f32_e32 v3, 0, v3
	v_max_f32_e32 v4, 0, v4
	v_cvt_pk_bf16_f32 v13, v16, v13
	global_store_dwordx4 v[14:15], v[10:13], off nt
	v_max_f32_e32 v5, v5, v5
	s_mov_b64 s[38:39], 0x2c0000
	v_mul_f32_e32 v10, v2, v2
	v_max_f32_e32 v2, v7, v7
	v_mul_f32_e32 v7, v3, v3
	v_max_f32_e32 v3, v8, v8
	v_mul_f32_e32 v8, v4, v4
	v_max_f32_e32 v4, v9, v9
	v_max_f32_e32 v6, v6, v6
	v_max_f32_e32 v2, 0, v2
	v_max_f32_e32 v3, 0, v3
	v_max_f32_e32 v4, 0, v4
	v_max_f32_e32 v5, 0, v5
	v_lshl_add_u64 v[18:19], v[140:141], 0, s[38:39]
	v_max_f32_e32 v6, 0, v6
	v_mul_f32_e32 v2, v2, v2
	v_mul_f32_e32 v3, v3, v3
	v_mul_f32_e32 v4, v4, v4
	v_mul_f32_e32 v5, v5, v5
	s_and_b64 vcc, exec, s[40:41]
	s_mov_b32 s68, s26
	s_mov_b32 s8, s28
	s_mov_b64 s[46:47], s[44:45]
	s_mov_b64 s[48:49], s[42:43]
	v_mul_f32_e32 v6, v6, v6
	v_cvt_pk_bf16_f32 v2, v6, v2
	v_cvt_pk_bf16_f32 v3, v3, v4
	v_cvt_pk_bf16_f32 v4, v10, v7
	v_cvt_pk_bf16_f32 v5, v8, v5
	global_store_dwordx4 v[18:19], v[2:5], off offset:256 nt
	s_cbranch_vccz .LBB0_70
	s_waitcnt vmcnt(0)
	s_cmpk_gt_u32 s52, 0xff
	s_cbranch_scc1 .LBB0_77
	s_barrier

; #define PG8_STAGE(bufoff, gbase, voff) do { _Pragma("unroll") for (int _i = 0; _i < 2; ++_i) \
;         __builtin_amdgcn_global_load_lds((const unsigned*)((const char*)(gbase) + (voff)[_i]), (LAS unsigned*)(lds + (bufoff) + ldsw + _i * 8192), 16, 0, 0); } while (0)
; #define PG8_LDA(dst, b, h) do { _Pragma("unroll") for (int m = 0; m < 4; ++m) _Pragma("unroll") for (int k = 0; k < 2; ++k) dst[m][k] = *(const LAS bf16x8*)(lds + PG8_SA(b, h) + aoff + m * 2048 + k * 1024); } while (0)
; #define PG8_LDB(dst, b, h) do { _Pragma("unroll") for (int n = 0; n < 2; ++n) _Pragma("unroll") for (int k = 0; k < 2; ++k) dst[n][k] = *(const LAS bf16x8*)(lds + PG8_SB(b, h) + boff + n * 2048 + k * 1024); } while (0)
; #define PG8_SCHED __builtin_amdgcn_sched_barrier(0)
; template <class Epi, class Sched>
; __device__ __forceinline__ void gemm_phase(LAS unsigned char* lds, const Gemm g, const Sched& S, const Epi& E) {
;     ...
;         const char* nA = has_next ? (const char*)g.A + (size_t)nxt.pm * tstep + (size_t)nxt.ks * sstep : cA; const char* nB = has_next ? (const char*)g.Bt + (size_t)nxt.pn * tstep + (size_t)nxt.ks * sstep : cB;
;         for (int t = 0; t < nt; t += 2) {
;             const bool last = (t == nt - 2);
;             const char* a1 = cA + (size_t)(t + 1) * kstep;
;             const char* a2 = last ? nA : cA + (size_t)(t + 2) * kstep; const char* b2 = last ? nB : cB + (size_t)(t + 2) * kstep;
;             const char* a3 = a2 + kstep; const char* b3 = b2 + kstep;
;             PG8_LDB(B0, 0, 0); PG8_SCHED; PG8_LDA(At, 0, 0); PG8_STAGE(PG8_SA(1, 1), a1 + hstep, voffA);
;     ...
;         for (int a = 0; a < 2; ++a)
; #pragma unroll
;             for (int b = 0; b < 2; ++b)
; #pragma unroll
;                 for (int m = 0; m < 4; ++m)
; #pragma unroll
;                     for (int n = 0; n < 2; ++n) acc[a][b][m][n] = (f32x4){0.f, 0.f, 0.f, 0.f};
.LBB0_98:
	s_ashr_i32 s51, s50, 31
	s_lshl_b64 s[38:39], s[50:51], 20
	v_cmp_lt_i64_e32 vcc, s[52:53], v[158:159]
	s_add_u32 s52, s10, s38
	s_addc_u32 s53, s11, s39
	s_and_b64 s[38:39], vcc, exec
	s_cselect_b32 s51, s53, s29
	s_cselect_b32 s77, s52, s28
	s_ashr_i32 s49, s48, 31
	s_lshl_b64 s[38:39], s[48:49], 20
	s_add_u32 s54, s13, s38
	s_addc_u32 s55, s62, s39
	s_and_b64 s[38:39], vcc, exec
	s_cselect_b32 s49, s55, s57
	s_cselect_b32 s78, s54, s56
	s_add_u32 s79, s56, 0x100
	v_mov_b32_e32 v2, 0
	s_addc_u32 s80, s57, 0
	s_mov_b32 s81, -2
	v_mov_b32_e32 v3, v2
	v_mov_b32_e32 v4, v2
	v_mov_b32_e32 v5, v2
	v_mov_b32_e32 v6, v2
	v_mov_b32_e32 v7, v2
	v_mov_b32_e32 v8, v2
	v_mov_b32_e32 v9, v2
	v_mov_b32_e32 v10, v2
	v_mov_b32_e32 v11, v2
	v_mov_b32_e32 v12, v2
	v_mov_b32_e32 v13, v2
	v_mov_b32_e32 v14, v2
	v_mov_b32_e32 v15, v2
	v_mov_b32_e32 v16, v2
	v_mov_b32_e32 v17, v2
	v_mov_b32_e32 v34, v2
	v_mov_b32_e32 v35, v2
	v_mov_b32_e32 v36, v2
	v_mov_b32_e32 v37, v2
	v_mov_b32_e32 v38, v2
	v_mov_b32_e32 v39, v2
	v_mov_b32_e32 v40, v2
	v_mov_b32_e32 v41, v2
	v_mov_b32_e32 v50, v2
	v_mov_b32_e32 v51, v2
	v_mov_b32_e32 v52, v2
	v_mov_b32_e32 v53, v2
	v_mov_b32_e32 v54, v2
	v_mov_b32_e32 v55, v2
	v_mov_b32_e32 v56, v2
	v_mov_b32_e32 v57, v2
	v_mov_b32_e32 v18, v2
	v_mov_b32_e32 v19, v2
	v_mov_b32_e32 v20, v2
	v_mov_b32_e32 v21, v2
	s_waitcnt vmcnt(0)
	v_mov_b32_e32 v22, v2
	v_mov_b32_e32 v23, v2
	v_mov_b32_e32 v24, v2
	v_mov_b32_e32 v25, v2
	v_mov_b32_e32 v26, v2
	v_mov_b32_e32 v27, v2
	v_mov_b32_e32 v28, v2
	v_mov_b32_e32 v29, v2
	v_mov_b32_e32 v30, v2
	v_mov_b32_e32 v31, v2
	v_mov_b32_e32 v32, v2
	v_mov_b32_e32 v33, v2
	v_mov_b32_e32 v42, v2
	v_mov_b32_e32 v43, v2
	v_mov_b32_e32 v44, v2
	v_mov_b32_e32 v45, v2
	v_mov_b32_e32 v46, v2
	v_mov_b32_e32 v47, v2
	v_mov_b32_e32 v48, v2
	v_mov_b32_e32 v49, v2
	v_mov_b32_e32 v58, v2
	v_mov_b32_e32 v59, v2
	v_mov_b32_e32 v60, v2
	v_mov_b32_e32 v61, v2
	v_mov_b32_e32 v62, v2
	v_mov_b32_e32 v63, v2
	v_mov_b32_e32 v64, v2
	v_mov_b32_e32 v65, v2
	v_mov_b32_e32 v66, v2
	v_mov_b32_e32 v67, v2
	v_mov_b32_e32 v68, v2
	v_mov_b32_e32 v69, v2
	v_mov_b32_e32 v70, v2
	v_mov_b32_e32 v71, v2
	v_mov_b32_e32 v72, v2
	v_mov_b32_e32 v73, v2
	v_mov_b32_e32 v74, v2
	v_mov_b32_e32 v75, v2
	v_mov_b32_e32 v76, v2
	v_mov_b32_e32 v77, v2
	v_mov_b32_e32 v78, v2
	v_mov_b32_e32 v79, v2
	v_mov_b32_e32 v80, v2
	v_mov_b32_e32 v81, v2
	v_mov_b32_e32 v114, v2
	v_mov_b32_e32 v115, v2
	v_mov_b32_e32 v116, v2
	v_mov_b32_e32 v117, v2
	v_mov_b32_e32 v118, v2
	v_mov_b32_e32 v119, v2
	v_mov_b32_e32 v120, v2
	v_mov_b32_e32 v121, v2
	v_mov_b32_e32 v130, v2
	v_mov_b32_e32 v131, v2
	v_mov_b32_e32 v132, v2
	v_mov_b32_e32 v133, v2
	v_mov_b32_e32 v134, v2
	v_mov_b32_e32 v135, v2
	v_mov_b32_e32 v136, v2
	v_mov_b32_e32 v137, v2
	v_mov_b32_e32 v82, v2
	v_mov_b32_e32 v83, v2
	v_mov_b32_e32 v84, v2
	v_mov_b32_e32 v85, v2
	v_mov_b32_e32 v86, v2
	v_mov_b32_e32 v87, v2
	v_mov_b32_e32 v88, v2
	v_mov_b32_e32 v89, v2
	v_mov_b32_e32 v90, v2
	v_mov_b32_e32 v91, v2
	v_mov_b32_e32 v92, v2
	v_mov_b32_e32 v93, v2
	v_mov_b32_e32 v94, v2
	v_mov_b32_e32 v95, v2
	v_mov_b32_e32 v96, v2
	v_mov_b32_e32 v97, v2
	v_mov_b32_e32 v122, v2
	v_mov_b32_e32 v123, v2
	v_mov_b32_e32 v124, v2
	v_mov_b32_e32 v125, v2
	v_mov_b32_e32 v126, v2
	v_mov_b32_e32 v127, v2
	v_mov_b32_e32 v128, v2
	v_mov_b32_e32 v129, v2
	v_mov_b32_e32 v138, v2
	v_mov_b32_e32 v139, v2
	v_mov_b32_e32 v140, v2
	v_mov_b32_e32 v141, v2
	v_mov_b32_e32 v142, v2
	v_mov_b32_e32 v143, v2
	v_mov_b32_e32 v144, v2
	v_mov_b32_e32 v145, v2
	s_branch .Lent_99
.LBB0_99:
	s_add_i32 s81, s81, 2
	s_add_u32 s79, s79, 0x100
	s_addc_u32 s80, s80, 0
	s_mov_b64 s[28:29], s[56:57]
.Lent_99:
	s_add_u32 s56, s28, 0x100
	s_addc_u32 s57, s29, 0
	s_cmp_eq_u32 s81, 28
	s_cselect_b32 s61, s51, s57
	s_cselect_b32 s60, s77, s56
	s_cselect_b32 s59, s49, s80
	s_cselect_b32 s58, s78, s79
	s_add_i32 m0, s9, 0xc000
	ds_read_b128 v[98:101], v226
	global_load_lds_dwordx4 v150, s[28:29]
	s_add_i32 m0, s9, 0xe000
	ds_read_b128 v[102:105], v226 offset:1024
	global_load_lds_dwordx4 v148, s[28:29]
	s_add_i32 s38, 0, 0x10000
	ds_read_b128 v[106:109], v226 offset:2048
	ds_read_b128 v[110:113], v226 offset:3072
	ds_read_b128 v[152:155], v171
	ds_read_b128 v[160:163], v171 offset:1024
	ds_read_b128 v[164:167], v171 offset:2048
	ds_read_b128 v[172:175], v171 offset:3072
	ds_read_b128 v[176:179], v171 offset:4096
	ds_read_b128 v[180:183], v171 offset:5120
	ds_read_b128 v[184:187], v171 offset:6144
	ds_read_b128 v[188:191], v171 offset:7168
	s_add_i32 s39, 0, 0x14000
	ds_read_b128 v[192:195], v226 offset:16384
	ds_read_b128 v[196:199], v226 offset:17408
	ds_read_b128 v[200:203], v226 offset:18432
	ds_read_b128 v[204:207], v226 offset:19456
	s_waitcnt lgkmcnt(4)
	s_barrier
; #define PG8_STAGE(bufoff, gbase, voff) do { _Pragma("unroll") for (int _i = 0; _i < 2; ++_i) \
;         __builtin_amdgcn_global_load_lds((const unsigned*)((const char*)(gbase) + (voff)[_i]), (LAS unsigned*)(lds + (bufoff) + ldsw + _i * 8192), 16, 0, 0); } while (0)
; #define PG8_LDA(dst, b, h) do { _Pragma("unroll") for (int m = 0; m < 4; ++m) _Pragma("unroll") for (int k = 0; k < 2; ++k) dst[m][k] = *(const LAS bf16x8*)(lds + PG8_SA(b, h) + aoff + m * 2048 + k * 1024); } while (0)
; #define PG8_LDB(dst, b, h) do { _Pragma("unroll") for (int n = 0; n < 2; ++n) _Pragma("unroll") for (int k = 0; k < 2; ++k) dst[n][k] = *(const LAS bf16x8*)(lds + PG8_SB(b, h) + boff + n * 2048 + k * 1024); } while (0)
; #define PG8_MMA(ai, bj, At, Bt) do { __builtin_amdgcn_s_setprio(1); _Pragma("unroll") for (int m = 0; m < 4; ++m) _Pragma("unroll") for (int n = 0; n < 2; ++n) _Pragma("unroll") for (int k = 0; k < 2; ++k) \
;         acc[ai][bj][m][n] = __builtin_amdgcn_mfma_f32_16x16x32_bf16(Bt[n][k], At[m][k], acc[ai][bj][m][n], 0, 0, 0); __builtin_amdgcn_s_setprio(0); } while (0)
; #define PG8_WAIT_V(n) asm volatile("s_waitcnt vmcnt(" #n ")" ::: "memory")
; #define PG8_WAIT_L(n) asm volatile("s_waitcnt lgkmcnt(" #n ")" ::: "memory")
; #define PG8_BAR __builtin_amdgcn_s_barrier()
; #define PG8_SCHED __builtin_amdgcn_sched_barrier(0)
; template <class Epi, class Sched>
; __device__ __forceinline__ void gemm_phase(LAS unsigned char* lds, const Gemm g, const Sched& S, const Epi& E) {
;     ...
;             PG8_LDB(B0, 0, 0); PG8_SCHED; PG8_LDA(At, 0, 0); PG8_STAGE(PG8_SA(1, 1), a1 + hstep, voffA);
;             PG8_WAIT_L(8); PG8_BAR; PG8_WAIT_L(0); PG8_MMA(0, 0, At, B0); PG8_BAR; PG8_SCHED;
;             PG8_LDB(B1, 0, 1); PG8_STAGE(PG8_SB(0, 0), b2, voffB);
;             PG8_BAR; PG8_WAIT_L(0); PG8_MMA(0, 1, At, B1); PG8_BAR;
;             PG8_LDA(At, 0, 1); PG8_STAGE(PG8_SA(0, 0), a2, voffA);
;             PG8_BAR; PG8_WAIT_L(0); PG8_MMA(1, 0, At, B0); PG8_BAR; PG8_SCHED;
;             PG8_STAGE(PG8_SB(0, 1), b2 + hstep, voffB);
;             PG8_WAIT_V(6); PG8_BAR; PG8_MMA(1, 1, At, B1); PG8_BAR;
	s_waitcnt lgkmcnt(0)
	v_mfma_f32_16x16x32_bf16 v[142:145], v[98:101], v[152:155], v[142:145]
	v_mfma_f32_16x16x32_bf16 v[138:141], v[106:109], v[152:155], v[138:141]
	v_mfma_f32_16x16x32_bf16 v[126:129], v[98:101], v[164:167], v[126:129]
	v_mfma_f32_16x16x32_bf16 v[122:125], v[106:109], v[164:167], v[122:125]
	v_mfma_f32_16x16x32_bf16 v[94:97], v[98:101], v[176:179], v[94:97]
	v_mfma_f32_16x16x32_bf16 v[90:93], v[106:109], v[176:179], v[90:93]
	v_mfma_f32_16x16x32_bf16 v[86:89], v[98:101], v[184:187], v[86:89]
	v_mfma_f32_16x16x32_bf16 v[82:85], v[106:109], v[184:187], v[82:85]
	v_mfma_f32_16x16x32_bf16 v[142:145], v[102:105], v[160:163], v[142:145]
	v_mfma_f32_16x16x32_bf16 v[138:141], v[110:113], v[160:163], v[138:141]
	v_mfma_f32_16x16x32_bf16 v[126:129], v[102:105], v[172:175], v[126:129]
	v_mfma_f32_16x16x32_bf16 v[122:125], v[110:113], v[172:175], v[122:125]
	v_mfma_f32_16x16x32_bf16 v[94:97], v[102:105], v[180:183], v[94:97]
	v_mfma_f32_16x16x32_bf16 v[90:93], v[110:113], v[180:183], v[90:93]
	v_mfma_f32_16x16x32_bf16 v[86:89], v[102:105], v[188:191], v[86:89]
	v_mfma_f32_16x16x32_bf16 v[82:85], v[110:113], v[188:191], v[82:85]
	v_mfma_f32_16x16x32_bf16 v[134:137], v[192:195], v[152:155], v[134:137]
	v_mfma_f32_16x16x32_bf16 v[130:133], v[200:203], v[152:155], v[130:133]
	v_mfma_f32_16x16x32_bf16 v[118:121], v[192:195], v[164:167], v[118:121]
	v_mfma_f32_16x16x32_bf16 v[114:117], v[200:203], v[164:167], v[114:117]
	v_mfma_f32_16x16x32_bf16 v[78:81], v[192:195], v[176:179], v[78:81]
	v_mfma_f32_16x16x32_bf16 v[74:77], v[200:203], v[176:179], v[74:77]
	v_mfma_f32_16x16x32_bf16 v[70:73], v[192:195], v[184:187], v[70:73]
	v_mfma_f32_16x16x32_bf16 v[66:69], v[200:203], v[184:187], v[66:69]
	v_mfma_f32_16x16x32_bf16 v[134:137], v[196:199], v[160:163], v[134:137]
	v_mfma_f32_16x16x32_bf16 v[130:133], v[204:207], v[160:163], v[130:133]
	v_mfma_f32_16x16x32_bf16 v[118:121], v[196:199], v[172:175], v[118:121]
	v_mfma_f32_16x16x32_bf16 v[114:117], v[204:207], v[172:175], v[114:117]
	v_mfma_f32_16x16x32_bf16 v[78:81], v[196:199], v[180:183], v[78:81]
	v_mfma_f32_16x16x32_bf16 v[74:77], v[204:207], v[180:183], v[74:77]
	v_mfma_f32_16x16x32_bf16 v[70:73], v[196:199], v[188:191], v[70:73]
	v_mfma_f32_16x16x32_bf16 v[66:69], v[204:207], v[188:191], v[66:69]
	s_barrier
	s_add_i32 s28, s38, s67
	s_mov_b32 m0, s28
	ds_read_b128 v[152:155], v171 offset:16384
	global_load_lds_dwordx4 v0, s[58:59]
	s_add_i32 m0, s28, 0x2000
	ds_read_b128 v[160:163], v171 offset:17408
	global_load_lds_dwordx4 v146, s[58:59]
	s_mov_b32 m0, s9
	ds_read_b128 v[164:167], v171 offset:18432
	global_load_lds_dwordx4 v0, s[60:61]
	s_mov_b32 m0, s68
	ds_read_b128 v[172:175], v171 offset:19456
	global_load_lds_dwordx4 v146, s[60:61]
	ds_read_b128 v[176:179], v171 offset:20480
	ds_read_b128 v[180:183], v171 offset:21504
	ds_read_b128 v[184:187], v171 offset:22528
	ds_read_b128 v[188:191], v171 offset:23552
	s_waitcnt vmcnt(4)
	s_waitcnt lgkmcnt(0)
	s_barrier
	v_mfma_f32_16x16x32_bf16 v[62:65], v[98:101], v[152:155], v[62:65]
	v_mfma_f32_16x16x32_bf16 v[58:61], v[106:109], v[152:155], v[58:61]
	v_mfma_f32_16x16x32_bf16 v[46:49], v[98:101], v[164:167], v[46:49]
	v_mfma_f32_16x16x32_bf16 v[42:45], v[106:109], v[164:167], v[42:45]
	v_mfma_f32_16x16x32_bf16 v[30:33], v[98:101], v[176:179], v[30:33]
	v_mfma_f32_16x16x32_bf16 v[26:29], v[106:109], v[176:179], v[26:29]
	v_mfma_f32_16x16x32_bf16 v[22:25], v[98:101], v[184:187], v[22:25]
	v_mfma_f32_16x16x32_bf16 v[18:21], v[106:109], v[184:187], v[18:21]
	v_mfma_f32_16x16x32_bf16 v[62:65], v[102:105], v[160:163], v[62:65]
	v_mfma_f32_16x16x32_bf16 v[58:61], v[110:113], v[160:163], v[58:61]
	v_mfma_f32_16x16x32_bf16 v[46:49], v[102:105], v[172:175], v[46:49]
	v_mfma_f32_16x16x32_bf16 v[42:45], v[110:113], v[172:175], v[42:45]
	v_mfma_f32_16x16x32_bf16 v[30:33], v[102:105], v[180:183], v[30:33]
	v_mfma_f32_16x16x32_bf16 v[26:29], v[110:113], v[180:183], v[26:29]
	v_mfma_f32_16x16x32_bf16 v[22:25], v[102:105], v[188:191], v[22:25]
	v_mfma_f32_16x16x32_bf16 v[18:21], v[110:113], v[188:191], v[18:21]
	v_mfma_f32_16x16x32_bf16 v[54:57], v[192:195], v[152:155], v[54:57]
	v_mfma_f32_16x16x32_bf16 v[50:53], v[200:203], v[152:155], v[50:53]
	v_mfma_f32_16x16x32_bf16 v[38:41], v[192:195], v[164:167], v[38:41]
	v_mfma_f32_16x16x32_bf16 v[34:37], v[200:203], v[164:167], v[34:37]
	v_mfma_f32_16x16x32_bf16 v[14:17], v[192:195], v[176:179], v[14:17]
	v_mfma_f32_16x16x32_bf16 v[10:13], v[200:203], v[176:179], v[10:13]
	v_mfma_f32_16x16x32_bf16 v[6:9], v[192:195], v[184:187], v[6:9]
	v_mfma_f32_16x16x32_bf16 v[2:5], v[200:203], v[184:187], v[2:5]
	v_mfma_f32_16x16x32_bf16 v[54:57], v[196:199], v[160:163], v[54:57]
	v_mfma_f32_16x16x32_bf16 v[50:53], v[204:207], v[160:163], v[50:53]
	v_mfma_f32_16x16x32_bf16 v[38:41], v[196:199], v[172:175], v[38:41]
	v_mfma_f32_16x16x32_bf16 v[34:37], v[204:207], v[172:175], v[34:37]
	v_mfma_f32_16x16x32_bf16 v[14:17], v[196:199], v[180:183], v[14:17]
	v_mfma_f32_16x16x32_bf16 v[10:13], v[204:207], v[180:183], v[10:13]
	v_mfma_f32_16x16x32_bf16 v[6:9], v[196:199], v[188:191], v[6:9]
	v_mfma_f32_16x16x32_bf16 v[2:5], v[204:207], v[188:191], v[2:5]
	s_barrier
; #define PG8_STAGE(bufoff, gbase, voff) do { _Pragma("unroll") for (int _i = 0; _i < 2; ++_i) \
;         __builtin_amdgcn_global_load_lds((const unsigned*)((const char*)(gbase) + (voff)[_i]), (LAS unsigned*)(lds + (bufoff) + ldsw + _i * 8192), 16, 0, 0); } while (0)
; #define PG8_LDA(dst, b, h) do { _Pragma("unroll") for (int m = 0; m < 4; ++m) _Pragma("unroll") for (int k = 0; k < 2; ++k) dst[m][k] = *(const LAS bf16x8*)(lds + PG8_SA(b, h) + aoff + m * 2048 + k * 1024); } while (0)
; #define PG8_LDB(dst, b, h) do { _Pragma("unroll") for (int n = 0; n < 2; ++n) _Pragma("unroll") for (int k = 0; k < 2; ++k) dst[n][k] = *(const LAS bf16x8*)(lds + PG8_SB(b, h) + boff + n * 2048 + k * 1024); } while (0)
; #define PG8_MMA(ai, bj, At, Bt) do { __builtin_amdgcn_s_setprio(1); _Pragma("unroll") for (int m = 0; m < 4; ++m) _Pragma("unroll") for (int n = 0; n < 2; ++n) _Pragma("unroll") for (int k = 0; k < 2; ++k) \
;         acc[ai][bj][m][n] = __builtin_amdgcn_mfma_f32_16x16x32_bf16(Bt[n][k], At[m][k], acc[ai][bj][m][n], 0, 0, 0); __builtin_amdgcn_s_setprio(0); } while (0)
; #define PG8_WAIT_V(n) asm volatile("s_waitcnt vmcnt(" #n ")" ::: "memory")
; #define PG8_WAIT_L(n) asm volatile("s_waitcnt lgkmcnt(" #n ")" ::: "memory")
; #define PG8_BAR __builtin_amdgcn_s_barrier()
;     __device__ __forceinline__ void operator()(const f32x4 (&acc)[2][2][4][2], const Unit& u, int wr, int wc, int fr, int fq) const {
;         const bool lat = u.pm < 64; const int r = lat ? (u.pm >> 3) : 8;
; template <class Epi, class Sched>
; __device__ __forceinline__ void gemm_phase(LAS unsigned char* lds, const Gemm g, const Sched& S, const Epi& E) {
;     ...
;             PG8_LDB(B0, 1, 0); PG8_SCHED; PG8_LDA(At, 1, 0); PG8_STAGE(PG8_SA(0, 1), a2 + hstep, voffA);
;             PG8_WAIT_L(8); PG8_BAR; PG8_WAIT_L(0); PG8_MMA(0, 0, At, B0); PG8_BAR; PG8_SCHED;
;             PG8_LDB(B1, 1, 1); PG8_STAGE(PG8_SB(1, 0), b3, voffB);
;             PG8_BAR; PG8_WAIT_L(0); PG8_MMA(0, 1, At, B1); PG8_BAR;
;             PG8_LDA(At, 1, 1); PG8_STAGE(PG8_SA(1, 0), a3, voffA);
;             PG8_BAR; PG8_WAIT_L(0); PG8_MMA(1, 0, At, B0); PG8_BAR; PG8_SCHED;
;             PG8_STAGE(PG8_SB(1, 1), b3 + hstep, voffB);
;             PG8_WAIT_V(6); PG8_BAR; PG8_MMA(1, 1, At, B1); PG8_BAR;
;         }
;         E(acc, cur, wr, wc, fr, fq);
;         if (!has_next) break;
	s_add_u32 s28, s58, 0x80000
	s_addc_u32 s29, s59, 0
	s_add_i32 s38, s39, s67
	s_mov_b32 m0, s38
	ds_read_b128 v[98:101], v226 offset:32768
	global_load_lds_dwordx4 v0, s[28:29]
	s_add_i32 m0, s38, 0x2000
	ds_read_b128 v[102:105], v226 offset:33792
	global_load_lds_dwordx4 v146, s[28:29]
	s_add_u32 s28, s60, 0x80000
	s_addc_u32 s29, s61, 0
	s_mov_b32 m0, s69
	ds_read_b128 v[106:109], v226 offset:34816
	global_load_lds_dwordx4 v0, s[28:29]
	s_mov_b32 m0, s70
	ds_read_b128 v[110:113], v226 offset:35840
	global_load_lds_dwordx4 v146, s[28:29]
	s_add_i32 s38, 0, 0x18000
	ds_read_b128 v[152:155], v171 offset:32768
	ds_read_b128 v[160:163], v171 offset:33792
	ds_read_b128 v[164:167], v171 offset:34816
	ds_read_b128 v[172:175], v171 offset:35840
	ds_read_b128 v[176:179], v171 offset:36864
	ds_read_b128 v[180:183], v171 offset:37888
	ds_read_b128 v[184:187], v171 offset:38912
	ds_read_b128 v[188:191], v171 offset:39936
	s_add_i32 s39, 0, 0x1c000
	ds_read_b128 v[192:195], v226 offset:49152
	ds_read_b128 v[196:199], v226 offset:50176
	ds_read_b128 v[200:203], v226 offset:51200
	ds_read_b128 v[204:207], v226 offset:52224
	s_waitcnt lgkmcnt(4)
	s_barrier
	s_waitcnt lgkmcnt(0)
	v_mfma_f32_16x16x32_bf16 v[142:145], v[98:101], v[152:155], v[142:145]
	v_mfma_f32_16x16x32_bf16 v[138:141], v[106:109], v[152:155], v[138:141]
	v_mfma_f32_16x16x32_bf16 v[126:129], v[98:101], v[164:167], v[126:129]
	v_mfma_f32_16x16x32_bf16 v[122:125], v[106:109], v[164:167], v[122:125]
	v_mfma_f32_16x16x32_bf16 v[94:97], v[98:101], v[176:179], v[94:97]
	v_mfma_f32_16x16x32_bf16 v[90:93], v[106:109], v[176:179], v[90:93]
	v_mfma_f32_16x16x32_bf16 v[86:89], v[98:101], v[184:187], v[86:89]
	v_mfma_f32_16x16x32_bf16 v[82:85], v[106:109], v[184:187], v[82:85]
	v_mfma_f32_16x16x32_bf16 v[142:145], v[102:105], v[160:163], v[142:145]
	v_mfma_f32_16x16x32_bf16 v[138:141], v[110:113], v[160:163], v[138:141]
	v_mfma_f32_16x16x32_bf16 v[126:129], v[102:105], v[172:175], v[126:129]
	v_mfma_f32_16x16x32_bf16 v[122:125], v[110:113], v[172:175], v[122:125]
	v_mfma_f32_16x16x32_bf16 v[94:97], v[102:105], v[180:183], v[94:97]
	v_mfma_f32_16x16x32_bf16 v[90:93], v[110:113], v[180:183], v[90:93]
	v_mfma_f32_16x16x32_bf16 v[86:89], v[102:105], v[188:191], v[86:89]
	v_mfma_f32_16x16x32_bf16 v[82:85], v[110:113], v[188:191], v[82:85]
	v_mfma_f32_16x16x32_bf16 v[134:137], v[192:195], v[152:155], v[134:137]
	v_mfma_f32_16x16x32_bf16 v[130:133], v[200:203], v[152:155], v[130:133]
	v_mfma_f32_16x16x32_bf16 v[118:121], v[192:195], v[164:167], v[118:121]
	v_mfma_f32_16x16x32_bf16 v[114:117], v[200:203], v[164:167], v[114:117]
	v_mfma_f32_16x16x32_bf16 v[78:81], v[192:195], v[176:179], v[78:81]
	v_mfma_f32_16x16x32_bf16 v[74:77], v[200:203], v[176:179], v[74:77]
	v_mfma_f32_16x16x32_bf16 v[70:73], v[192:195], v[184:187], v[70:73]
	v_mfma_f32_16x16x32_bf16 v[66:69], v[200:203], v[184:187], v[66:69]
	v_mfma_f32_16x16x32_bf16 v[134:137], v[196:199], v[160:163], v[134:137]
	v_mfma_f32_16x16x32_bf16 v[130:133], v[204:207], v[160:163], v[130:133]
	v_mfma_f32_16x16x32_bf16 v[118:121], v[196:199], v[172:175], v[118:121]
	v_mfma_f32_16x16x32_bf16 v[114:117], v[204:207], v[172:175], v[114:117]
	v_mfma_f32_16x16x32_bf16 v[78:81], v[196:199], v[180:183], v[78:81]
	v_mfma_f32_16x16x32_bf16 v[74:77], v[204:207], v[180:183], v[74:77]
	v_mfma_f32_16x16x32_bf16 v[70:73], v[196:199], v[188:191], v[70:73]
	v_mfma_f32_16x16x32_bf16 v[66:69], v[204:207], v[188:191], v[66:69]
	s_barrier
	s_add_i32 s28, s38, s67
	s_add_u32 s100, s58, s36
	s_addc_u32 s101, s59, s37
	s_mov_b32 m0, s28
	ds_read_b128 v[152:155], v171 offset:49152
	global_load_lds_dwordx4 v0, s[100:101]
	s_add_i32 m0, s28, 0x2000
	ds_read_b128 v[160:163], v171 offset:50176
	global_load_lds_dwordx4 v146, s[100:101]
	s_mov_b32 m0, s72
	s_add_u32 s100, s60, s36
	s_addc_u32 s101, s61, s37
	global_load_lds_dwordx4 v0, s[100:101]
	s_mov_b32 m0, s73
	ds_read_b128 v[164:167], v171 offset:51200
	global_load_lds_dwordx4 v146, s[100:101]
	ds_read_b128 v[172:175], v171 offset:52224
	ds_read_b128 v[176:179], v171 offset:53248
	ds_read_b128 v[180:183], v171 offset:54272
	ds_read_b128 v[184:187], v171 offset:55296
	ds_read_b128 v[188:191], v171 offset:56320
	s_waitcnt vmcnt(4)
	s_waitcnt lgkmcnt(0)
	s_barrier
	v_mfma_f32_16x16x32_bf16 v[62:65], v[98:101], v[152:155], v[62:65]
	v_mfma_f32_16x16x32_bf16 v[58:61], v[106:109], v[152:155], v[58:61]
	v_mfma_f32_16x16x32_bf16 v[46:49], v[98:101], v[164:167], v[46:49]
	v_mfma_f32_16x16x32_bf16 v[42:45], v[106:109], v[164:167], v[42:45]
	v_mfma_f32_16x16x32_bf16 v[30:33], v[98:101], v[176:179], v[30:33]
	v_mfma_f32_16x16x32_bf16 v[26:29], v[106:109], v[176:179], v[26:29]
	v_mfma_f32_16x16x32_bf16 v[22:25], v[98:101], v[184:187], v[22:25]
	v_mfma_f32_16x16x32_bf16 v[18:21], v[106:109], v[184:187], v[18:21]
	v_mfma_f32_16x16x32_bf16 v[62:65], v[102:105], v[160:163], v[62:65]
	v_mfma_f32_16x16x32_bf16 v[58:61], v[110:113], v[160:163], v[58:61]
	v_mfma_f32_16x16x32_bf16 v[46:49], v[102:105], v[172:175], v[46:49]
	v_mfma_f32_16x16x32_bf16 v[42:45], v[110:113], v[172:175], v[42:45]
	v_mfma_f32_16x16x32_bf16 v[30:33], v[102:105], v[180:183], v[30:33]
	v_mfma_f32_16x16x32_bf16 v[26:29], v[110:113], v[180:183], v[26:29]
	v_mfma_f32_16x16x32_bf16 v[22:25], v[102:105], v[188:191], v[22:25]
	v_mfma_f32_16x16x32_bf16 v[18:21], v[110:113], v[188:191], v[18:21]
	s_add_u32 s28, s58, 0x80080
	s_addc_u32 s29, s59, 0
	s_add_i32 s38, s39, s67
	s_mov_b32 m0, s38
	s_nop 0
	global_load_lds_dwordx4 v0, s[28:29]
	s_add_i32 m0, s38, 0x2000
	s_nop 0
	global_load_lds_dwordx4 v146, s[28:29]
	v_mfma_f32_16x16x32_bf16 v[54:57], v[192:195], v[152:155], v[54:57]
	v_mfma_f32_16x16x32_bf16 v[50:53], v[200:203], v[152:155], v[50:53]
	v_mfma_f32_16x16x32_bf16 v[38:41], v[192:195], v[164:167], v[38:41]
	v_mfma_f32_16x16x32_bf16 v[34:37], v[200:203], v[164:167], v[34:37]
	v_mfma_f32_16x16x32_bf16 v[14:17], v[192:195], v[176:179], v[14:17]
	v_mfma_f32_16x16x32_bf16 v[10:13], v[200:203], v[176:179], v[10:13]
	v_mfma_f32_16x16x32_bf16 v[6:9], v[192:195], v[184:187], v[6:9]
	v_mfma_f32_16x16x32_bf16 v[2:5], v[200:203], v[184:187], v[2:5]
	v_mfma_f32_16x16x32_bf16 v[54:57], v[196:199], v[160:163], v[54:57]
	v_mfma_f32_16x16x32_bf16 v[50:53], v[204:207], v[160:163], v[50:53]
	v_mfma_f32_16x16x32_bf16 v[38:41], v[196:199], v[172:175], v[38:41]
	v_mfma_f32_16x16x32_bf16 v[34:37], v[204:207], v[172:175], v[34:37]
	v_mfma_f32_16x16x32_bf16 v[14:17], v[196:199], v[180:183], v[14:17]
	v_mfma_f32_16x16x32_bf16 v[10:13], v[204:207], v[180:183], v[10:13]
	v_mfma_f32_16x16x32_bf16 v[6:9], v[196:199], v[188:191], v[6:9]
	v_mfma_f32_16x16x32_bf16 v[2:5], v[204:207], v[188:191], v[2:5]
	s_cmp_gt_i32 s81, 27
	s_barrier
	s_cbranch_scc0 .LBB0_99
	s_cmp_lt_i32 s8, 64
	s_cselect_b64 s[58:59], -1, 0
	s_cmp_gt_i32 s8, 63
	s_cbranch_scc0 .LBB0_90
	s_mov_b64 s[60:61], 0x18000
	s_mov_b64 s[28:29], s[46:47]
	s_mov_b64 s[56:57], s[24:25]
	s_branch .LBB0_91

; #define PG8_STAGE(bufoff, gbase, voff) do { _Pragma("unroll") for (int _i = 0; _i < 2; ++_i) \
;         __builtin_amdgcn_global_load_lds((const unsigned*)((const char*)(gbase) + (voff)[_i]), (LAS unsigned*)(lds + (bufoff) + ldsw + _i * 8192), 16, 0, 0); } while (0)
; #define PG8_LDA(dst, b, h) do { _Pragma("unroll") for (int m = 0; m < 4; ++m) _Pragma("unroll") for (int k = 0; k < 2; ++k) dst[m][k] = *(const LAS bf16x8*)(lds + PG8_SA(b, h) + aoff + m * 2048 + k * 1024); } while (0)
; #define PG8_LDB(dst, b, h) do { _Pragma("unroll") for (int n = 0; n < 2; ++n) _Pragma("unroll") for (int k = 0; k < 2; ++k) dst[n][k] = *(const LAS bf16x8*)(lds + PG8_SB(b, h) + boff + n * 2048 + k * 1024); } while (0)
; #define PG8_SCHED __builtin_amdgcn_sched_barrier(0)
; template <class Epi, class Sched>
; __device__ __forceinline__ void gemm_phase(LAS unsigned char* lds, const Gemm g, const Sched& S, const Epi& E) {
;     ...
;         const char* nA = has_next ? (const char*)g.A + (size_t)nxt.pm * tstep + (size_t)nxt.ks * sstep : cA; const char* nB = has_next ? (const char*)g.Bt + (size_t)nxt.pn * tstep + (size_t)nxt.ks * sstep : cB;
;         for (int t = 0; t < nt; t += 2) {
;             const bool last = (t == nt - 2);
;             const char* a1 = cA + (size_t)(t + 1) * kstep;
;             const char* a2 = last ? nA : cA + (size_t)(t + 2) * kstep; const char* b2 = last ? nB : cB + (size_t)(t + 2) * kstep;
;             const char* a3 = a2 + kstep; const char* b3 = b2 + kstep;
;             PG8_LDB(B0, 0, 0); PG8_SCHED; PG8_LDA(At, 0, 0); PG8_STAGE(PG8_SA(1, 1), a1 + hstep, voffA);
;     ...
;         for (int a = 0; a < 2; ++a)
; #pragma unroll
;             for (int b = 0; b < 2; ++b)
; #pragma unroll
;                 for (int m = 0; m < 4; ++m)
; #pragma unroll
;                     for (int n = 0; n < 2; ++n) acc[a][b][m][n] = (f32x4){0.f, 0.f, 0.f, 0.f};
.LBB0_112:
	s_ashr_i32 s45, s44, 31
	s_lshl_b64 s[38:39], s[44:45], 20
	s_add_u32 s11, s61, s38
	s_addc_u32 s41, s64, s39
	s_ashr_i32 s29, s28, 31
	s_lshl_b64 s[38:39], s[28:29], 10
	s_add_u32 s48, s11, s38
	s_addc_u32 s49, s41, s39
	s_and_b64 s[50:51], s[56:57], exec
	s_cselect_b32 s11, s49, s53
	s_cselect_b32 s29, s48, s52
	s_ashr_i32 s41, s40, 31
	s_lshl_b64 s[50:51], s[40:41], 20
	s_add_u32 s41, s13, s50
	s_addc_u32 s45, s62, s51
	s_add_u32 s50, s41, s38
	s_addc_u32 s51, s45, s39
	s_and_b64 s[38:39], s[56:57], exec
	s_cselect_b32 s41, s51, s55
	s_cselect_b32 s45, s50, s54
	s_add_u32 s71, s54, 0x100
	v_mov_b32_e32 v2, 0
	s_addc_u32 s72, s55, 0
	s_mov_b32 s73, -2
	v_mov_b32_e32 v3, v2
	v_mov_b32_e32 v4, v2
	v_mov_b32_e32 v5, v2
	v_mov_b32_e32 v6, v2
	v_mov_b32_e32 v7, v2
	v_mov_b32_e32 v8, v2
	v_mov_b32_e32 v9, v2
	v_mov_b32_e32 v10, v2
	v_mov_b32_e32 v11, v2
	v_mov_b32_e32 v12, v2
	v_mov_b32_e32 v13, v2
	v_mov_b32_e32 v14, v2
	v_mov_b32_e32 v15, v2
	v_mov_b32_e32 v16, v2
	v_mov_b32_e32 v17, v2
	v_mov_b32_e32 v26, v2
	v_mov_b32_e32 v27, v2
	v_mov_b32_e32 v28, v2
	v_mov_b32_e32 v29, v2
	v_mov_b32_e32 v30, v2
	v_mov_b32_e32 v31, v2
	v_mov_b32_e32 v32, v2
	v_mov_b32_e32 v33, v2
	v_mov_b32_e32 v42, v2
	v_mov_b32_e32 v43, v2
	v_mov_b32_e32 v44, v2
	v_mov_b32_e32 v45, v2
	v_mov_b32_e32 v46, v2
	v_mov_b32_e32 v47, v2
	v_mov_b32_e32 v48, v2
	v_mov_b32_e32 v49, v2
	v_mov_b32_e32 v18, v2
	v_mov_b32_e32 v19, v2
	v_mov_b32_e32 v20, v2
	v_mov_b32_e32 v21, v2
	v_mov_b32_e32 v22, v2
	v_mov_b32_e32 v23, v2
	v_mov_b32_e32 v24, v2
	v_mov_b32_e32 v25, v2
	v_mov_b32_e32 v34, v2
	v_mov_b32_e32 v35, v2
	v_mov_b32_e32 v36, v2
	v_mov_b32_e32 v37, v2
	v_mov_b32_e32 v38, v2
	v_mov_b32_e32 v39, v2
	v_mov_b32_e32 v40, v2
	v_mov_b32_e32 v41, v2
	v_mov_b32_e32 v50, v2
	v_mov_b32_e32 v51, v2
	v_mov_b32_e32 v52, v2
	v_mov_b32_e32 v53, v2
	v_mov_b32_e32 v54, v2
	v_mov_b32_e32 v55, v2
	v_mov_b32_e32 v56, v2
	v_mov_b32_e32 v57, v2
	v_mov_b32_e32 v58, v2
	v_mov_b32_e32 v59, v2
	v_mov_b32_e32 v60, v2
	v_mov_b32_e32 v61, v2
	v_mov_b32_e32 v62, v2
	v_mov_b32_e32 v63, v2
	v_mov_b32_e32 v64, v2
	v_mov_b32_e32 v65, v2
	v_mov_b32_e32 v66, v2
	v_mov_b32_e32 v67, v2
	v_mov_b32_e32 v68, v2
	v_mov_b32_e32 v69, v2
	v_mov_b32_e32 v70, v2
	v_mov_b32_e32 v71, v2
	v_mov_b32_e32 v72, v2
	v_mov_b32_e32 v73, v2
	v_mov_b32_e32 v74, v2
	v_mov_b32_e32 v75, v2
	v_mov_b32_e32 v76, v2
	v_mov_b32_e32 v77, v2
	v_mov_b32_e32 v78, v2
	v_mov_b32_e32 v79, v2
	v_mov_b32_e32 v80, v2
	v_mov_b32_e32 v81, v2
	v_mov_b32_e32 v86, v2
	v_mov_b32_e32 v87, v2
	v_mov_b32_e32 v88, v2
	v_mov_b32_e32 v89, v2
	v_mov_b32_e32 v94, v2
	v_mov_b32_e32 v95, v2
	v_mov_b32_e32 v96, v2
	v_mov_b32_e32 v97, v2
	v_mov_b32_e32 v102, v2
	v_mov_b32_e32 v103, v2
	v_mov_b32_e32 v104, v2
	v_mov_b32_e32 v105, v2
	v_mov_b32_e32 v110, v2
	v_mov_b32_e32 v111, v2
	v_mov_b32_e32 v112, v2
	v_mov_b32_e32 v113, v2
	v_mov_b32_e32 v82, v2
	v_mov_b32_e32 v83, v2
	v_mov_b32_e32 v84, v2
	v_mov_b32_e32 v85, v2
	v_mov_b32_e32 v90, v2
	v_mov_b32_e32 v91, v2
	v_mov_b32_e32 v92, v2
	v_mov_b32_e32 v93, v2
	v_mov_b32_e32 v98, v2
	v_mov_b32_e32 v99, v2
	v_mov_b32_e32 v100, v2
	v_mov_b32_e32 v101, v2
	v_mov_b32_e32 v106, v2
	v_mov_b32_e32 v107, v2
	v_mov_b32_e32 v108, v2
	v_mov_b32_e32 v109, v2
	v_mov_b32_e32 v114, v2
	v_mov_b32_e32 v115, v2
	v_mov_b32_e32 v116, v2
	v_mov_b32_e32 v117, v2
	v_mov_b32_e32 v118, v2
	v_mov_b32_e32 v119, v2
	v_mov_b32_e32 v120, v2
	v_mov_b32_e32 v121, v2
	v_mov_b32_e32 v122, v2
	v_mov_b32_e32 v123, v2
	v_mov_b32_e32 v124, v2
	v_mov_b32_e32 v125, v2
	v_mov_b32_e32 v126, v2
	v_mov_b32_e32 v127, v2
	v_mov_b32_e32 v128, v2
	v_mov_b32_e32 v129, v2
	s_branch .Lent_113
.LBB0_113:
	s_add_i32 s73, s73, 2
	s_add_u32 s71, s71, 0x100
	s_addc_u32 s72, s72, 0
	s_mov_b64 s[52:53], s[54:55]
.Lent_113:
	s_add_u32 s54, s52, 0x100
	s_addc_u32 s55, s53, 0
	s_cmp_eq_u32 s73, 4
	s_cselect_b32 s59, s11, s55
	s_cselect_b32 s58, s29, s54
	s_cselect_b32 s57, s41, s72
	s_cselect_b32 s56, s45, s71
	s_add_i32 m0, s25, 0xc000
	ds_read_b128 v[140:143], v226
	global_load_lds_dwordx4 v134, s[52:53]
	s_add_i32 m0, s25, 0xe000
	ds_read_b128 v[144:147], v226 offset:1024
	global_load_lds_dwordx4 v132, s[52:53]
	s_add_i32 s38, 0, 0x10000
	ds_read_b128 v[148:151], v226 offset:2048
	ds_read_b128 v[152:155], v226 offset:3072
	ds_read_b128 v[160:163], v139
	ds_read_b128 v[164:167], v139 offset:1024
	ds_read_b128 v[168:171], v139 offset:2048
	ds_read_b128 v[172:175], v139 offset:3072
	ds_read_b128 v[176:179], v139 offset:4096
	ds_read_b128 v[180:183], v139 offset:5120
	ds_read_b128 v[184:187], v139 offset:6144
	ds_read_b128 v[188:191], v139 offset:7168
	s_add_i32 s52, 0, 0x14000
	ds_read_b128 v[192:195], v226 offset:16384
	ds_read_b128 v[196:199], v226 offset:17408
	ds_read_b128 v[200:203], v226 offset:18432
	ds_read_b128 v[204:207], v226 offset:19456
	s_waitcnt lgkmcnt(4)
	s_barrier
; #define PG8_STAGE(bufoff, gbase, voff) do { _Pragma("unroll") for (int _i = 0; _i < 2; ++_i) \
;         __builtin_amdgcn_global_load_lds((const unsigned*)((const char*)(gbase) + (voff)[_i]), (LAS unsigned*)(lds + (bufoff) + ldsw + _i * 8192), 16, 0, 0); } while (0)
; #define PG8_LDA(dst, b, h) do { _Pragma("unroll") for (int m = 0; m < 4; ++m) _Pragma("unroll") for (int k = 0; k < 2; ++k) dst[m][k] = *(const LAS bf16x8*)(lds + PG8_SA(b, h) + aoff + m * 2048 + k * 1024); } while (0)
; #define PG8_LDB(dst, b, h) do { _Pragma("unroll") for (int n = 0; n < 2; ++n) _Pragma("unroll") for (int k = 0; k < 2; ++k) dst[n][k] = *(const LAS bf16x8*)(lds + PG8_SB(b, h) + boff + n * 2048 + k * 1024); } while (0)
; #define PG8_MMA(ai, bj, At, Bt) do { __builtin_amdgcn_s_setprio(1); _Pragma("unroll") for (int m = 0; m < 4; ++m) _Pragma("unroll") for (int n = 0; n < 2; ++n) _Pragma("unroll") for (int k = 0; k < 2; ++k) \
;         acc[ai][bj][m][n] = __builtin_amdgcn_mfma_f32_16x16x32_bf16(Bt[n][k], At[m][k], acc[ai][bj][m][n], 0, 0, 0); __builtin_amdgcn_s_setprio(0); } while (0)
; #define PG8_WAIT_V(n) asm volatile("s_waitcnt vmcnt(" #n ")" ::: "memory")
; #define PG8_WAIT_L(n) asm volatile("s_waitcnt lgkmcnt(" #n ")" ::: "memory")
; #define PG8_BAR __builtin_amdgcn_s_barrier()
; #define PG8_SCHED __builtin_amdgcn_sched_barrier(0)
; template <class Epi, class Sched>
; __device__ __forceinline__ void gemm_phase(LAS unsigned char* lds, const Gemm g, const Sched& S, const Epi& E) {
;     ...
;             PG8_LDB(B0, 0, 0); PG8_SCHED; PG8_LDA(At, 0, 0); PG8_STAGE(PG8_SA(1, 1), a1 + hstep, voffA);
;             PG8_WAIT_L(8); PG8_BAR; PG8_WAIT_L(0); PG8_MMA(0, 0, At, B0); PG8_BAR; PG8_SCHED;
;             PG8_LDB(B1, 0, 1); PG8_STAGE(PG8_SB(0, 0), b2, voffB);
;             PG8_BAR; PG8_WAIT_L(0); PG8_MMA(0, 1, At, B1); PG8_BAR;
;             PG8_LDA(At, 0, 1); PG8_STAGE(PG8_SA(0, 0), a2, voffA);
;             PG8_BAR; PG8_WAIT_L(0); PG8_MMA(1, 0, At, B0); PG8_BAR; PG8_SCHED;
;             PG8_STAGE(PG8_SB(0, 1), b2 + hstep, voffB);
;             PG8_WAIT_V(6); PG8_BAR; PG8_MMA(1, 1, At, B1); PG8_BAR;
	s_waitcnt lgkmcnt(0)
	v_mfma_f32_16x16x32_bf16 v[126:129], v[140:143], v[160:163], v[126:129]
	v_mfma_f32_16x16x32_bf16 v[122:125], v[148:151], v[160:163], v[122:125]
	v_mfma_f32_16x16x32_bf16 v[118:121], v[140:143], v[168:171], v[118:121]
	v_mfma_f32_16x16x32_bf16 v[114:117], v[148:151], v[168:171], v[114:117]
	v_mfma_f32_16x16x32_bf16 v[106:109], v[140:143], v[176:179], v[106:109]
	v_mfma_f32_16x16x32_bf16 v[98:101], v[148:151], v[176:179], v[98:101]
	v_mfma_f32_16x16x32_bf16 v[90:93], v[140:143], v[184:187], v[90:93]
	v_mfma_f32_16x16x32_bf16 v[82:85], v[148:151], v[184:187], v[82:85]
	v_mfma_f32_16x16x32_bf16 v[126:129], v[144:147], v[164:167], v[126:129]
	v_mfma_f32_16x16x32_bf16 v[122:125], v[152:155], v[164:167], v[122:125]
	v_mfma_f32_16x16x32_bf16 v[118:121], v[144:147], v[172:175], v[118:121]
	v_mfma_f32_16x16x32_bf16 v[114:117], v[152:155], v[172:175], v[114:117]
	v_mfma_f32_16x16x32_bf16 v[106:109], v[144:147], v[180:183], v[106:109]
	v_mfma_f32_16x16x32_bf16 v[98:101], v[152:155], v[180:183], v[98:101]
	v_mfma_f32_16x16x32_bf16 v[90:93], v[144:147], v[188:191], v[90:93]
	v_mfma_f32_16x16x32_bf16 v[82:85], v[152:155], v[188:191], v[82:85]
	v_mfma_f32_16x16x32_bf16 v[110:113], v[192:195], v[160:163], v[110:113]
	v_mfma_f32_16x16x32_bf16 v[102:105], v[200:203], v[160:163], v[102:105]
	v_mfma_f32_16x16x32_bf16 v[94:97], v[192:195], v[168:171], v[94:97]
	v_mfma_f32_16x16x32_bf16 v[86:89], v[200:203], v[168:171], v[86:89]
	v_mfma_f32_16x16x32_bf16 v[78:81], v[192:195], v[176:179], v[78:81]
	v_mfma_f32_16x16x32_bf16 v[74:77], v[200:203], v[176:179], v[74:77]
	v_mfma_f32_16x16x32_bf16 v[70:73], v[192:195], v[184:187], v[70:73]
	v_mfma_f32_16x16x32_bf16 v[66:69], v[200:203], v[184:187], v[66:69]
	v_mfma_f32_16x16x32_bf16 v[110:113], v[196:199], v[164:167], v[110:113]
	v_mfma_f32_16x16x32_bf16 v[102:105], v[204:207], v[164:167], v[102:105]
	v_mfma_f32_16x16x32_bf16 v[94:97], v[196:199], v[172:175], v[94:97]
	v_mfma_f32_16x16x32_bf16 v[86:89], v[204:207], v[172:175], v[86:89]
	v_mfma_f32_16x16x32_bf16 v[78:81], v[196:199], v[180:183], v[78:81]
	v_mfma_f32_16x16x32_bf16 v[74:77], v[204:207], v[180:183], v[74:77]
	v_mfma_f32_16x16x32_bf16 v[70:73], v[196:199], v[188:191], v[70:73]
	v_mfma_f32_16x16x32_bf16 v[66:69], v[204:207], v[188:191], v[66:69]
	s_barrier
	s_add_i32 s38, s38, s65
	s_mov_b32 m0, s38
	ds_read_b128 v[160:163], v139 offset:16384
	global_load_lds_dwordx4 v0, s[56:57]
	s_add_i32 m0, s38, 0x2000
	ds_read_b128 v[164:167], v139 offset:17408
	global_load_lds_dwordx4 v130, s[56:57]
	s_mov_b32 m0, s25
	ds_read_b128 v[168:171], v139 offset:18432
	global_load_lds_dwordx4 v0, s[58:59]
	s_mov_b32 m0, s27
	ds_read_b128 v[172:175], v139 offset:19456
	global_load_lds_dwordx4 v130, s[58:59]
	ds_read_b128 v[176:179], v139 offset:20480
	ds_read_b128 v[180:183], v139 offset:21504
	ds_read_b128 v[184:187], v139 offset:22528
	ds_read_b128 v[188:191], v139 offset:23552
	s_waitcnt vmcnt(4)
	s_waitcnt lgkmcnt(0)
	s_barrier
	v_mfma_f32_16x16x32_bf16 v[62:65], v[140:143], v[160:163], v[62:65]
	v_mfma_f32_16x16x32_bf16 v[58:61], v[148:151], v[160:163], v[58:61]
	v_mfma_f32_16x16x32_bf16 v[54:57], v[140:143], v[168:171], v[54:57]
	v_mfma_f32_16x16x32_bf16 v[50:53], v[148:151], v[168:171], v[50:53]
	v_mfma_f32_16x16x32_bf16 v[38:41], v[140:143], v[176:179], v[38:41]
	v_mfma_f32_16x16x32_bf16 v[34:37], v[148:151], v[176:179], v[34:37]
	v_mfma_f32_16x16x32_bf16 v[22:25], v[140:143], v[184:187], v[22:25]
	v_mfma_f32_16x16x32_bf16 v[18:21], v[148:151], v[184:187], v[18:21]
	v_mfma_f32_16x16x32_bf16 v[62:65], v[144:147], v[164:167], v[62:65]
	v_mfma_f32_16x16x32_bf16 v[58:61], v[152:155], v[164:167], v[58:61]
	v_mfma_f32_16x16x32_bf16 v[54:57], v[144:147], v[172:175], v[54:57]
	v_mfma_f32_16x16x32_bf16 v[50:53], v[152:155], v[172:175], v[50:53]
	v_mfma_f32_16x16x32_bf16 v[38:41], v[144:147], v[180:183], v[38:41]
	v_mfma_f32_16x16x32_bf16 v[34:37], v[152:155], v[180:183], v[34:37]
	v_mfma_f32_16x16x32_bf16 v[22:25], v[144:147], v[188:191], v[22:25]
	v_mfma_f32_16x16x32_bf16 v[18:21], v[152:155], v[188:191], v[18:21]
	v_mfma_f32_16x16x32_bf16 v[46:49], v[192:195], v[160:163], v[46:49]
	v_mfma_f32_16x16x32_bf16 v[42:45], v[200:203], v[160:163], v[42:45]
	v_mfma_f32_16x16x32_bf16 v[30:33], v[192:195], v[168:171], v[30:33]
	v_mfma_f32_16x16x32_bf16 v[26:29], v[200:203], v[168:171], v[26:29]
	v_mfma_f32_16x16x32_bf16 v[14:17], v[192:195], v[176:179], v[14:17]
	v_mfma_f32_16x16x32_bf16 v[10:13], v[200:203], v[176:179], v[10:13]
	v_mfma_f32_16x16x32_bf16 v[6:9], v[192:195], v[184:187], v[6:9]
	v_mfma_f32_16x16x32_bf16 v[2:5], v[200:203], v[184:187], v[2:5]
	v_mfma_f32_16x16x32_bf16 v[46:49], v[196:199], v[164:167], v[46:49]
	v_mfma_f32_16x16x32_bf16 v[42:45], v[204:207], v[164:167], v[42:45]
	v_mfma_f32_16x16x32_bf16 v[30:33], v[196:199], v[172:175], v[30:33]
	v_mfma_f32_16x16x32_bf16 v[26:29], v[204:207], v[172:175], v[26:29]
	v_mfma_f32_16x16x32_bf16 v[14:17], v[196:199], v[180:183], v[14:17]
	v_mfma_f32_16x16x32_bf16 v[10:13], v[204:207], v[180:183], v[10:13]
	v_mfma_f32_16x16x32_bf16 v[6:9], v[196:199], v[188:191], v[6:9]
	v_mfma_f32_16x16x32_bf16 v[2:5], v[204:207], v[188:191], v[2:5]
	s_barrier
; #define PG8_STAGE(bufoff, gbase, voff) do { _Pragma("unroll") for (int _i = 0; _i < 2; ++_i) \
;         __builtin_amdgcn_global_load_lds((const unsigned*)((const char*)(gbase) + (voff)[_i]), (LAS unsigned*)(lds + (bufoff) + ldsw + _i * 8192), 16, 0, 0); } while (0)
; #define PG8_LDA(dst, b, h) do { _Pragma("unroll") for (int m = 0; m < 4; ++m) _Pragma("unroll") for (int k = 0; k < 2; ++k) dst[m][k] = *(const LAS bf16x8*)(lds + PG8_SA(b, h) + aoff + m * 2048 + k * 1024); } while (0)
; #define PG8_LDB(dst, b, h) do { _Pragma("unroll") for (int n = 0; n < 2; ++n) _Pragma("unroll") for (int k = 0; k < 2; ++k) dst[n][k] = *(const LAS bf16x8*)(lds + PG8_SB(b, h) + boff + n * 2048 + k * 1024); } while (0)
; #define PG8_MMA(ai, bj, At, Bt) do { __builtin_amdgcn_s_setprio(1); _Pragma("unroll") for (int m = 0; m < 4; ++m) _Pragma("unroll") for (int n = 0; n < 2; ++n) _Pragma("unroll") for (int k = 0; k < 2; ++k) \
;         acc[ai][bj][m][n] = __builtin_amdgcn_mfma_f32_16x16x32_bf16(Bt[n][k], At[m][k], acc[ai][bj][m][n], 0, 0, 0); __builtin_amdgcn_s_setprio(0); } while (0)
; #define PG8_WAIT_L(n) asm volatile("s_waitcnt lgkmcnt(" #n ")" ::: "memory")
; #define PG8_BAR __builtin_amdgcn_s_barrier()
; #define PG8_SCHED __builtin_amdgcn_sched_barrier(0)
; template <class Epi, class Sched>
; __device__ __forceinline__ void gemm_phase(LAS unsigned char* lds, const Gemm g, const Sched& S, const Epi& E) {
;     ...
;             PG8_LDB(B0, 1, 0); PG8_SCHED; PG8_LDA(At, 1, 0); PG8_STAGE(PG8_SA(0, 1), a2 + hstep, voffA);
;             PG8_WAIT_L(8); PG8_BAR; PG8_WAIT_L(0); PG8_MMA(0, 0, At, B0); PG8_BAR; PG8_SCHED;
;             PG8_LDB(B1, 1, 1); PG8_STAGE(PG8_SB(1, 0), b3, voffB);
;             PG8_BAR; PG8_WAIT_L(0); PG8_MMA(0, 1, At, B1); PG8_BAR;
;             PG8_LDA(At, 1, 1); PG8_STAGE(PG8_SA(1, 0), a3, voffA);
;             PG8_BAR; PG8_WAIT_L(0); PG8_MMA(1, 0, At, B0); PG8_BAR; PG8_SCHED;
	s_add_u32 s38, s56, 0x80000
	s_addc_u32 s39, s57, 0
	s_add_i32 s52, s52, s65
	s_mov_b32 m0, s52
	ds_read_b128 v[140:143], v226 offset:32768
	global_load_lds_dwordx4 v0, s[38:39]
	s_add_i32 m0, s52, 0x2000
	ds_read_b128 v[144:147], v226 offset:33792
	global_load_lds_dwordx4 v130, s[38:39]
	s_add_u32 s38, s58, 0x80000
	s_addc_u32 s39, s59, 0
	s_mov_b32 m0, s66
	ds_read_b128 v[148:151], v226 offset:34816
	global_load_lds_dwordx4 v0, s[38:39]
	s_mov_b32 m0, s67
	ds_read_b128 v[152:155], v226 offset:35840
	global_load_lds_dwordx4 v130, s[38:39]
	s_add_i32 s52, 0, 0x18000
	ds_read_b128 v[160:163], v139 offset:32768
	ds_read_b128 v[164:167], v139 offset:33792
	ds_read_b128 v[168:171], v139 offset:34816
	ds_read_b128 v[172:175], v139 offset:35840
	ds_read_b128 v[176:179], v139 offset:36864
	ds_read_b128 v[180:183], v139 offset:37888
	ds_read_b128 v[184:187], v139 offset:38912
	ds_read_b128 v[188:191], v139 offset:39936
	s_add_i32 s53, 0, 0x1c000
	ds_read_b128 v[192:195], v226 offset:49152
	ds_read_b128 v[196:199], v226 offset:50176
	ds_read_b128 v[200:203], v226 offset:51200
	ds_read_b128 v[204:207], v226 offset:52224
	s_waitcnt lgkmcnt(4)
	s_barrier
	s_waitcnt lgkmcnt(0)
	v_mfma_f32_16x16x32_bf16 v[126:129], v[140:143], v[160:163], v[126:129]
	v_mfma_f32_16x16x32_bf16 v[122:125], v[148:151], v[160:163], v[122:125]
	v_mfma_f32_16x16x32_bf16 v[118:121], v[140:143], v[168:171], v[118:121]
	v_mfma_f32_16x16x32_bf16 v[114:117], v[148:151], v[168:171], v[114:117]
	v_mfma_f32_16x16x32_bf16 v[106:109], v[140:143], v[176:179], v[106:109]
	v_mfma_f32_16x16x32_bf16 v[98:101], v[148:151], v[176:179], v[98:101]
	v_mfma_f32_16x16x32_bf16 v[90:93], v[140:143], v[184:187], v[90:93]
	v_mfma_f32_16x16x32_bf16 v[82:85], v[148:151], v[184:187], v[82:85]
	v_mfma_f32_16x16x32_bf16 v[126:129], v[144:147], v[164:167], v[126:129]
	v_mfma_f32_16x16x32_bf16 v[122:125], v[152:155], v[164:167], v[122:125]
	v_mfma_f32_16x16x32_bf16 v[118:121], v[144:147], v[172:175], v[118:121]
	v_mfma_f32_16x16x32_bf16 v[114:117], v[152:155], v[172:175], v[114:117]
	v_mfma_f32_16x16x32_bf16 v[106:109], v[144:147], v[180:183], v[106:109]
	v_mfma_f32_16x16x32_bf16 v[98:101], v[152:155], v[180:183], v[98:101]
	v_mfma_f32_16x16x32_bf16 v[90:93], v[144:147], v[188:191], v[90:93]
	v_mfma_f32_16x16x32_bf16 v[82:85], v[152:155], v[188:191], v[82:85]
	v_mfma_f32_16x16x32_bf16 v[110:113], v[192:195], v[160:163], v[110:113]
	v_mfma_f32_16x16x32_bf16 v[102:105], v[200:203], v[160:163], v[102:105]
	v_mfma_f32_16x16x32_bf16 v[94:97], v[192:195], v[168:171], v[94:97]
	v_mfma_f32_16x16x32_bf16 v[86:89], v[200:203], v[168:171], v[86:89]
	v_mfma_f32_16x16x32_bf16 v[78:81], v[192:195], v[176:179], v[78:81]
	v_mfma_f32_16x16x32_bf16 v[74:77], v[200:203], v[176:179], v[74:77]
	v_mfma_f32_16x16x32_bf16 v[70:73], v[192:195], v[184:187], v[70:73]
	v_mfma_f32_16x16x32_bf16 v[66:69], v[200:203], v[184:187], v[66:69]
	v_mfma_f32_16x16x32_bf16 v[110:113], v[196:199], v[164:167], v[110:113]
	v_mfma_f32_16x16x32_bf16 v[102:105], v[204:207], v[164:167], v[102:105]
	v_mfma_f32_16x16x32_bf16 v[94:97], v[196:199], v[172:175], v[94:97]
	v_mfma_f32_16x16x32_bf16 v[86:89], v[204:207], v[172:175], v[86:89]
	v_mfma_f32_16x16x32_bf16 v[78:81], v[196:199], v[180:183], v[78:81]
	v_mfma_f32_16x16x32_bf16 v[74:77], v[204:207], v[180:183], v[74:77]
	v_mfma_f32_16x16x32_bf16 v[70:73], v[196:199], v[188:191], v[70:73]
	v_mfma_f32_16x16x32_bf16 v[66:69], v[204:207], v[188:191], v[66:69]
	s_barrier
	s_add_i32 s38, s52, s65
	s_add_u32 s100, s56, s36
	s_addc_u32 s101, s57, s37
	s_mov_b32 m0, s38
	ds_read_b128 v[160:163], v139 offset:49152
	global_load_lds_dwordx4 v0, s[100:101]
	s_add_i32 m0, s38, 0x2000
	ds_read_b128 v[164:167], v139 offset:50176
	global_load_lds_dwordx4 v130, s[100:101]
	s_mov_b32 m0, s68
	s_add_u32 s100, s58, s36
	s_addc_u32 s101, s59, s37
	global_load_lds_dwordx4 v0, s[100:101]
	s_mov_b32 m0, s69
	ds_read_b128 v[168:171], v139 offset:51200
	global_load_lds_dwordx4 v130, s[100:101]
	ds_read_b128 v[172:175], v139 offset:52224
	ds_read_b128 v[176:179], v139 offset:53248
	ds_read_b128 v[180:183], v139 offset:54272
	ds_read_b128 v[184:187], v139 offset:55296
	ds_read_b128 v[188:191], v139 offset:56320
	s_waitcnt vmcnt(4)
	s_waitcnt lgkmcnt(0)
	s_barrier
; #define PG8_STAGE(bufoff, gbase, voff) do { _Pragma("unroll") for (int _i = 0; _i < 2; ++_i) \
;         __builtin_amdgcn_global_load_lds((const unsigned*)((const char*)(gbase) + (voff)[_i]), (LAS unsigned*)(lds + (bufoff) + ldsw + _i * 8192), 16, 0, 0); } while (0)
; #define PG8_MMA(ai, bj, At, Bt) do { __builtin_amdgcn_s_setprio(1); _Pragma("unroll") for (int m = 0; m < 4; ++m) _Pragma("unroll") for (int n = 0; n < 2; ++n) _Pragma("unroll") for (int k = 0; k < 2; ++k) \
;         acc[ai][bj][m][n] = __builtin_amdgcn_mfma_f32_16x16x32_bf16(Bt[n][k], At[m][k], acc[ai][bj][m][n], 0, 0, 0); __builtin_amdgcn_s_setprio(0); } while (0)
; #define PG8_WAIT_V(n) asm volatile("s_waitcnt vmcnt(" #n ")" ::: "memory")
; #define PG8_WAIT_L(n) asm volatile("s_waitcnt lgkmcnt(" #n ")" ::: "memory")
; #define PG8_BAR __builtin_amdgcn_s_barrier()
;     __device__ __forceinline__ void operator()(const f32x4 (&acc)[2][2][4][2], const Unit& u, int wr, int wc, int fr, int fq) const {
;         const int row0 = u.pm * BM + wr * 64 + fr, col0 = u.pn * BM + wc * 32 + 4 * fq;
;         float* base = part + (size_t)u.ks * Mp * ldc;
; #pragma unroll
;         for (int ai = 0; ai < 2; ++ai)
; #pragma unroll
;             for (int m = 0; m < 4; ++m) { float* rowp = base + (size_t)(row0 + ai * HALF + m * 16) * ldc + col0;
; #pragma unroll
;                 for (int bj = 0; bj < 2; ++bj)
; #pragma unroll
;                     for (int n = 0; n < 2; ++n) *(f32x4*)(rowp + bj * HALF + n * 16) = acc[ai][bj][m][n]; }
;     }
; template <class Epi, class Sched>
; __device__ __forceinline__ void gemm_phase(LAS unsigned char* lds, const Gemm g, const Sched& S, const Epi& E) {
;     ...
;             PG8_BAR; PG8_WAIT_L(0); PG8_MMA(1, 0, At, B0); PG8_BAR; PG8_SCHED;
;             PG8_STAGE(PG8_SB(1, 1), b3 + hstep, voffB);
;             PG8_WAIT_V(6); PG8_BAR; PG8_MMA(1, 1, At, B1); PG8_BAR;
;         }
;         E(acc, cur, wr, wc, fr, fq);
;         if (!has_next) break;
; #pragma unroll
;         for (int a = 0; a < 2; ++a)
; #pragma unroll
;             for (int b = 0; b < 2; ++b)
; #pragma unroll
;                 for (int m = 0; m < 4; ++m)
; #pragma unroll
;                     for (int n = 0; n < 2; ++n) acc[a][b][m][n] = (f32x4){0.f, 0.f, 0.f, 0.f};
;         cur = nxt; cA = nA; cB = nB; ++ui;
;     }
;     PG8_WAIT_V(0);
;     if (wr == 0) PG8_BAR;
;     PG8_BAR;
	v_mfma_f32_16x16x32_bf16 v[62:65], v[140:143], v[160:163], v[62:65]
	v_mfma_f32_16x16x32_bf16 v[58:61], v[148:151], v[160:163], v[58:61]
	v_mfma_f32_16x16x32_bf16 v[54:57], v[140:143], v[168:171], v[54:57]
	v_mfma_f32_16x16x32_bf16 v[50:53], v[148:151], v[168:171], v[50:53]
	v_mfma_f32_16x16x32_bf16 v[38:41], v[140:143], v[176:179], v[38:41]
	v_mfma_f32_16x16x32_bf16 v[34:37], v[148:151], v[176:179], v[34:37]
	v_mfma_f32_16x16x32_bf16 v[22:25], v[140:143], v[184:187], v[22:25]
	v_mfma_f32_16x16x32_bf16 v[18:21], v[148:151], v[184:187], v[18:21]
	v_mfma_f32_16x16x32_bf16 v[62:65], v[144:147], v[164:167], v[62:65]
	v_mfma_f32_16x16x32_bf16 v[58:61], v[152:155], v[164:167], v[58:61]
	v_mfma_f32_16x16x32_bf16 v[54:57], v[144:147], v[172:175], v[54:57]
	v_mfma_f32_16x16x32_bf16 v[50:53], v[152:155], v[172:175], v[50:53]
	v_mfma_f32_16x16x32_bf16 v[38:41], v[144:147], v[180:183], v[38:41]
	v_mfma_f32_16x16x32_bf16 v[34:37], v[152:155], v[180:183], v[34:37]
	v_mfma_f32_16x16x32_bf16 v[22:25], v[144:147], v[188:191], v[22:25]
	v_mfma_f32_16x16x32_bf16 v[18:21], v[152:155], v[188:191], v[18:21]
	s_add_u32 s38, s56, 0x80080
	s_addc_u32 s39, s57, 0
	s_add_i32 s52, s53, s65
	s_mov_b32 m0, s52
	s_nop 0
	global_load_lds_dwordx4 v0, s[38:39]
	s_add_i32 m0, s52, 0x2000
	s_nop 0
	global_load_lds_dwordx4 v130, s[38:39]
	v_mfma_f32_16x16x32_bf16 v[46:49], v[192:195], v[160:163], v[46:49]
	v_mfma_f32_16x16x32_bf16 v[42:45], v[200:203], v[160:163], v[42:45]
	v_mfma_f32_16x16x32_bf16 v[30:33], v[192:195], v[168:171], v[30:33]
	v_mfma_f32_16x16x32_bf16 v[26:29], v[200:203], v[168:171], v[26:29]
	v_mfma_f32_16x16x32_bf16 v[14:17], v[192:195], v[176:179], v[14:17]
	v_mfma_f32_16x16x32_bf16 v[10:13], v[200:203], v[176:179], v[10:13]
	v_mfma_f32_16x16x32_bf16 v[6:9], v[192:195], v[184:187], v[6:9]
	v_mfma_f32_16x16x32_bf16 v[2:5], v[200:203], v[184:187], v[2:5]
	v_mfma_f32_16x16x32_bf16 v[46:49], v[196:199], v[164:167], v[46:49]
	v_mfma_f32_16x16x32_bf16 v[42:45], v[204:207], v[164:167], v[42:45]
	v_mfma_f32_16x16x32_bf16 v[30:33], v[196:199], v[172:175], v[30:33]
	v_mfma_f32_16x16x32_bf16 v[26:29], v[204:207], v[172:175], v[26:29]
	v_mfma_f32_16x16x32_bf16 v[14:17], v[196:199], v[180:183], v[14:17]
	v_mfma_f32_16x16x32_bf16 v[10:13], v[204:207], v[180:183], v[10:13]
	v_mfma_f32_16x16x32_bf16 v[6:9], v[196:199], v[188:191], v[6:9]
	v_mfma_f32_16x16x32_bf16 v[2:5], v[204:207], v[188:191], v[2:5]
	s_cmp_gt_i32 s73, 3
	s_barrier
	s_cbranch_scc0 .LBB0_113
	s_ashr_i32 s11, s10, 31
	s_lshl_b64 s[10:11], s[10:11], 24
	v_lshl_or_b32 v140, s26, 8, v138
	s_add_u32 s10, s8, s10
	v_lshl_add_u32 v142, s24, 8, v136
	s_addc_u32 s11, s9, s11
	v_ashrrev_i32_e32 v141, 31, v140
	v_ashrrev_i32_e32 v143, 31, v142
	v_lshl_add_u64 v[140:141], v[140:141], 2, s[10:11]
	v_lshlrev_b64 v[144:145], 13, v[142:143]
	v_lshl_add_u64 v[144:145], v[140:141], 0, v[144:145]
	global_store_dwordx4 v[144:145], v[126:129], off
	global_store_dwordx4 v[144:145], v[122:125], off offset:64
	global_store_dwordx4 v[144:145], v[110:113], off offset:512
	global_store_dwordx4 v[144:145], v[102:105], off offset:576
	s_mov_b64 s[10:11], 0x100000
	s_mov_b32 s26, s40
	v_or_b32_e32 v102, 16, v142
	v_ashrrev_i32_e32 v103, 31, v102
	v_lshlrev_b64 v[102:103], 13, v[102:103]
	v_lshl_add_u64 v[102:103], v[140:141], 0, v[102:103]
	global_store_dwordx4 v[102:103], v[118:121], off
	global_store_dwordx4 v[102:103], v[114:117], off offset:64
	global_store_dwordx4 v[102:103], v[94:97], off offset:512
	global_store_dwordx4 v[102:103], v[86:89], off offset:576
	s_mov_b32 s24, s44
	s_mov_b64 s[54:55], s[50:51]
	v_or_b32_e32 v86, 32, v142
	v_ashrrev_i32_e32 v87, 31, v86
	v_lshlrev_b64 v[86:87], 13, v[86:87]
	v_lshl_add_u64 v[86:87], v[140:141], 0, v[86:87]
	global_store_dwordx4 v[86:87], v[106:109], off
	global_store_dwordx4 v[86:87], v[98:101], off offset:64
	global_store_dwordx4 v[86:87], v[78:81], off offset:512
	global_store_dwordx4 v[86:87], v[74:77], off offset:576
	s_mov_b64 s[52:53], s[48:49]
	s_nop 0
	v_or_b32_e32 v74, 48, v142
	v_ashrrev_i32_e32 v75, 31, v74
	v_lshlrev_b64 v[74:75], 13, v[74:75]
	v_lshl_add_u64 v[74:75], v[140:141], 0, v[74:75]
	global_store_dwordx4 v[74:75], v[90:93], off
	global_store_dwordx4 v[74:75], v[82:85], off offset:64
	global_store_dwordx4 v[74:75], v[70:73], off offset:512
	global_store_dwordx4 v[74:75], v[66:69], off offset:576
	s_nop 1
	v_add_co_u32_e32 v68, vcc, s93, v144
	v_lshl_add_u64 v[66:67], v[144:145], 0, s[10:11]
	s_nop 0
	v_addc_co_u32_e32 v69, vcc, 0, v145, vcc
	s_mov_b64 s[10:11], 0x120000
	global_store_dwordx4 v[68:69], v[62:65], off
	global_store_dwordx4 v[66:67], v[58:61], off offset:64
	global_store_dwordx4 v[66:67], v[46:49], off offset:512
	global_store_dwordx4 v[66:67], v[42:45], off offset:576
	s_nop 1
	v_lshl_add_u64 v[42:43], v[144:145], 0, s[10:11]
	s_mov_b32 s10, 0x120000
	v_add_co_u32_e32 v44, vcc, s10, v144
	s_mov_b64 s[10:11], 0x140000
	s_nop 0
	v_addc_co_u32_e32 v45, vcc, 0, v145, vcc
	global_store_dwordx4 v[44:45], v[54:57], off
	global_store_dwordx4 v[42:43], v[50:53], off offset:64
	global_store_dwordx4 v[42:43], v[30:33], off offset:512
	global_store_dwordx4 v[42:43], v[26:29], off offset:576
	s_nop 1
	v_lshl_add_u64 v[26:27], v[144:145], 0, s[10:11]
	s_mov_b32 s10, 0x140000
	v_add_co_u32_e32 v28, vcc, s10, v144
	s_mov_b64 s[10:11], 0x160000
	s_nop 0
	v_addc_co_u32_e32 v29, vcc, 0, v145, vcc
	global_store_dwordx4 v[28:29], v[38:41], off
	global_store_dwordx4 v[26:27], v[34:37], off offset:64
	global_store_dwordx4 v[26:27], v[14:17], off offset:512
	global_store_dwordx4 v[26:27], v[10:13], off offset:576
	s_nop 1
	v_add_co_u32_e32 v12, vcc, 0x160000, v144
	v_lshl_add_u64 v[10:11], v[144:145], 0, s[10:11]
	s_nop 0
	v_addc_co_u32_e32 v13, vcc, 0, v145, vcc
	s_and_b64 vcc, exec, s[46:47]
	s_mov_b32 s10, s28
	global_store_dwordx4 v[12:13], v[22:25], off
	global_store_dwordx4 v[10:11], v[18:21], off offset:64
	global_store_dwordx4 v[10:11], v[6:9], off offset:512
	global_store_dwordx4 v[10:11], v[2:5], off offset:576
	s_cbranch_vccz .LBB0_110
	s_waitcnt vmcnt(0)
	s_cmpk_gt_u32 s60, 0xff
	s_cbranch_scc1 .LBB0_117
	s_barrier

; #define PG8_STAGE(bufoff, gbase, voff) do { _Pragma("unroll") for (int _i = 0; _i < 2; ++_i) \
;         __builtin_amdgcn_global_load_lds((const unsigned*)((const char*)(gbase) + (voff)[_i]), (LAS unsigned*)(lds + (bufoff) + ldsw + _i * 8192), 16, 0, 0); } while (0)
; #define PG8_LDA(dst, b, h) do { _Pragma("unroll") for (int m = 0; m < 4; ++m) _Pragma("unroll") for (int k = 0; k < 2; ++k) dst[m][k] = *(const LAS bf16x8*)(lds + PG8_SA(b, h) + aoff + m * 2048 + k * 1024); } while (0)
; #define PG8_WAIT_V(n) asm volatile("s_waitcnt vmcnt(" #n ")" ::: "memory")
; #define PG8_BAR __builtin_amdgcn_s_barrier()
; template <class Epi, class Sched>
; __device__ __forceinline__ void gemm_phase(LAS unsigned char* lds, const Gemm g, const Sched& S, const Epi& E) {
;     ...
;     const char* cA = (const char*)g.A + (size_t)cur.pm * tstep + (size_t)cur.ks * sstep; const char* cB = (const char*)g.Bt + (size_t)cur.pn * tstep + (size_t)cur.ks * sstep;
;     PG8_STAGE(PG8_SB(0, 0), cB, voffB); PG8_STAGE(PG8_SA(0, 0), cA, voffA); PG8_STAGE(PG8_SB(0, 1), cB + hstep, voffB); PG8_STAGE(PG8_SA(0, 1), cA + hstep, voffA);
;     if (wr == 1) PG8_BAR;
;     PG8_WAIT_V(4); PG8_BAR;
;     PG8_STAGE(PG8_SB(1, 0), cB + kstep, voffB); PG8_STAGE(PG8_SA(1, 0), cA + kstep, voffA); PG8_STAGE(PG8_SB(1, 1), cB + hstep + kstep, voffB);
;     PG8_WAIT_V(6); PG8_BAR;
;     for (;;) {
;         const bool has_next = S.next(ui + 1, nxt);
;         const char* nA = has_next ? (const char*)g.A + (size_t)nxt.pm * tstep + (size_t)nxt.ks * sstep : cA; const char* nB = has_next ? (const char*)g.Bt + (size_t)nxt.pn * tstep + (size_t)nxt.ks * sstep : cB;
;         for (int t = 0; t < nt; t += 2) {
;             const bool last = (t == nt - 2);
;             const char* a1 = cA + (size_t)(t + 1) * kstep;
;             const char* a2 = last ? nA : cA + (size_t)(t + 2) * kstep; const char* b2 = last ? nB : cB + (size_t)(t + 2) * kstep;
;             const char* a3 = a2 + kstep; const char* b3 = b2 + kstep;
;             PG8_LDB(B0, 0, 0); PG8_SCHED; PG8_LDA(At, 0, 0); PG8_STAGE(PG8_SA(1, 1), a1 + hstep, voffA);
;     ...
;         for (int a = 0; a < 2; ++a)
; #pragma unroll
;             for (int b = 0; b < 2; ++b)
; #pragma unroll
;                 for (int m = 0; m < 4; ++m)
; #pragma unroll
;                     for (int n = 0; n < 2; ++n) acc[a][b][m][n] = (f32x4){0.f, 0.f, 0.f, 0.f};
.LBB0_353:
	s_ashr_i32 s9, s8, 31
	s_xor_b64 s[46:47], s[54:55], -1
	s_lshl_b64 s[44:45], s[8:9], 20
	s_add_u32 s44, s26, s44
	s_addc_u32 s45, s27, s45
	s_and_b64 s[48:49], s[54:55], exec
	s_cselect_b32 s9, s45, s53
	s_cselect_b32 s66, s44, s52
	s_ashr_i32 s43, s42, 31
	s_lshl_b64 s[48:49], s[42:43], 20
	s_add_u32 s48, s75, s48
	s_addc_u32 s49, s76, s49
	s_and_b64 s[54:55], s[54:55], exec
	s_cselect_b32 s43, s49, s51
	s_cselect_b32 s67, s48, s50
	s_add_u32 s68, s50, 0x100
	s_addc_u32 s69, s51, 0
	s_add_u32 s50, s52, 0x80080
	v_mov_b32_e32 v2, 0
	s_addc_u32 s51, s53, 0
	s_mov_b32 s70, -2
	v_mov_b32_e32 v3, v2
	v_mov_b32_e32 v4, v2
	v_mov_b32_e32 v5, v2
	v_mov_b32_e32 v6, v2
	v_mov_b32_e32 v7, v2
	v_mov_b32_e32 v8, v2
	v_mov_b32_e32 v9, v2
	v_mov_b32_e32 v10, v2
	v_mov_b32_e32 v11, v2
	v_mov_b32_e32 v12, v2
	v_mov_b32_e32 v13, v2
	v_mov_b32_e32 v18, v2
	v_mov_b32_e32 v19, v2
	v_mov_b32_e32 v20, v2
	v_mov_b32_e32 v21, v2
	v_mov_b32_e32 v26, v2
	v_mov_b32_e32 v27, v2
	v_mov_b32_e32 v28, v2
	v_mov_b32_e32 v29, v2
	v_mov_b32_e32 v34, v2
	v_mov_b32_e32 v35, v2
	v_mov_b32_e32 v36, v2
	v_mov_b32_e32 v37, v2
	v_mov_b32_e32 v42, v2
	v_mov_b32_e32 v43, v2
	v_mov_b32_e32 v44, v2
	v_mov_b32_e32 v45, v2
	v_mov_b32_e32 v50, v2
	v_mov_b32_e32 v51, v2
	v_mov_b32_e32 v52, v2
	v_mov_b32_e32 v53, v2
	v_mov_b32_e32 v14, v2
	v_mov_b32_e32 v15, v2
	v_mov_b32_e32 v16, v2
	v_mov_b32_e32 v17, v2
	v_mov_b32_e32 v22, v2
	v_mov_b32_e32 v23, v2
	v_mov_b32_e32 v24, v2
	v_mov_b32_e32 v25, v2
	v_mov_b32_e32 v30, v2
	v_mov_b32_e32 v31, v2
	v_mov_b32_e32 v32, v2
	v_mov_b32_e32 v33, v2
	v_mov_b32_e32 v38, v2
	v_mov_b32_e32 v39, v2
	v_mov_b32_e32 v40, v2
	v_mov_b32_e32 v41, v2
	v_mov_b32_e32 v46, v2
	v_mov_b32_e32 v47, v2
	v_mov_b32_e32 v48, v2
	v_mov_b32_e32 v49, v2
	v_mov_b32_e32 v54, v2
	v_mov_b32_e32 v55, v2
	v_mov_b32_e32 v56, v2
	v_mov_b32_e32 v57, v2
	v_mov_b32_e32 v58, v2
	v_mov_b32_e32 v59, v2
	v_mov_b32_e32 v60, v2
	v_mov_b32_e32 v61, v2
	v_mov_b32_e32 v62, v2
	v_mov_b32_e32 v63, v2
	v_mov_b32_e32 v64, v2
	v_mov_b32_e32 v65, v2
	v_mov_b32_e32 v66, v2
	v_mov_b32_e32 v67, v2
	v_mov_b32_e32 v68, v2
	v_mov_b32_e32 v69, v2
	v_mov_b32_e32 v70, v2
	v_mov_b32_e32 v71, v2
	v_mov_b32_e32 v72, v2
	v_mov_b32_e32 v73, v2
	v_mov_b32_e32 v74, v2
	v_mov_b32_e32 v75, v2
	v_mov_b32_e32 v76, v2
	v_mov_b32_e32 v77, v2
	v_mov_b32_e32 v82, v2
	v_mov_b32_e32 v83, v2
	v_mov_b32_e32 v84, v2
	v_mov_b32_e32 v85, v2
	v_mov_b32_e32 v90, v2
	v_mov_b32_e32 v91, v2
	v_mov_b32_e32 v92, v2
	v_mov_b32_e32 v93, v2
	v_mov_b32_e32 v98, v2
	v_mov_b32_e32 v99, v2
	v_mov_b32_e32 v100, v2
	v_mov_b32_e32 v101, v2
	v_mov_b32_e32 v106, v2
	v_mov_b32_e32 v107, v2
	v_mov_b32_e32 v108, v2
	v_mov_b32_e32 v109, v2
	v_mov_b32_e32 v114, v2
	v_mov_b32_e32 v115, v2
	v_mov_b32_e32 v116, v2
	v_mov_b32_e32 v117, v2
	v_mov_b32_e32 v78, v2
	v_mov_b32_e32 v79, v2
	v_mov_b32_e32 v80, v2
	v_mov_b32_e32 v81, v2
	v_mov_b32_e32 v86, v2
	v_mov_b32_e32 v87, v2
	v_mov_b32_e32 v88, v2
	v_mov_b32_e32 v89, v2
	v_mov_b32_e32 v94, v2
	v_mov_b32_e32 v95, v2
	v_mov_b32_e32 v96, v2
	v_mov_b32_e32 v97, v2
	v_mov_b32_e32 v102, v2
	v_mov_b32_e32 v103, v2
	v_mov_b32_e32 v104, v2
	v_mov_b32_e32 v105, v2
	v_mov_b32_e32 v110, v2
	v_mov_b32_e32 v111, v2
	v_mov_b32_e32 v112, v2
	v_mov_b32_e32 v113, v2
	v_mov_b32_e32 v118, v2
	v_mov_b32_e32 v119, v2
	v_mov_b32_e32 v120, v2
	v_mov_b32_e32 v121, v2
	v_mov_b32_e32 v122, v2
	v_mov_b32_e32 v123, v2
	v_mov_b32_e32 v124, v2
	v_mov_b32_e32 v125, v2
	v_mov_b32_e32 v126, v2
	v_mov_b32_e32 v127, v2
	v_mov_b32_e32 v128, v2
	v_mov_b32_e32 v129, v2
	s_branch .Lent_354
.LBB0_354:
	s_add_i32 s70, s70, 2
	s_add_u32 s68, s68, 0x100
	s_addc_u32 s69, s69, 0
	s_add_u32 s50, s50, 0x100
	s_addc_u32 s51, s51, 0
.Lent_354:
	s_add_u32 s38, s50, 0xfff80080
	s_addc_u32 s39, s51, -1
	s_cmp_eq_u32 s70, 28
	s_cselect_b32 s55, s9, s39
	s_cselect_b32 s54, s66, s38
	s_cselect_b32 s53, s43, s69
	s_cselect_b32 s52, s67, s68
	s_add_i32 m0, s29, 0xc000
	ds_read_b128 v[140:143], v226
	global_load_lds_dwordx4 v138, s[50:51]
	s_add_i32 m0, s29, 0xe000
	ds_read_b128 v[148:151], v226 offset:1024
	global_load_lds_dwordx4 v136, s[50:51]
	s_add_i32 s71, 0, 0x10000
	ds_read_b128 v[152:155], v226 offset:2048
	ds_read_b128 v[160:163], v226 offset:3072
	ds_read_b128 v[164:167], v147
	ds_read_b128 v[168:171], v147 offset:1024
	ds_read_b128 v[172:175], v147 offset:2048
	ds_read_b128 v[176:179], v147 offset:3072
	ds_read_b128 v[180:183], v147 offset:4096
	ds_read_b128 v[184:187], v147 offset:5120
	ds_read_b128 v[188:191], v147 offset:6144
	ds_read_b128 v[192:195], v147 offset:7168
	s_add_i32 s38, 0, 0x14000
	ds_read_b128 v[196:199], v226 offset:16384
	ds_read_b128 v[200:203], v226 offset:17408
	ds_read_b128 v[204:207], v226 offset:18432
	ds_read_b128 v[210:213], v226 offset:19456
	s_waitcnt lgkmcnt(4)
	s_barrier
; #define PG8_STAGE(bufoff, gbase, voff) do { _Pragma("unroll") for (int _i = 0; _i < 2; ++_i) \
;         __builtin_amdgcn_global_load_lds((const unsigned*)((const char*)(gbase) + (voff)[_i]), (LAS unsigned*)(lds + (bufoff) + ldsw + _i * 8192), 16, 0, 0); } while (0)
; #define PG8_LDA(dst, b, h) do { _Pragma("unroll") for (int m = 0; m < 4; ++m) _Pragma("unroll") for (int k = 0; k < 2; ++k) dst[m][k] = *(const LAS bf16x8*)(lds + PG8_SA(b, h) + aoff + m * 2048 + k * 1024); } while (0)
; #define PG8_LDB(dst, b, h) do { _Pragma("unroll") for (int n = 0; n < 2; ++n) _Pragma("unroll") for (int k = 0; k < 2; ++k) dst[n][k] = *(const LAS bf16x8*)(lds + PG8_SB(b, h) + boff + n * 2048 + k * 1024); } while (0)
; #define PG8_MMA(ai, bj, At, Bt) do { __builtin_amdgcn_s_setprio(1); _Pragma("unroll") for (int m = 0; m < 4; ++m) _Pragma("unroll") for (int n = 0; n < 2; ++n) _Pragma("unroll") for (int k = 0; k < 2; ++k) \
;         acc[ai][bj][m][n] = __builtin_amdgcn_mfma_f32_16x16x32_bf16(Bt[n][k], At[m][k], acc[ai][bj][m][n], 0, 0, 0); __builtin_amdgcn_s_setprio(0); } while (0)
; #define PG8_WAIT_V(n) asm volatile("s_waitcnt vmcnt(" #n ")" ::: "memory")
; #define PG8_WAIT_L(n) asm volatile("s_waitcnt lgkmcnt(" #n ")" ::: "memory")
; #define PG8_BAR __builtin_amdgcn_s_barrier()
; #define PG8_SCHED __builtin_amdgcn_sched_barrier(0)
; template <class Epi, class Sched>
; __device__ __forceinline__ void gemm_phase(LAS unsigned char* lds, const Gemm g, const Sched& S, const Epi& E) {
;     ...
;             PG8_LDB(B0, 0, 0); PG8_SCHED; PG8_LDA(At, 0, 0); PG8_STAGE(PG8_SA(1, 1), a1 + hstep, voffA);
;             PG8_WAIT_L(8); PG8_BAR; PG8_WAIT_L(0); PG8_MMA(0, 0, At, B0); PG8_BAR; PG8_SCHED;
;             PG8_LDB(B1, 0, 1); PG8_STAGE(PG8_SB(0, 0), b2, voffB);
;             PG8_BAR; PG8_WAIT_L(0); PG8_MMA(0, 1, At, B1); PG8_BAR;
;             PG8_LDA(At, 0, 1); PG8_STAGE(PG8_SA(0, 0), a2, voffA);
;             PG8_BAR; PG8_WAIT_L(0); PG8_MMA(1, 0, At, B0); PG8_BAR; PG8_SCHED;
;             PG8_STAGE(PG8_SB(0, 1), b2 + hstep, voffB);
;             PG8_WAIT_V(6); PG8_BAR; PG8_MMA(1, 1, At, B1); PG8_BAR;
	s_waitcnt lgkmcnt(0)
	v_mfma_f32_16x16x32_bf16 v[126:129], v[140:143], v[164:167], v[126:129]
	v_mfma_f32_16x16x32_bf16 v[122:125], v[152:155], v[164:167], v[122:125]
	v_mfma_f32_16x16x32_bf16 v[118:121], v[140:143], v[172:175], v[118:121]
	v_mfma_f32_16x16x32_bf16 v[110:113], v[152:155], v[172:175], v[110:113]
	v_mfma_f32_16x16x32_bf16 v[102:105], v[140:143], v[180:183], v[102:105]
	v_mfma_f32_16x16x32_bf16 v[94:97], v[152:155], v[180:183], v[94:97]
	v_mfma_f32_16x16x32_bf16 v[86:89], v[140:143], v[188:191], v[86:89]
	v_mfma_f32_16x16x32_bf16 v[78:81], v[152:155], v[188:191], v[78:81]
	v_mfma_f32_16x16x32_bf16 v[126:129], v[148:151], v[168:171], v[126:129]
	v_mfma_f32_16x16x32_bf16 v[122:125], v[160:163], v[168:171], v[122:125]
	v_mfma_f32_16x16x32_bf16 v[118:121], v[148:151], v[176:179], v[118:121]
	v_mfma_f32_16x16x32_bf16 v[110:113], v[160:163], v[176:179], v[110:113]
	v_mfma_f32_16x16x32_bf16 v[102:105], v[148:151], v[184:187], v[102:105]
	v_mfma_f32_16x16x32_bf16 v[94:97], v[160:163], v[184:187], v[94:97]
	v_mfma_f32_16x16x32_bf16 v[86:89], v[148:151], v[192:195], v[86:89]
	v_mfma_f32_16x16x32_bf16 v[78:81], v[160:163], v[192:195], v[78:81]
	v_mfma_f32_16x16x32_bf16 v[114:117], v[196:199], v[164:167], v[114:117]
	v_mfma_f32_16x16x32_bf16 v[106:109], v[204:207], v[164:167], v[106:109]
	v_mfma_f32_16x16x32_bf16 v[98:101], v[196:199], v[172:175], v[98:101]
	v_mfma_f32_16x16x32_bf16 v[90:93], v[204:207], v[172:175], v[90:93]
	v_mfma_f32_16x16x32_bf16 v[82:85], v[196:199], v[180:183], v[82:85]
	v_mfma_f32_16x16x32_bf16 v[74:77], v[204:207], v[180:183], v[74:77]
	v_mfma_f32_16x16x32_bf16 v[70:73], v[196:199], v[188:191], v[70:73]
	v_mfma_f32_16x16x32_bf16 v[66:69], v[204:207], v[188:191], v[66:69]
	v_mfma_f32_16x16x32_bf16 v[114:117], v[200:203], v[168:171], v[114:117]
	v_mfma_f32_16x16x32_bf16 v[106:109], v[210:213], v[168:171], v[106:109]
	v_mfma_f32_16x16x32_bf16 v[98:101], v[200:203], v[176:179], v[98:101]
	v_mfma_f32_16x16x32_bf16 v[90:93], v[210:213], v[176:179], v[90:93]
	v_mfma_f32_16x16x32_bf16 v[82:85], v[200:203], v[184:187], v[82:85]
	v_mfma_f32_16x16x32_bf16 v[74:77], v[210:213], v[184:187], v[74:77]
	v_mfma_f32_16x16x32_bf16 v[70:73], v[200:203], v[192:195], v[70:73]
	v_mfma_f32_16x16x32_bf16 v[66:69], v[210:213], v[192:195], v[66:69]
	s_barrier
	s_add_i32 s39, s71, s56
	s_mov_b32 m0, s39
	ds_read_b128 v[164:167], v147 offset:16384
	global_load_lds_dwordx4 v0, s[52:53]
	s_add_i32 m0, s39, 0x2000
	ds_read_b128 v[168:171], v147 offset:17408
	global_load_lds_dwordx4 v134, s[52:53]
	s_mov_b32 m0, s29
	ds_read_b128 v[172:175], v147 offset:18432
	global_load_lds_dwordx4 v130, s[54:55]
	s_mov_b32 m0, s41
	ds_read_b128 v[176:179], v147 offset:19456
	global_load_lds_dwordx4 v132, s[54:55]
	ds_read_b128 v[180:183], v147 offset:20480
	ds_read_b128 v[184:187], v147 offset:21504
	ds_read_b128 v[188:191], v147 offset:22528
	ds_read_b128 v[192:195], v147 offset:23552
	s_waitcnt vmcnt(4)
	s_waitcnt lgkmcnt(0)
	s_barrier
	v_mfma_f32_16x16x32_bf16 v[62:65], v[140:143], v[164:167], v[62:65]
	v_mfma_f32_16x16x32_bf16 v[58:61], v[152:155], v[164:167], v[58:61]
	v_mfma_f32_16x16x32_bf16 v[54:57], v[140:143], v[172:175], v[54:57]
	v_mfma_f32_16x16x32_bf16 v[46:49], v[152:155], v[172:175], v[46:49]
	v_mfma_f32_16x16x32_bf16 v[38:41], v[140:143], v[180:183], v[38:41]
	v_mfma_f32_16x16x32_bf16 v[30:33], v[152:155], v[180:183], v[30:33]
	v_mfma_f32_16x16x32_bf16 v[22:25], v[140:143], v[188:191], v[22:25]
	v_mfma_f32_16x16x32_bf16 v[14:17], v[152:155], v[188:191], v[14:17]
	v_mfma_f32_16x16x32_bf16 v[62:65], v[148:151], v[168:171], v[62:65]
	v_mfma_f32_16x16x32_bf16 v[58:61], v[160:163], v[168:171], v[58:61]
	v_mfma_f32_16x16x32_bf16 v[54:57], v[148:151], v[176:179], v[54:57]
	v_mfma_f32_16x16x32_bf16 v[46:49], v[160:163], v[176:179], v[46:49]
	v_mfma_f32_16x16x32_bf16 v[38:41], v[148:151], v[184:187], v[38:41]
	v_mfma_f32_16x16x32_bf16 v[30:33], v[160:163], v[184:187], v[30:33]
	v_mfma_f32_16x16x32_bf16 v[22:25], v[148:151], v[192:195], v[22:25]
	v_mfma_f32_16x16x32_bf16 v[14:17], v[160:163], v[192:195], v[14:17]
	v_mfma_f32_16x16x32_bf16 v[50:53], v[196:199], v[164:167], v[50:53]
	v_mfma_f32_16x16x32_bf16 v[42:45], v[204:207], v[164:167], v[42:45]
	v_mfma_f32_16x16x32_bf16 v[34:37], v[196:199], v[172:175], v[34:37]
	v_mfma_f32_16x16x32_bf16 v[26:29], v[204:207], v[172:175], v[26:29]
	v_mfma_f32_16x16x32_bf16 v[18:21], v[196:199], v[180:183], v[18:21]
	v_mfma_f32_16x16x32_bf16 v[10:13], v[204:207], v[180:183], v[10:13]
	v_mfma_f32_16x16x32_bf16 v[6:9], v[196:199], v[188:191], v[6:9]
	v_mfma_f32_16x16x32_bf16 v[2:5], v[204:207], v[188:191], v[2:5]
	v_mfma_f32_16x16x32_bf16 v[50:53], v[200:203], v[168:171], v[50:53]
	v_mfma_f32_16x16x32_bf16 v[42:45], v[210:213], v[168:171], v[42:45]
	v_mfma_f32_16x16x32_bf16 v[34:37], v[200:203], v[176:179], v[34:37]
	v_mfma_f32_16x16x32_bf16 v[26:29], v[210:213], v[176:179], v[26:29]
	v_mfma_f32_16x16x32_bf16 v[18:21], v[200:203], v[184:187], v[18:21]
	v_mfma_f32_16x16x32_bf16 v[10:13], v[210:213], v[184:187], v[10:13]
	v_mfma_f32_16x16x32_bf16 v[6:9], v[200:203], v[192:195], v[6:9]
	v_mfma_f32_16x16x32_bf16 v[2:5], v[210:213], v[192:195], v[2:5]
	s_barrier
; #define PG8_STAGE(bufoff, gbase, voff) do { _Pragma("unroll") for (int _i = 0; _i < 2; ++_i) \
;         __builtin_amdgcn_global_load_lds((const unsigned*)((const char*)(gbase) + (voff)[_i]), (LAS unsigned*)(lds + (bufoff) + ldsw + _i * 8192), 16, 0, 0); } while (0)
; #define PG8_LDA(dst, b, h) do { _Pragma("unroll") for (int m = 0; m < 4; ++m) _Pragma("unroll") for (int k = 0; k < 2; ++k) dst[m][k] = *(const LAS bf16x8*)(lds + PG8_SA(b, h) + aoff + m * 2048 + k * 1024); } while (0)
; #define PG8_LDB(dst, b, h) do { _Pragma("unroll") for (int n = 0; n < 2; ++n) _Pragma("unroll") for (int k = 0; k < 2; ++k) dst[n][k] = *(const LAS bf16x8*)(lds + PG8_SB(b, h) + boff + n * 2048 + k * 1024); } while (0)
; #define PG8_MMA(ai, bj, At, Bt) do { __builtin_amdgcn_s_setprio(1); _Pragma("unroll") for (int m = 0; m < 4; ++m) _Pragma("unroll") for (int n = 0; n < 2; ++n) _Pragma("unroll") for (int k = 0; k < 2; ++k) \
;         acc[ai][bj][m][n] = __builtin_amdgcn_mfma_f32_16x16x32_bf16(Bt[n][k], At[m][k], acc[ai][bj][m][n], 0, 0, 0); __builtin_amdgcn_s_setprio(0); } while (0)
; #define PG8_WAIT_V(n) asm volatile("s_waitcnt vmcnt(" #n ")" ::: "memory")
; #define PG8_WAIT_L(n) asm volatile("s_waitcnt lgkmcnt(" #n ")" ::: "memory")
; #define PG8_BAR __builtin_amdgcn_s_barrier()
; #define PG8_SCHED __builtin_amdgcn_sched_barrier(0)
; template <class Epi, class Sched>
; __device__ __forceinline__ void gemm_phase(LAS unsigned char* lds, const Gemm g, const Sched& S, const Epi& E) {
;     ...
;             PG8_LDB(B0, 1, 0); PG8_SCHED; PG8_LDA(At, 1, 0); PG8_STAGE(PG8_SA(0, 1), a2 + hstep, voffA);
;             PG8_WAIT_L(8); PG8_BAR; PG8_WAIT_L(0); PG8_MMA(0, 0, At, B0); PG8_BAR; PG8_SCHED;
;             PG8_LDB(B1, 1, 1); PG8_STAGE(PG8_SB(1, 0), b3, voffB);
;             PG8_BAR; PG8_WAIT_L(0); PG8_MMA(0, 1, At, B1); PG8_BAR;
;             PG8_LDA(At, 1, 1); PG8_STAGE(PG8_SA(1, 0), a3, voffA);
;             PG8_BAR; PG8_WAIT_L(0); PG8_MMA(1, 0, At, B0); PG8_BAR; PG8_SCHED;
;             PG8_STAGE(PG8_SB(1, 1), b3 + hstep, voffB);
;             PG8_WAIT_V(6); PG8_BAR; PG8_MMA(1, 1, At, B1); PG8_BAR;
	s_add_u32 s72, s52, 0x80000
	s_addc_u32 s73, s53, 0
	s_add_i32 s38, s38, s56
	s_mov_b32 m0, s38
	ds_read_b128 v[140:143], v226 offset:32768
	global_load_lds_dwordx4 v0, s[72:73]
	s_add_i32 m0, s38, 0x2000
	ds_read_b128 v[148:151], v226 offset:33792
	global_load_lds_dwordx4 v134, s[72:73]
	s_add_u32 s54, s54, 0x80000
	s_addc_u32 s55, s55, 0
	s_mov_b32 m0, s57
	ds_read_b128 v[152:155], v226 offset:34816
	global_load_lds_dwordx4 v130, s[54:55]
	s_mov_b32 m0, s58
	ds_read_b128 v[160:163], v226 offset:35840
	global_load_lds_dwordx4 v132, s[54:55]
	s_add_i32 s38, 0, 0x18000
	ds_read_b128 v[164:167], v147 offset:32768
	ds_read_b128 v[168:171], v147 offset:33792
	ds_read_b128 v[172:175], v147 offset:34816
	ds_read_b128 v[176:179], v147 offset:35840
	ds_read_b128 v[180:183], v147 offset:36864
	ds_read_b128 v[184:187], v147 offset:37888
	ds_read_b128 v[188:191], v147 offset:38912
	ds_read_b128 v[192:195], v147 offset:39936
	s_add_i32 s39, 0, 0x1c000
	ds_read_b128 v[196:199], v226 offset:49152
	ds_read_b128 v[200:203], v226 offset:50176
	ds_read_b128 v[204:207], v226 offset:51200
	ds_read_b128 v[210:213], v226 offset:52224
	s_waitcnt lgkmcnt(4)
	s_barrier
	s_waitcnt lgkmcnt(0)
	v_mfma_f32_16x16x32_bf16 v[126:129], v[140:143], v[164:167], v[126:129]
	v_mfma_f32_16x16x32_bf16 v[122:125], v[152:155], v[164:167], v[122:125]
	v_mfma_f32_16x16x32_bf16 v[118:121], v[140:143], v[172:175], v[118:121]
	v_mfma_f32_16x16x32_bf16 v[110:113], v[152:155], v[172:175], v[110:113]
	v_mfma_f32_16x16x32_bf16 v[102:105], v[140:143], v[180:183], v[102:105]
	v_mfma_f32_16x16x32_bf16 v[94:97], v[152:155], v[180:183], v[94:97]
	v_mfma_f32_16x16x32_bf16 v[86:89], v[140:143], v[188:191], v[86:89]
	v_mfma_f32_16x16x32_bf16 v[78:81], v[152:155], v[188:191], v[78:81]
	v_mfma_f32_16x16x32_bf16 v[126:129], v[148:151], v[168:171], v[126:129]
	v_mfma_f32_16x16x32_bf16 v[122:125], v[160:163], v[168:171], v[122:125]
	v_mfma_f32_16x16x32_bf16 v[118:121], v[148:151], v[176:179], v[118:121]
	v_mfma_f32_16x16x32_bf16 v[110:113], v[160:163], v[176:179], v[110:113]
	v_mfma_f32_16x16x32_bf16 v[102:105], v[148:151], v[184:187], v[102:105]
	v_mfma_f32_16x16x32_bf16 v[94:97], v[160:163], v[184:187], v[94:97]
	v_mfma_f32_16x16x32_bf16 v[86:89], v[148:151], v[192:195], v[86:89]
	v_mfma_f32_16x16x32_bf16 v[78:81], v[160:163], v[192:195], v[78:81]
	v_mfma_f32_16x16x32_bf16 v[114:117], v[196:199], v[164:167], v[114:117]
	v_mfma_f32_16x16x32_bf16 v[106:109], v[204:207], v[164:167], v[106:109]
	v_mfma_f32_16x16x32_bf16 v[98:101], v[196:199], v[172:175], v[98:101]
	v_mfma_f32_16x16x32_bf16 v[90:93], v[204:207], v[172:175], v[90:93]
	v_mfma_f32_16x16x32_bf16 v[82:85], v[196:199], v[180:183], v[82:85]
	v_mfma_f32_16x16x32_bf16 v[74:77], v[204:207], v[180:183], v[74:77]
	v_mfma_f32_16x16x32_bf16 v[70:73], v[196:199], v[188:191], v[70:73]
	v_mfma_f32_16x16x32_bf16 v[66:69], v[204:207], v[188:191], v[66:69]
	v_mfma_f32_16x16x32_bf16 v[114:117], v[200:203], v[168:171], v[114:117]
	v_mfma_f32_16x16x32_bf16 v[106:109], v[210:213], v[168:171], v[106:109]
	v_mfma_f32_16x16x32_bf16 v[98:101], v[200:203], v[176:179], v[98:101]
	v_mfma_f32_16x16x32_bf16 v[90:93], v[210:213], v[176:179], v[90:93]
	v_mfma_f32_16x16x32_bf16 v[82:85], v[200:203], v[184:187], v[82:85]
	v_mfma_f32_16x16x32_bf16 v[74:77], v[210:213], v[184:187], v[74:77]
	v_mfma_f32_16x16x32_bf16 v[70:73], v[200:203], v[192:195], v[70:73]
	v_mfma_f32_16x16x32_bf16 v[66:69], v[210:213], v[192:195], v[66:69]
	s_barrier
	s_add_i32 s38, s38, s56
	s_add_u32 s100, s52, s36
	s_addc_u32 s101, s53, s37
	s_mov_b32 m0, s38
	ds_read_b128 v[164:167], v147 offset:49152
	global_load_lds_dwordx4 v0, s[100:101]
	s_add_i32 m0, s38, 0x2000
	ds_read_b128 v[168:171], v147 offset:50176
	global_load_lds_dwordx4 v134, s[100:101]
	s_mov_b32 m0, s59
	s_add_u32 s100, s54, s36
	s_addc_u32 s101, s55, s37
	s_sub_u32 s100, s100, 0x80000
	s_subb_u32 s101, s101, 0
	global_load_lds_dwordx4 v130, s[100:101]
	s_mov_b32 m0, s60
	ds_read_b128 v[172:175], v147 offset:51200
	global_load_lds_dwordx4 v132, s[100:101]
	ds_read_b128 v[176:179], v147 offset:52224
	ds_read_b128 v[180:183], v147 offset:53248
	ds_read_b128 v[184:187], v147 offset:54272
	ds_read_b128 v[188:191], v147 offset:55296
	ds_read_b128 v[192:195], v147 offset:56320
	s_waitcnt vmcnt(4)
	s_waitcnt lgkmcnt(0)
	s_barrier
	v_mfma_f32_16x16x32_bf16 v[62:65], v[140:143], v[164:167], v[62:65]
	v_mfma_f32_16x16x32_bf16 v[58:61], v[152:155], v[164:167], v[58:61]
	v_mfma_f32_16x16x32_bf16 v[54:57], v[140:143], v[172:175], v[54:57]
	v_mfma_f32_16x16x32_bf16 v[46:49], v[152:155], v[172:175], v[46:49]
	v_mfma_f32_16x16x32_bf16 v[38:41], v[140:143], v[180:183], v[38:41]
	v_mfma_f32_16x16x32_bf16 v[30:33], v[152:155], v[180:183], v[30:33]
	v_mfma_f32_16x16x32_bf16 v[22:25], v[140:143], v[188:191], v[22:25]
	v_mfma_f32_16x16x32_bf16 v[14:17], v[152:155], v[188:191], v[14:17]
	v_mfma_f32_16x16x32_bf16 v[62:65], v[148:151], v[168:171], v[62:65]
	v_mfma_f32_16x16x32_bf16 v[58:61], v[160:163], v[168:171], v[58:61]
	v_mfma_f32_16x16x32_bf16 v[54:57], v[148:151], v[176:179], v[54:57]
	v_mfma_f32_16x16x32_bf16 v[46:49], v[160:163], v[176:179], v[46:49]
	v_mfma_f32_16x16x32_bf16 v[38:41], v[148:151], v[184:187], v[38:41]
	v_mfma_f32_16x16x32_bf16 v[30:33], v[160:163], v[184:187], v[30:33]
	v_mfma_f32_16x16x32_bf16 v[22:25], v[148:151], v[192:195], v[22:25]
	v_mfma_f32_16x16x32_bf16 v[14:17], v[160:163], v[192:195], v[14:17]
	s_add_u32 s52, s52, 0x80080
	s_addc_u32 s53, s53, 0
	s_add_i32 s38, s39, s56
	s_mov_b32 m0, s38
	s_nop 0
	global_load_lds_dwordx4 v0, s[52:53]
	s_add_i32 m0, s38, 0x2000
	s_nop 0
	global_load_lds_dwordx4 v134, s[52:53]
	v_mfma_f32_16x16x32_bf16 v[50:53], v[196:199], v[164:167], v[50:53]
	v_mfma_f32_16x16x32_bf16 v[42:45], v[204:207], v[164:167], v[42:45]
	v_mfma_f32_16x16x32_bf16 v[34:37], v[196:199], v[172:175], v[34:37]
	v_mfma_f32_16x16x32_bf16 v[26:29], v[204:207], v[172:175], v[26:29]
	v_mfma_f32_16x16x32_bf16 v[18:21], v[196:199], v[180:183], v[18:21]
	v_mfma_f32_16x16x32_bf16 v[10:13], v[204:207], v[180:183], v[10:13]
	v_mfma_f32_16x16x32_bf16 v[6:9], v[196:199], v[188:191], v[6:9]
	v_mfma_f32_16x16x32_bf16 v[2:5], v[204:207], v[188:191], v[2:5]
	v_mfma_f32_16x16x32_bf16 v[50:53], v[200:203], v[168:171], v[50:53]
	v_mfma_f32_16x16x32_bf16 v[42:45], v[210:213], v[168:171], v[42:45]
	v_mfma_f32_16x16x32_bf16 v[34:37], v[200:203], v[176:179], v[34:37]
	v_mfma_f32_16x16x32_bf16 v[26:29], v[210:213], v[176:179], v[26:29]
	v_mfma_f32_16x16x32_bf16 v[18:21], v[200:203], v[184:187], v[18:21]
	v_mfma_f32_16x16x32_bf16 v[10:13], v[210:213], v[184:187], v[10:13]
	v_mfma_f32_16x16x32_bf16 v[6:9], v[200:203], v[192:195], v[6:9]
	v_mfma_f32_16x16x32_bf16 v[2:5], v[210:213], v[192:195], v[2:5]
	s_cmp_gt_i32 s70, 27
	s_barrier
; __device__ __forceinline__ unsigned cvt_pk_bf16(float lo, float hi) { unsigned r; asm("v_cvt_pk_bf16_f32 %0, %1, %2" : "=v"(r) : "v"(lo), "v"(hi)); return r; }
;     __device__ __forceinline__ void operator()(const f32x4 (&acc)[2][2][4][2], const Unit& u, int wr, int wc, int fr, int fq) const {
;         const int row0 = u.pm * BM + wr * 64 + fr, col0 = u.pn * BM + wc * 32 + 8 * fq;
; #pragma unroll
;         for (int ai = 0; ai < 2; ++ai)
; #pragma unroll
;             for (int m = 0; m < 4; ++m) { bf16_t* rowp = O + (size_t)(row0 + ai * HALF + m * 16) * ldc + col0;
; #pragma unroll
;                 for (int bj = 0; bj < 2; ++bj) { f32x4 v0 = acc[ai][bj][m][0], v1 = acc[ai][bj][m][1];
;                     if (ACT == 1) {
; #pragma unroll
;                         for (int j = 0; j < 4; ++j) { float a = fmaxf(v0[j], 0.f), b = fmaxf(v1[j], 0.f); v0[j] = a * a; v1[j] = b * b; } }
;                     u32x4 w; w.x = cvt_pk_bf16(v0[0], v0[1]); w.y = cvt_pk_bf16(v0[2], v0[3]); w.z = cvt_pk_bf16(v1[0], v1[1]); w.w = cvt_pk_bf16(v1[2], v1[3]);
;                     if (ACT == 1) __builtin_nontemporal_store(w, (u32x4*)(rowp + bj * HALF));
;                     else *(u32x4*)(rowp + bj * HALF) = w; } }
; template <class Epi, class Sched>
; __device__ __forceinline__ void gemm_phase(LAS unsigned char* lds, const Gemm g, const Sched& S, const Epi& E) {
;     ...
;         E(acc, cur, wr, wc, fr, fq);
;         if (!has_next) break;
	s_cbranch_scc0 .LBB0_354
	s_load_dwordx2 s[50:51], s[0:1], 0xc0
	v_lshl_add_u32 v150, s28, 8, v144
	v_lshl_or_b32 v142, s40, 8, v146
	v_ashrrev_i32_e32 v143, 31, v142
	v_cvt_pk_bf16_f32 v70, v70, v71
	s_waitcnt lgkmcnt(0)
	v_mov_b64_e32 v[140:141], s[50:51]
	v_cvt_pk_bf16_f32 v71, v72, v73
	v_cvt_pk_bf16_f32 v72, v66, v67
	v_add_u32_e32 v66, 0x80, v150
	v_mad_i64_i32 v[148:149], s[50:51], v150, s17, v[140:141]
	v_lshlrev_b64 v[142:143], 1, v[142:143]
	v_cvt_pk_bf16_f32 v114, v114, v115
	v_cvt_pk_bf16_f32 v115, v116, v117
	v_cvt_pk_bf16_f32 v116, v106, v107
	v_or_b32_e32 v106, 16, v150
	v_mad_i64_i32 v[66:67], s[50:51], v66, s17, v[140:141]
	v_cvt_pk_bf16_f32 v50, v50, v51
	v_cvt_pk_bf16_f32 v51, v52, v53
	v_cvt_pk_bf16_f32 v52, v42, v43
	v_add_u32_e32 v42, 0x90, v150
	v_lshl_add_u64 v[148:149], v[148:149], 0, v[142:143]
	v_mad_i64_i32 v[106:107], s[50:51], v106, s17, v[140:141]
	v_cvt_pk_bf16_f32 v98, v98, v99
	v_cvt_pk_bf16_f32 v99, v100, v101
	v_cvt_pk_bf16_f32 v100, v90, v91
	v_or_b32_e32 v90, 32, v150
	v_lshl_add_u64 v[66:67], v[66:67], 0, v[142:143]
	v_mad_i64_i32 v[42:43], s[50:51], v42, s17, v[140:141]
	v_cvt_pk_bf16_f32 v34, v34, v35
	v_cvt_pk_bf16_f32 v35, v36, v37
	v_cvt_pk_bf16_f32 v36, v26, v27
	v_add_u32_e32 v26, 0xa0, v150
	v_cvt_pk_bf16_f32 v117, v108, v109
	global_store_dwordx4 v[148:149], v[114:117], off offset:256
	v_mad_i64_i32 v[90:91], s[50:51], v90, s17, v[140:141]
	s_nop 0
	v_lshl_add_u64 v[114:115], v[106:107], 0, v[142:143]
	v_cvt_pk_bf16_f32 v82, v82, v83
	v_cvt_pk_bf16_f32 v83, v84, v85
	v_cvt_pk_bf16_f32 v84, v74, v75
	v_or_b32_e32 v74, 48, v150
	v_cvt_pk_bf16_f32 v53, v44, v45
	global_store_dwordx4 v[66:67], v[50:53], off offset:256
	v_mad_i64_i32 v[26:27], s[50:51], v26, s17, v[140:141]
	s_nop 0
	v_lshl_add_u64 v[50:51], v[42:43], 0, v[142:143]
	v_cvt_pk_bf16_f32 v18, v18, v19
	v_cvt_pk_bf16_f32 v19, v20, v21
	v_cvt_pk_bf16_f32 v20, v10, v11
	v_add_u32_e32 v10, 0xb0, v150
	v_cvt_pk_bf16_f32 v101, v92, v93
	global_store_dwordx4 v[114:115], v[98:101], off offset:256
	v_mad_i64_i32 v[74:75], s[50:51], v74, s17, v[140:141]
	s_nop 0
	v_lshl_add_u64 v[98:99], v[90:91], 0, v[142:143]
	v_cvt_pk_bf16_f32 v37, v28, v29
	global_store_dwordx4 v[50:51], v[34:37], off offset:256
	v_mad_i64_i32 v[10:11], s[50:51], v10, s17, v[140:141]
	s_nop 0
	v_lshl_add_u64 v[34:35], v[26:27], 0, v[142:143]
	v_cvt_pk_bf16_f32 v85, v76, v77
	global_store_dwordx4 v[98:99], v[82:85], off offset:256
	v_cvt_pk_bf16_f32 v21, v12, v13
	global_store_dwordx4 v[34:35], v[18:21], off offset:256
	s_and_b64 vcc, exec, s[46:47]
	v_lshl_add_u64 v[82:83], v[74:75], 0, v[142:143]
	v_lshl_add_u64 v[18:19], v[10:11], 0, v[142:143]
	s_mov_b32 s40, s42
	s_mov_b32 s28, s8
	s_mov_b32 s43, s42
	s_mov_b32 s46, s8
	s_mov_b64 s[50:51], s[48:49]
	s_mov_b64 s[52:53], s[44:45]
	v_cvt_pk_bf16_f32 v126, v126, v127
	v_cvt_pk_bf16_f32 v127, v128, v129
	v_cvt_pk_bf16_f32 v128, v122, v123
	v_cvt_pk_bf16_f32 v129, v124, v125
	global_store_dwordx4 v[148:149], v[126:129], off
	v_cvt_pk_bf16_f32 v106, v118, v119
	v_cvt_pk_bf16_f32 v107, v120, v121
	v_cvt_pk_bf16_f32 v108, v110, v111
	v_cvt_pk_bf16_f32 v109, v112, v113
	global_store_dwordx4 v[114:115], v[106:109], off
	v_cvt_pk_bf16_f32 v90, v102, v103
	v_cvt_pk_bf16_f32 v91, v104, v105
	v_cvt_pk_bf16_f32 v92, v94, v95
	v_cvt_pk_bf16_f32 v93, v96, v97
	global_store_dwordx4 v[98:99], v[90:93], off
	v_cvt_pk_bf16_f32 v74, v86, v87
	v_cvt_pk_bf16_f32 v75, v88, v89
	v_cvt_pk_bf16_f32 v76, v78, v79
	v_cvt_pk_bf16_f32 v77, v80, v81
	global_store_dwordx4 v[82:83], v[74:77], off
	v_cvt_pk_bf16_f32 v73, v68, v69
	global_store_dwordx4 v[82:83], v[70:73], off offset:256
	v_cvt_pk_bf16_f32 v62, v62, v63
	v_cvt_pk_bf16_f32 v63, v64, v65
	v_cvt_pk_bf16_f32 v64, v58, v59
	v_cvt_pk_bf16_f32 v65, v60, v61
	global_store_dwordx4 v[66:67], v[62:65], off
	v_cvt_pk_bf16_f32 v42, v54, v55
	v_cvt_pk_bf16_f32 v43, v56, v57
	v_cvt_pk_bf16_f32 v44, v46, v47
	v_cvt_pk_bf16_f32 v45, v48, v49
	global_store_dwordx4 v[50:51], v[42:45], off
	v_cvt_pk_bf16_f32 v26, v38, v39
	v_cvt_pk_bf16_f32 v27, v40, v41
	v_cvt_pk_bf16_f32 v28, v30, v31
	v_cvt_pk_bf16_f32 v29, v32, v33
	global_store_dwordx4 v[34:35], v[26:29], off
	v_cvt_pk_bf16_f32 v10, v22, v23
	v_cvt_pk_bf16_f32 v11, v24, v25
	v_cvt_pk_bf16_f32 v12, v14, v15
	v_cvt_pk_bf16_f32 v13, v16, v17
	global_store_dwordx4 v[18:19], v[10:13], off
	v_cvt_pk_bf16_f32 v6, v6, v7
	v_cvt_pk_bf16_f32 v7, v8, v9
	v_cvt_pk_bf16_f32 v8, v2, v3
	v_cvt_pk_bf16_f32 v9, v4, v5
	global_store_dwordx4 v[18:19], v[6:9], off offset:256
	s_cbranch_vccz .LBB0_346
	s_waitcnt vmcnt(0)
	s_cmpk_gt_u32 s25, 0xff
	s_cbranch_scc1 .LBB0_358
	s_barrier
